# zero-setprio variant with operand-stationary MFMA order inside each 8-MFMA group (one operand tuple held for four consecutive MFMAs)
# baseline (speedup 1.0000x reference)
;     __device__ __forceinline__ Pre prefetch(const Unit& u, int tid) const { return prenorm_load(stats, u.pn * BM, sW + (size_t)(u.pn >> 4) * SW_ROWS + u.pm * BM, tid); }
;     __device__ __forceinline__ Pre prefetch(const Unit& u, int tid) const { return prenorm_load(stats, u.pm * BM, sW + (size_t)(u.pm >> 4) * SW_ROWS + u.pn * BM, tid); }
;     __device__ __forceinline__ Pre prefetch(const Unit& u, int tid) const { return prenorm_load(stats, u.pm * BM, sW + (size_t)(u.pm >> 4) * SW_ROWS + u.pn * BM, tid); }
; #define PG8_STAGE(bufoff, gbase, voff) do { _Pragma("unroll") for (int _i = 0; _i < 2; ++_i) \
;         __builtin_amdgcn_global_load_lds((const unsigned*)((const char*)(gbase) + (voff)[_i]), (LAS unsigned*)(lds + (bufoff) + ldsw + _i * 8192), 16, 0, 0); } while (0)
; #define PG8_LDA(dst, b, h) do { _Pragma("unroll") for (int m = 0; m < 4; ++m) _Pragma("unroll") for (int k = 0; k < 2; ++k) dst[m][k] = *(const LAS bf16x8*)(lds + PG8_SA(b, h) + aoff + m * 2048 + k * 1024); } while (0)
; #define PG8_LDB(dst, b, h) do { _Pragma("unroll") for (int n = 0; n < 2; ++n) _Pragma("unroll") for (int k = 0; k < 2; ++k) dst[n][k] = *(const LAS bf16x8*)(lds + PG8_SB(b, h) + boff + n * 2048 + k * 1024); } while (0)
; template <class Epi, class Sched>
; __device__ __forceinline__ void gemm_phase(LAS unsigned char* lds, const Gemm g, const Sched& S, const Epi& E, const int tid) {
;     ...
;         const char* nA = has_next ? (const char*)g.A + (size_t)nxt.pm * tstep : cA; const char* nB = has_next ? (const char*)g.Bt + (size_t)nxt.pn * tstep : cB;
;         const typename Epi::Pre pre = E.prefetch(cur, tid);
;         for (int t = 0; t < nt; t += 2) {
;             const bool last = (t == nt - 2);
;             const char* a1 = cA + (size_t)(t + 1) * kstep;
;             const char* a2 = last ? nA : cA + (size_t)(t + 2) * kstep; const char* b2 = last ? nB : cB + (size_t)(t + 2) * kstep;
;             const char* a3 = a2 + kstep; const char* b3 = b2 + kstep;
;             PG8_LDB(B0, 0, 0); PG8_LDB(B1, 0, 1); PG8_SCHED; PG8_LDA(At, 0, 0); PG8_STAGE(PG8_SA(1, 1), a1 + hstep, voffA);
;             PG8_WAIT_V(8); PG8_WAIT_L(0); PG8_BAR; PG8_MMA(0, 0, At, B0); PG8_MMA(0, 1, At, B1); PG8_BAR; PG8_SCHED;
;             PG8_LDA(At, 0, 1); PG8_STAGE(PG8_SB(0, 0), b2, voffB); PG8_STAGE(PG8_SB(0, 1), b2 + hstep, voffB); PG8_STAGE(PG8_SA(0, 0), a2, voffA);
.LBB0_167:
	s_or_b64 exec, exec, s[22:23]
	s_ashr_i32 s55, s54, 31
	s_lshl_b64 s[22:23], s[54:55], 19
	s_add_u32 s22, s46, s22
	s_addc_u32 s23, s47, s23
	s_and_b64 s[38:39], s[6:7], exec
	s_cselect_b32 s55, s23, s65
	s_cselect_b32 s56, s22, s64
	s_ashr_i32 s63, s62, 31
	s_lshl_b64 s[38:39], s[62:63], 19
	s_add_u32 s38, s12, s38
	s_addc_u32 s39, s73, s39
	s_and_b64 s[58:59], s[6:7], exec
	s_cselect_b32 s57, s39, s67
	s_cselect_b32 s58, s38, s66
	s_add_u32 s64, s64, 0x40080
	s_addc_u32 s65, s65, 0
	s_add_u32 s59, s66, 0x100
	s_addc_u32 s60, s67, 0
	s_mov_b32 s61, -2
	s_add_u32 s63, s64, 0xfffc0080
	s_addc_u32 s66, s65, -1
	s_add_i32 s78, 0, 0x10000
	s_cmp_eq_u32 s61, 12
	s_cselect_b32 s71, s55, s66
	s_cselect_b32 s70, s56, s63
	v_add_u32_e32 v145, s78, v166
	s_cselect_b32 s67, s57, s60
	s_cselect_b32 s66, s58, s59
	s_add_i32 s63, 0, 0x14000
	ds_read_b128 v[146:149], v145
	ds_read_b128 v[150:153], v145 offset:1024
	ds_read_b128 v[154:157], v145 offset:2048
	ds_read_b128 v[158:161], v145 offset:3072
	v_add_u32_e32 v145, s63, v166
	ds_read_b128 v[172:175], v145
	ds_read_b128 v[176:179], v145 offset:1024
	ds_read_b128 v[180:183], v145 offset:2048
	ds_read_b128 v[184:187], v145 offset:3072
	v_lshl_add_u64 v[162:163], s[64:65], 0, v[140:141]
	s_add_i32 m0, s75, 0xc000
	ds_read_b128 v[188:191], v171
	ds_read_b128 v[198:201], v171 offset:1024
	ds_read_b128 v[202:205], v171 offset:2048
	ds_read_b128 v[206:209], v171 offset:3072
	ds_read_b128 v[210:213], v171 offset:4096
	ds_read_b128 v[214:217], v171 offset:5120
	ds_read_b128 v[218:221], v171 offset:6144
	ds_read_b128 v[230:233], v171 offset:7168
	global_load_lds_dwordx4 v[162:163], off
	v_lshl_add_u64 v[162:163], s[64:65], 0, v[142:143]
	s_add_i32 m0, s75, 0xe000
	s_nop 0
	global_load_lds_dwordx4 v[162:163], off
	s_waitcnt vmcnt(8)
	s_waitcnt lgkmcnt(0)
	s_barrier
	s_waitcnt lgkmcnt(0)
	v_mfma_f32_16x16x32_bf16 v[128:131], v[146:149], v[188:191], 0
	v_mfma_f32_16x16x32_bf16 v[108:111], v[146:149], v[202:205], 0
	v_mfma_f32_16x16x32_bf16 v[92:95], v[146:149], v[210:213], 0
	v_mfma_f32_16x16x32_bf16 v[76:79], v[146:149], v[218:221], 0
	v_mfma_f32_16x16x32_bf16 v[72:75], v[154:157], v[218:221], 0
	v_mfma_f32_16x16x32_bf16 v[88:91], v[154:157], v[210:213], 0
	v_mfma_f32_16x16x32_bf16 v[104:107], v[154:157], v[202:205], 0
	v_mfma_f32_16x16x32_bf16 v[124:127], v[154:157], v[188:191], 0
	v_mfma_f32_16x16x32_bf16 v[128:131], v[150:153], v[198:201], v[128:131]
	v_mfma_f32_16x16x32_bf16 v[108:111], v[150:153], v[206:209], v[108:111]
	v_mfma_f32_16x16x32_bf16 v[92:95], v[150:153], v[214:217], v[92:95]
	v_mfma_f32_16x16x32_bf16 v[76:79], v[150:153], v[230:233], v[76:79]
	v_mfma_f32_16x16x32_bf16 v[72:75], v[158:161], v[230:233], v[72:75]
	v_mfma_f32_16x16x32_bf16 v[88:91], v[158:161], v[214:217], v[88:91]
	v_mfma_f32_16x16x32_bf16 v[104:107], v[158:161], v[206:209], v[104:107]
	v_mfma_f32_16x16x32_bf16 v[124:127], v[158:161], v[198:201], v[124:127]
	v_mfma_f32_16x16x32_bf16 v[120:123], v[172:175], v[188:191], 0
	v_mfma_f32_16x16x32_bf16 v[100:103], v[172:175], v[202:205], 0
	v_mfma_f32_16x16x32_bf16 v[84:87], v[172:175], v[210:213], 0
	v_mfma_f32_16x16x32_bf16 v[68:71], v[172:175], v[218:221], 0
	v_mfma_f32_16x16x32_bf16 v[64:67], v[180:183], v[218:221], 0
	v_mfma_f32_16x16x32_bf16 v[80:83], v[180:183], v[210:213], 0
	v_mfma_f32_16x16x32_bf16 v[96:99], v[180:183], v[202:205], 0
	v_mfma_f32_16x16x32_bf16 v[116:119], v[180:183], v[188:191], 0
	v_mfma_f32_16x16x32_bf16 v[120:123], v[176:179], v[198:201], v[120:123]
	v_mfma_f32_16x16x32_bf16 v[100:103], v[176:179], v[206:209], v[100:103]
	v_mfma_f32_16x16x32_bf16 v[84:87], v[176:179], v[214:217], v[84:87]
	v_mfma_f32_16x16x32_bf16 v[68:71], v[176:179], v[230:233], v[68:71]
	v_mfma_f32_16x16x32_bf16 v[64:67], v[184:187], v[230:233], v[64:67]
	v_mfma_f32_16x16x32_bf16 v[80:83], v[184:187], v[214:217], v[80:83]
	v_mfma_f32_16x16x32_bf16 v[96:99], v[184:187], v[206:209], v[96:99]
	v_mfma_f32_16x16x32_bf16 v[116:119], v[184:187], v[198:201], v[116:119]
	s_barrier
	s_add_i32 s78, s78, s74
	v_lshl_add_u64 v[162:163], s[66:67], 0, v[192:193]
	s_mov_b32 m0, s78
	ds_read_b128 v[188:191], v171 offset:16384
	ds_read_b128 v[198:201], v171 offset:17408
	ds_read_b128 v[202:205], v171 offset:18432
	ds_read_b128 v[206:209], v171 offset:19456
	ds_read_b128 v[210:213], v171 offset:20480
	ds_read_b128 v[214:217], v171 offset:21504
	ds_read_b128 v[218:221], v171 offset:22528
	ds_read_b128 v[230:233], v171 offset:23552
	global_load_lds_dwordx4 v[162:163], off
	s_add_i32 m0, s78, 0x2000
	s_add_u32 s78, s66, 0x40000
	v_lshl_add_u64 v[234:235], s[66:67], 0, v[134:135]
	s_addc_u32 s79, s67, 0
	s_add_i32 s63, s63, s74
	global_load_lds_dwordx4 v[234:235], off
	v_lshl_add_u64 v[236:237], s[78:79], 0, v[192:193]
	s_mov_b32 m0, s63
	v_lshl_add_u64 v[238:239], s[70:71], 0, v[136:137]
	global_load_lds_dwordx4 v[236:237], off
	v_lshl_add_u64 v[236:237], s[78:79], 0, v[134:135]
	s_add_i32 m0, s63, 0x2000
	s_nop 0
	global_load_lds_dwordx4 v[236:237], off
	v_lshl_add_u64 v[236:237], s[70:71], 0, v[138:139]
	s_mov_b32 m0, s75
	s_nop 0
	global_load_lds_dwordx4 v[236:237], off
	s_mov_b32 m0, s81
	s_nop 0
	global_load_lds_dwordx4 v[238:239], off
	s_waitcnt vmcnt(8)
	s_waitcnt lgkmcnt(0)
	s_barrier
; #define PG8_STAGE(bufoff, gbase, voff) do { _Pragma("unroll") for (int _i = 0; _i < 2; ++_i) \
;         __builtin_amdgcn_global_load_lds((const unsigned*)((const char*)(gbase) + (voff)[_i]), (LAS unsigned*)(lds + (bufoff) + ldsw + _i * 8192), 16, 0, 0); } while (0)
; #define PG8_LDA(dst, b, h) do { _Pragma("unroll") for (int m = 0; m < 4; ++m) _Pragma("unroll") for (int k = 0; k < 2; ++k) dst[m][k] = *(const LAS bf16x8*)(lds + PG8_SA(b, h) + aoff + m * 2048 + k * 1024); } while (0)
; #define PG8_LDB(dst, b, h) do { _Pragma("unroll") for (int n = 0; n < 2; ++n) _Pragma("unroll") for (int k = 0; k < 2; ++k) dst[n][k] = *(const LAS bf16x8*)(lds + PG8_SB(b, h) + boff + n * 2048 + k * 1024); } while (0)
; #define PG8_MMA(ai, bj, At, Bt) do { __builtin_amdgcn_s_setprio(1); _Pragma("unroll") for (int m = 0; m < 4; ++m) _Pragma("unroll") for (int n = 0; n < 2; ++n) _Pragma("unroll") for (int k = 0; k < 2; ++k) \
;         acc[ai][bj][m][n] = __builtin_amdgcn_mfma_f32_16x16x32_bf16(Bt[n][k], At[m][k], acc[ai][bj][m][n], 0, 0, 0); __builtin_amdgcn_s_setprio(0); } while (0)
; #define PG8_WAIT_V(n) asm volatile("s_waitcnt vmcnt(" #n ")" ::: "memory")
; #define PG8_WAIT_L(n) asm volatile("s_waitcnt lgkmcnt(" #n ")" ::: "memory")
; #define PG8_BAR __builtin_amdgcn_s_barrier()
; #define PG8_SCHED __builtin_amdgcn_sched_barrier(0)
; template <class Epi, class Sched>
; __device__ __forceinline__ void gemm_phase(LAS unsigned char* lds, const Gemm g, const Sched& S, const Epi& E, const int tid) {
;     ...
;             PG8_WAIT_V(8); PG8_WAIT_L(0); PG8_BAR; PG8_MMA(1, 0, At, B0); PG8_MMA(1, 1, At, B1); PG8_BAR; PG8_SCHED;
;             PG8_LDB(B0, 1, 0); PG8_LDB(B1, 1, 1); PG8_SCHED; PG8_LDA(At, 1, 0); PG8_STAGE(PG8_SA(0, 1), a2 + hstep, voffA);
;             PG8_WAIT_V(8); PG8_WAIT_L(0); PG8_BAR; PG8_MMA(0, 0, At, B0); PG8_MMA(0, 1, At, B1); PG8_BAR; PG8_SCHED;
	s_waitcnt lgkmcnt(0)
	v_mfma_f32_16x16x32_bf16 v[60:63], v[146:149], v[188:191], 0
	v_mfma_f32_16x16x32_bf16 v[44:47], v[146:149], v[202:205], 0
	v_mfma_f32_16x16x32_bf16 v[28:31], v[146:149], v[210:213], 0
	v_mfma_f32_16x16x32_bf16 v[12:15], v[146:149], v[218:221], 0
	v_mfma_f32_16x16x32_bf16 v[8:11], v[154:157], v[218:221], 0
	v_mfma_f32_16x16x32_bf16 v[24:27], v[154:157], v[210:213], 0
	v_mfma_f32_16x16x32_bf16 v[40:43], v[154:157], v[202:205], 0
	v_mfma_f32_16x16x32_bf16 v[56:59], v[154:157], v[188:191], 0
	v_mfma_f32_16x16x32_bf16 v[60:63], v[150:153], v[198:201], v[60:63]
	v_mfma_f32_16x16x32_bf16 v[44:47], v[150:153], v[206:209], v[44:47]
	v_mfma_f32_16x16x32_bf16 v[28:31], v[150:153], v[214:217], v[28:31]
	v_mfma_f32_16x16x32_bf16 v[12:15], v[150:153], v[230:233], v[12:15]
	v_mfma_f32_16x16x32_bf16 v[8:11], v[158:161], v[230:233], v[8:11]
	v_mfma_f32_16x16x32_bf16 v[24:27], v[158:161], v[214:217], v[24:27]
	v_mfma_f32_16x16x32_bf16 v[40:43], v[158:161], v[206:209], v[40:43]
	v_mfma_f32_16x16x32_bf16 v[56:59], v[158:161], v[198:201], v[56:59]
	v_mfma_f32_16x16x32_bf16 v[52:55], v[172:175], v[188:191], 0
	v_mfma_f32_16x16x32_bf16 v[36:39], v[172:175], v[202:205], 0
	v_mfma_f32_16x16x32_bf16 v[20:23], v[172:175], v[210:213], 0
	v_mfma_f32_16x16x32_bf16 v[4:7], v[172:175], v[218:221], 0
	v_mfma_f32_16x16x32_bf16 v[0:3], v[180:183], v[218:221], 0
	v_mfma_f32_16x16x32_bf16 v[16:19], v[180:183], v[210:213], 0
	v_mfma_f32_16x16x32_bf16 v[32:35], v[180:183], v[202:205], 0
	v_mfma_f32_16x16x32_bf16 v[48:51], v[180:183], v[188:191], 0
	v_mfma_f32_16x16x32_bf16 v[52:55], v[176:179], v[198:201], v[52:55]
	v_mfma_f32_16x16x32_bf16 v[36:39], v[176:179], v[206:209], v[36:39]
	v_mfma_f32_16x16x32_bf16 v[20:23], v[176:179], v[214:217], v[20:23]
	v_mfma_f32_16x16x32_bf16 v[4:7], v[176:179], v[230:233], v[4:7]
	v_mfma_f32_16x16x32_bf16 v[0:3], v[184:187], v[230:233], v[0:3]
	v_mfma_f32_16x16x32_bf16 v[16:19], v[184:187], v[214:217], v[16:19]
	v_mfma_f32_16x16x32_bf16 v[32:35], v[184:187], v[206:209], v[32:35]
	v_mfma_f32_16x16x32_bf16 v[48:51], v[184:187], v[198:201], v[48:51]
	s_barrier
	s_add_i32 s63, 0, 0x18000
	v_add_u32_e32 v145, s63, v166
	s_add_i32 s78, 0, 0x1c000
	ds_read_b128 v[146:149], v145
	ds_read_b128 v[150:153], v145 offset:1024
	ds_read_b128 v[154:157], v145 offset:2048
	ds_read_b128 v[158:161], v145 offset:3072
	v_add_u32_e32 v145, s78, v166
	ds_read_b128 v[172:175], v145
	ds_read_b128 v[176:179], v145 offset:1024
	ds_read_b128 v[180:183], v145 offset:2048
	ds_read_b128 v[184:187], v145 offset:3072
	s_add_u32 s70, s70, 0x40000
	s_addc_u32 s71, s71, 0
	s_mov_b32 m0, s82
	v_lshl_add_u64 v[240:241], s[70:71], 0, v[138:139]
	ds_read_b128 v[188:191], v171 offset:32768
	ds_read_b128 v[198:201], v171 offset:33792
	ds_read_b128 v[202:205], v171 offset:34816
	ds_read_b128 v[206:209], v171 offset:35840
	ds_read_b128 v[210:213], v171 offset:36864
	ds_read_b128 v[214:217], v171 offset:37888
	ds_read_b128 v[218:221], v171 offset:38912
	ds_read_b128 v[230:233], v171 offset:39936
	global_load_lds_dwordx4 v[240:241], off
	v_lshl_add_u64 v[240:241], s[70:71], 0, v[136:137]
	s_mov_b32 m0, s83
	s_nop 0
	global_load_lds_dwordx4 v[240:241], off
	s_waitcnt vmcnt(8)
	s_waitcnt lgkmcnt(0)
	s_barrier
	s_waitcnt lgkmcnt(0)
	v_mfma_f32_16x16x32_bf16 v[128:131], v[146:149], v[188:191], v[128:131]
	v_mfma_f32_16x16x32_bf16 v[108:111], v[146:149], v[202:205], v[108:111]
	v_mfma_f32_16x16x32_bf16 v[92:95], v[146:149], v[210:213], v[92:95]
	v_mfma_f32_16x16x32_bf16 v[76:79], v[146:149], v[218:221], v[76:79]
	v_mfma_f32_16x16x32_bf16 v[72:75], v[154:157], v[218:221], v[72:75]
	v_mfma_f32_16x16x32_bf16 v[88:91], v[154:157], v[210:213], v[88:91]
	v_mfma_f32_16x16x32_bf16 v[104:107], v[154:157], v[202:205], v[104:107]
	v_mfma_f32_16x16x32_bf16 v[124:127], v[154:157], v[188:191], v[124:127]
	v_mfma_f32_16x16x32_bf16 v[128:131], v[150:153], v[198:201], v[128:131]
	v_mfma_f32_16x16x32_bf16 v[108:111], v[150:153], v[206:209], v[108:111]
	v_mfma_f32_16x16x32_bf16 v[92:95], v[150:153], v[214:217], v[92:95]
	v_mfma_f32_16x16x32_bf16 v[76:79], v[150:153], v[230:233], v[76:79]
	v_mfma_f32_16x16x32_bf16 v[72:75], v[158:161], v[230:233], v[72:75]
	v_mfma_f32_16x16x32_bf16 v[88:91], v[158:161], v[214:217], v[88:91]
	v_mfma_f32_16x16x32_bf16 v[104:107], v[158:161], v[206:209], v[104:107]
	v_mfma_f32_16x16x32_bf16 v[124:127], v[158:161], v[198:201], v[124:127]
	v_mfma_f32_16x16x32_bf16 v[120:123], v[172:175], v[188:191], v[120:123]
	v_mfma_f32_16x16x32_bf16 v[100:103], v[172:175], v[202:205], v[100:103]
	v_mfma_f32_16x16x32_bf16 v[84:87], v[172:175], v[210:213], v[84:87]
	v_mfma_f32_16x16x32_bf16 v[68:71], v[172:175], v[218:221], v[68:71]
	v_mfma_f32_16x16x32_bf16 v[64:67], v[180:183], v[218:221], v[64:67]
	v_mfma_f32_16x16x32_bf16 v[80:83], v[180:183], v[210:213], v[80:83]
	v_mfma_f32_16x16x32_bf16 v[96:99], v[180:183], v[202:205], v[96:99]
	v_mfma_f32_16x16x32_bf16 v[116:119], v[180:183], v[188:191], v[116:119]
	v_mfma_f32_16x16x32_bf16 v[120:123], v[176:179], v[198:201], v[120:123]
	v_mfma_f32_16x16x32_bf16 v[100:103], v[176:179], v[206:209], v[100:103]
	v_mfma_f32_16x16x32_bf16 v[84:87], v[176:179], v[214:217], v[84:87]
	v_mfma_f32_16x16x32_bf16 v[68:71], v[176:179], v[230:233], v[68:71]
	v_mfma_f32_16x16x32_bf16 v[64:67], v[184:187], v[230:233], v[64:67]
	v_mfma_f32_16x16x32_bf16 v[80:83], v[184:187], v[214:217], v[80:83]
	v_mfma_f32_16x16x32_bf16 v[96:99], v[184:187], v[206:209], v[96:99]
	v_mfma_f32_16x16x32_bf16 v[116:119], v[184:187], v[198:201], v[116:119]
	s_barrier
; #define PG8_STAGE(bufoff, gbase, voff) do { _Pragma("unroll") for (int _i = 0; _i < 2; ++_i) \
;         __builtin_amdgcn_global_load_lds((const unsigned*)((const char*)(gbase) + (voff)[_i]), (LAS unsigned*)(lds + (bufoff) + ldsw + _i * 8192), 16, 0, 0); } while (0)
; #define PG8_LDA(dst, b, h) do { _Pragma("unroll") for (int m = 0; m < 4; ++m) _Pragma("unroll") for (int k = 0; k < 2; ++k) dst[m][k] = *(const LAS bf16x8*)(lds + PG8_SA(b, h) + aoff + m * 2048 + k * 1024); } while (0)
; #define PG8_LDB(dst, b, h) do { _Pragma("unroll") for (int n = 0; n < 2; ++n) _Pragma("unroll") for (int k = 0; k < 2; ++k) dst[n][k] = *(const LAS bf16x8*)(lds + PG8_SB(b, h) + boff + n * 2048 + k * 1024); } while (0)
; #define PG8_MMA(ai, bj, At, Bt) do { __builtin_amdgcn_s_setprio(1); _Pragma("unroll") for (int m = 0; m < 4; ++m) _Pragma("unroll") for (int n = 0; n < 2; ++n) _Pragma("unroll") for (int k = 0; k < 2; ++k) \
;         acc[ai][bj][m][n] = __builtin_amdgcn_mfma_f32_16x16x32_bf16(Bt[n][k], At[m][k], acc[ai][bj][m][n], 0, 0, 0); __builtin_amdgcn_s_setprio(0); } while (0)
; #define PG8_WAIT_V(n) asm volatile("s_waitcnt vmcnt(" #n ")" ::: "memory")
; #define PG8_BAR __builtin_amdgcn_s_barrier()
; template <class Epi, class Sched>
; __device__ __forceinline__ void gemm_phase(LAS unsigned char* lds, const Gemm g, const Sched& S, const Epi& E, const int tid) {
;     ...
;             PG8_LDB(B0, 0, 0); PG8_LDB(B1, 0, 1); PG8_SCHED; PG8_LDA(At, 0, 0); PG8_STAGE(PG8_SA(1, 1), a1 + hstep, voffA);
;             PG8_WAIT_V(8); PG8_WAIT_L(0); PG8_BAR; PG8_MMA(0, 0, At, B0); PG8_MMA(0, 1, At, B1); PG8_BAR; PG8_SCHED;
;             PG8_LDA(At, 0, 1); PG8_STAGE(PG8_SB(0, 0), b2, voffB); PG8_STAGE(PG8_SB(0, 1), b2 + hstep, voffB); PG8_STAGE(PG8_SA(0, 0), a2, voffA);
;             PG8_WAIT_V(8); PG8_WAIT_L(0); PG8_BAR; PG8_MMA(1, 0, At, B0); PG8_MMA(1, 1, At, B1); PG8_BAR; PG8_SCHED;
;             PG8_LDB(B0, 1, 0); PG8_LDB(B1, 1, 1); PG8_SCHED; PG8_LDA(At, 1, 0); PG8_STAGE(PG8_SA(0, 1), a2 + hstep, voffA);
;             PG8_WAIT_V(8); PG8_WAIT_L(0); PG8_BAR; PG8_MMA(0, 0, At, B0); PG8_MMA(0, 1, At, B1); PG8_BAR; PG8_SCHED;
;             PG8_LDA(At, 1, 1); PG8_STAGE(PG8_SB(1, 0), b3, voffB); PG8_STAGE(PG8_SB(1, 1), b3 + hstep, voffB); PG8_STAGE(PG8_SA(1, 0), a3, voffA);
;             PG8_WAIT_V(8); PG8_WAIT_L(0); PG8_BAR; PG8_MMA(1, 0, At, B0); PG8_MMA(1, 1, At, B1); PG8_BAR; PG8_SCHED;
	s_add_i32 s63, s63, s74
	v_lshl_add_u64 v[162:163], v[162:163], 0, s[68:69]
	s_mov_b32 m0, s63
	ds_read_b128 v[188:191], v171 offset:49152
	ds_read_b128 v[198:201], v171 offset:50176
	ds_read_b128 v[202:205], v171 offset:51200
	ds_read_b128 v[206:209], v171 offset:52224
	ds_read_b128 v[210:213], v171 offset:53248
	ds_read_b128 v[214:217], v171 offset:54272
	ds_read_b128 v[218:221], v171 offset:55296
	ds_read_b128 v[230:233], v171 offset:56320
	global_load_lds_dwordx4 v[162:163], off
	s_add_i32 m0, s63, 0x2000
	s_add_u32 s66, s66, 0x40080
	v_lshl_add_u64 v[162:163], v[234:235], 0, s[68:69]
	s_addc_u32 s67, s67, 0
	s_add_i32 s63, s78, s74
	global_load_lds_dwordx4 v[162:163], off
	v_lshl_add_u64 v[162:163], s[66:67], 0, v[192:193]
	s_mov_b32 m0, s63
	s_nop 0
	global_load_lds_dwordx4 v[162:163], off
	v_lshl_add_u64 v[162:163], s[66:67], 0, v[134:135]
	s_add_i32 m0, s63, 0x2000
	s_nop 0
	global_load_lds_dwordx4 v[162:163], off
	v_lshl_add_u64 v[162:163], v[236:237], 0, s[68:69]
	s_mov_b32 m0, s93
	s_nop 0
	global_load_lds_dwordx4 v[162:163], off
	v_lshl_add_u64 v[162:163], v[238:239], 0, s[68:69]
	s_mov_b32 m0, s94
	s_nop 0
	global_load_lds_dwordx4 v[162:163], off
	s_waitcnt vmcnt(8)
	s_waitcnt lgkmcnt(0)
	s_barrier
	s_waitcnt lgkmcnt(0)
	v_mfma_f32_16x16x32_bf16 v[60:63], v[146:149], v[188:191], v[60:63]
	v_mfma_f32_16x16x32_bf16 v[44:47], v[146:149], v[202:205], v[44:47]
	v_mfma_f32_16x16x32_bf16 v[28:31], v[146:149], v[210:213], v[28:31]
	v_mfma_f32_16x16x32_bf16 v[12:15], v[146:149], v[218:221], v[12:15]
	v_mfma_f32_16x16x32_bf16 v[8:11], v[154:157], v[218:221], v[8:11]
	v_mfma_f32_16x16x32_bf16 v[24:27], v[154:157], v[210:213], v[24:27]
	v_mfma_f32_16x16x32_bf16 v[40:43], v[154:157], v[202:205], v[40:43]
	v_mfma_f32_16x16x32_bf16 v[56:59], v[154:157], v[188:191], v[56:59]
	v_mfma_f32_16x16x32_bf16 v[60:63], v[150:153], v[198:201], v[60:63]
	v_mfma_f32_16x16x32_bf16 v[44:47], v[150:153], v[206:209], v[44:47]
	v_mfma_f32_16x16x32_bf16 v[28:31], v[150:153], v[214:217], v[28:31]
	v_mfma_f32_16x16x32_bf16 v[12:15], v[150:153], v[230:233], v[12:15]
	v_mfma_f32_16x16x32_bf16 v[8:11], v[158:161], v[230:233], v[8:11]
	v_mfma_f32_16x16x32_bf16 v[24:27], v[158:161], v[214:217], v[24:27]
	v_mfma_f32_16x16x32_bf16 v[40:43], v[158:161], v[206:209], v[40:43]
	v_mfma_f32_16x16x32_bf16 v[56:59], v[158:161], v[198:201], v[56:59]
	v_mfma_f32_16x16x32_bf16 v[52:55], v[172:175], v[188:191], v[52:55]
	v_mfma_f32_16x16x32_bf16 v[36:39], v[172:175], v[202:205], v[36:39]
	v_mfma_f32_16x16x32_bf16 v[20:23], v[172:175], v[210:213], v[20:23]
	v_mfma_f32_16x16x32_bf16 v[4:7], v[172:175], v[218:221], v[4:7]
	v_mfma_f32_16x16x32_bf16 v[0:3], v[180:183], v[218:221], v[0:3]
	v_mfma_f32_16x16x32_bf16 v[16:19], v[180:183], v[210:213], v[16:19]
	v_mfma_f32_16x16x32_bf16 v[32:35], v[180:183], v[202:205], v[32:35]
	v_mfma_f32_16x16x32_bf16 v[48:51], v[180:183], v[188:191], v[48:51]
	v_mfma_f32_16x16x32_bf16 v[52:55], v[176:179], v[198:201], v[52:55]
	v_mfma_f32_16x16x32_bf16 v[36:39], v[176:179], v[206:209], v[36:39]
	v_mfma_f32_16x16x32_bf16 v[20:23], v[176:179], v[214:217], v[20:23]
	v_mfma_f32_16x16x32_bf16 v[4:7], v[176:179], v[230:233], v[4:7]
	v_mfma_f32_16x16x32_bf16 v[0:3], v[184:187], v[230:233], v[0:3]
	v_mfma_f32_16x16x32_bf16 v[16:19], v[184:187], v[214:217], v[16:19]
	v_mfma_f32_16x16x32_bf16 v[32:35], v[184:187], v[206:209], v[32:35]
	v_mfma_f32_16x16x32_bf16 v[48:51], v[184:187], v[198:201], v[48:51]
	s_barrier
	s_add_i32 s61, s61, 2
	s_add_u32 s64, s64, 0x100
	s_addc_u32 s65, s65, 0
	s_add_u32 s59, s59, 0x100
	s_addc_u32 s60, s60, 0
	s_cmp_gt_u32 s61, 13
.LBB0_168:
	s_add_u32 s63, s64, 0xfffc0080
	s_addc_u32 s66, s65, -1
	s_add_i32 s78, 0, 0x10000
	s_cmp_eq_u32 s61, 12
	s_cselect_b32 s71, s55, s66
	s_cselect_b32 s70, s56, s63
	v_add_u32_e32 v145, s78, v166
	s_cselect_b32 s67, s57, s60
	s_cselect_b32 s66, s58, s59
	s_add_i32 s63, 0, 0x14000
	ds_read_b128 v[146:149], v145
	ds_read_b128 v[150:153], v145 offset:1024
	ds_read_b128 v[154:157], v145 offset:2048
	ds_read_b128 v[158:161], v145 offset:3072
	v_add_u32_e32 v145, s63, v166
	ds_read_b128 v[172:175], v145
	ds_read_b128 v[176:179], v145 offset:1024
	ds_read_b128 v[180:183], v145 offset:2048
	ds_read_b128 v[184:187], v145 offset:3072
	v_lshl_add_u64 v[162:163], s[64:65], 0, v[140:141]
	s_add_i32 m0, s75, 0xc000
	ds_read_b128 v[188:191], v171
	ds_read_b128 v[198:201], v171 offset:1024
	ds_read_b128 v[202:205], v171 offset:2048
	ds_read_b128 v[206:209], v171 offset:3072
	ds_read_b128 v[210:213], v171 offset:4096
	ds_read_b128 v[214:217], v171 offset:5120
	ds_read_b128 v[218:221], v171 offset:6144
	ds_read_b128 v[230:233], v171 offset:7168
	global_load_lds_dwordx4 v[162:163], off
	v_lshl_add_u64 v[162:163], s[64:65], 0, v[142:143]
	s_add_i32 m0, s75, 0xe000
	s_nop 0
	global_load_lds_dwordx4 v[162:163], off
	s_waitcnt vmcnt(8)
	s_waitcnt lgkmcnt(0)
	s_barrier
; #define PG8_STAGE(bufoff, gbase, voff) do { _Pragma("unroll") for (int _i = 0; _i < 2; ++_i) \
;         __builtin_amdgcn_global_load_lds((const unsigned*)((const char*)(gbase) + (voff)[_i]), (LAS unsigned*)(lds + (bufoff) + ldsw + _i * 8192), 16, 0, 0); } while (0)
; #define PG8_LDA(dst, b, h) do { _Pragma("unroll") for (int m = 0; m < 4; ++m) _Pragma("unroll") for (int k = 0; k < 2; ++k) dst[m][k] = *(const LAS bf16x8*)(lds + PG8_SA(b, h) + aoff + m * 2048 + k * 1024); } while (0)
; #define PG8_MMA(ai, bj, At, Bt) do { __builtin_amdgcn_s_setprio(1); _Pragma("unroll") for (int m = 0; m < 4; ++m) _Pragma("unroll") for (int n = 0; n < 2; ++n) _Pragma("unroll") for (int k = 0; k < 2; ++k) \
;         acc[ai][bj][m][n] = __builtin_amdgcn_mfma_f32_16x16x32_bf16(Bt[n][k], At[m][k], acc[ai][bj][m][n], 0, 0, 0); __builtin_amdgcn_s_setprio(0); } while (0)
; #define PG8_WAIT_V(n) asm volatile("s_waitcnt vmcnt(" #n ")" ::: "memory")
; #define PG8_WAIT_L(n) asm volatile("s_waitcnt lgkmcnt(" #n ")" ::: "memory")
; #define PG8_BAR __builtin_amdgcn_s_barrier()
; #define PG8_SCHED __builtin_amdgcn_sched_barrier(0)
; template <class Epi, class Sched>
; __device__ __forceinline__ void gemm_phase(LAS unsigned char* lds, const Gemm g, const Sched& S, const Epi& E, const int tid) {
;     ...
;             PG8_WAIT_V(8); PG8_WAIT_L(0); PG8_BAR; PG8_MMA(0, 0, At, B0); PG8_MMA(0, 1, At, B1); PG8_BAR; PG8_SCHED;
;             PG8_LDA(At, 0, 1); PG8_STAGE(PG8_SB(0, 0), b2, voffB); PG8_STAGE(PG8_SB(0, 1), b2 + hstep, voffB); PG8_STAGE(PG8_SA(0, 0), a2, voffA);
;             PG8_WAIT_V(8); PG8_WAIT_L(0); PG8_BAR; PG8_MMA(1, 0, At, B0); PG8_MMA(1, 1, At, B1); PG8_BAR; PG8_SCHED;
	s_waitcnt lgkmcnt(0)
	v_mfma_f32_16x16x32_bf16 v[128:131], v[146:149], v[188:191], v[128:131]
	v_mfma_f32_16x16x32_bf16 v[108:111], v[146:149], v[202:205], v[108:111]
	v_mfma_f32_16x16x32_bf16 v[92:95], v[146:149], v[210:213], v[92:95]
	v_mfma_f32_16x16x32_bf16 v[76:79], v[146:149], v[218:221], v[76:79]
	v_mfma_f32_16x16x32_bf16 v[72:75], v[154:157], v[218:221], v[72:75]
	v_mfma_f32_16x16x32_bf16 v[88:91], v[154:157], v[210:213], v[88:91]
	v_mfma_f32_16x16x32_bf16 v[104:107], v[154:157], v[202:205], v[104:107]
	v_mfma_f32_16x16x32_bf16 v[124:127], v[154:157], v[188:191], v[124:127]
	v_mfma_f32_16x16x32_bf16 v[128:131], v[150:153], v[198:201], v[128:131]
	v_mfma_f32_16x16x32_bf16 v[108:111], v[150:153], v[206:209], v[108:111]
	v_mfma_f32_16x16x32_bf16 v[92:95], v[150:153], v[214:217], v[92:95]
	v_mfma_f32_16x16x32_bf16 v[76:79], v[150:153], v[230:233], v[76:79]
	v_mfma_f32_16x16x32_bf16 v[72:75], v[158:161], v[230:233], v[72:75]
	v_mfma_f32_16x16x32_bf16 v[88:91], v[158:161], v[214:217], v[88:91]
	v_mfma_f32_16x16x32_bf16 v[104:107], v[158:161], v[206:209], v[104:107]
	v_mfma_f32_16x16x32_bf16 v[124:127], v[158:161], v[198:201], v[124:127]
	v_mfma_f32_16x16x32_bf16 v[120:123], v[172:175], v[188:191], v[120:123]
	v_mfma_f32_16x16x32_bf16 v[100:103], v[172:175], v[202:205], v[100:103]
	v_mfma_f32_16x16x32_bf16 v[84:87], v[172:175], v[210:213], v[84:87]
	v_mfma_f32_16x16x32_bf16 v[68:71], v[172:175], v[218:221], v[68:71]
	v_mfma_f32_16x16x32_bf16 v[64:67], v[180:183], v[218:221], v[64:67]
	v_mfma_f32_16x16x32_bf16 v[80:83], v[180:183], v[210:213], v[80:83]
	v_mfma_f32_16x16x32_bf16 v[96:99], v[180:183], v[202:205], v[96:99]
	v_mfma_f32_16x16x32_bf16 v[116:119], v[180:183], v[188:191], v[116:119]
	v_mfma_f32_16x16x32_bf16 v[120:123], v[176:179], v[198:201], v[120:123]
	v_mfma_f32_16x16x32_bf16 v[100:103], v[176:179], v[206:209], v[100:103]
	v_mfma_f32_16x16x32_bf16 v[84:87], v[176:179], v[214:217], v[84:87]
	v_mfma_f32_16x16x32_bf16 v[68:71], v[176:179], v[230:233], v[68:71]
	v_mfma_f32_16x16x32_bf16 v[64:67], v[184:187], v[230:233], v[64:67]
	v_mfma_f32_16x16x32_bf16 v[80:83], v[184:187], v[214:217], v[80:83]
	v_mfma_f32_16x16x32_bf16 v[96:99], v[184:187], v[206:209], v[96:99]
	v_mfma_f32_16x16x32_bf16 v[116:119], v[184:187], v[198:201], v[116:119]
	s_barrier
	s_add_i32 s78, s78, s74
	v_lshl_add_u64 v[162:163], s[66:67], 0, v[192:193]
	s_mov_b32 m0, s78
	ds_read_b128 v[188:191], v171 offset:16384
	ds_read_b128 v[198:201], v171 offset:17408
	ds_read_b128 v[202:205], v171 offset:18432
	ds_read_b128 v[206:209], v171 offset:19456
	ds_read_b128 v[210:213], v171 offset:20480
	ds_read_b128 v[214:217], v171 offset:21504
	ds_read_b128 v[218:221], v171 offset:22528
	ds_read_b128 v[230:233], v171 offset:23552
	global_load_lds_dwordx4 v[162:163], off
	s_add_i32 m0, s78, 0x2000
	s_add_u32 s78, s66, 0x40000
	v_lshl_add_u64 v[234:235], s[66:67], 0, v[134:135]
	s_addc_u32 s79, s67, 0
	s_add_i32 s63, s63, s74
	global_load_lds_dwordx4 v[234:235], off
	v_lshl_add_u64 v[236:237], s[78:79], 0, v[192:193]
	s_mov_b32 m0, s63
	v_lshl_add_u64 v[238:239], s[70:71], 0, v[136:137]
	global_load_lds_dwordx4 v[236:237], off
	v_lshl_add_u64 v[236:237], s[78:79], 0, v[134:135]
	s_add_i32 m0, s63, 0x2000
	s_nop 0
	global_load_lds_dwordx4 v[236:237], off
	v_lshl_add_u64 v[236:237], s[70:71], 0, v[138:139]
	s_mov_b32 m0, s75
	s_nop 0
	global_load_lds_dwordx4 v[236:237], off
	s_mov_b32 m0, s81
	s_nop 0
	global_load_lds_dwordx4 v[238:239], off
	s_waitcnt vmcnt(8)
	s_waitcnt lgkmcnt(0)
	s_barrier
	s_waitcnt lgkmcnt(0)
	v_mfma_f32_16x16x32_bf16 v[60:63], v[146:149], v[188:191], v[60:63]
	v_mfma_f32_16x16x32_bf16 v[44:47], v[146:149], v[202:205], v[44:47]
	v_mfma_f32_16x16x32_bf16 v[28:31], v[146:149], v[210:213], v[28:31]
	v_mfma_f32_16x16x32_bf16 v[12:15], v[146:149], v[218:221], v[12:15]
	v_mfma_f32_16x16x32_bf16 v[8:11], v[154:157], v[218:221], v[8:11]
	v_mfma_f32_16x16x32_bf16 v[24:27], v[154:157], v[210:213], v[24:27]
	v_mfma_f32_16x16x32_bf16 v[40:43], v[154:157], v[202:205], v[40:43]
	v_mfma_f32_16x16x32_bf16 v[56:59], v[154:157], v[188:191], v[56:59]
	v_mfma_f32_16x16x32_bf16 v[60:63], v[150:153], v[198:201], v[60:63]
	v_mfma_f32_16x16x32_bf16 v[44:47], v[150:153], v[206:209], v[44:47]
	v_mfma_f32_16x16x32_bf16 v[28:31], v[150:153], v[214:217], v[28:31]
	v_mfma_f32_16x16x32_bf16 v[12:15], v[150:153], v[230:233], v[12:15]
	v_mfma_f32_16x16x32_bf16 v[8:11], v[158:161], v[230:233], v[8:11]
	v_mfma_f32_16x16x32_bf16 v[24:27], v[158:161], v[214:217], v[24:27]
	v_mfma_f32_16x16x32_bf16 v[40:43], v[158:161], v[206:209], v[40:43]
	v_mfma_f32_16x16x32_bf16 v[56:59], v[158:161], v[198:201], v[56:59]
	v_mfma_f32_16x16x32_bf16 v[52:55], v[172:175], v[188:191], v[52:55]
	v_mfma_f32_16x16x32_bf16 v[36:39], v[172:175], v[202:205], v[36:39]
	v_mfma_f32_16x16x32_bf16 v[20:23], v[172:175], v[210:213], v[20:23]
	v_mfma_f32_16x16x32_bf16 v[4:7], v[172:175], v[218:221], v[4:7]
	v_mfma_f32_16x16x32_bf16 v[0:3], v[180:183], v[218:221], v[0:3]
	v_mfma_f32_16x16x32_bf16 v[16:19], v[180:183], v[210:213], v[16:19]
	v_mfma_f32_16x16x32_bf16 v[32:35], v[180:183], v[202:205], v[32:35]
	v_mfma_f32_16x16x32_bf16 v[48:51], v[180:183], v[188:191], v[48:51]
	v_mfma_f32_16x16x32_bf16 v[52:55], v[176:179], v[198:201], v[52:55]
	v_mfma_f32_16x16x32_bf16 v[36:39], v[176:179], v[206:209], v[36:39]
	v_mfma_f32_16x16x32_bf16 v[20:23], v[176:179], v[214:217], v[20:23]
	v_mfma_f32_16x16x32_bf16 v[4:7], v[176:179], v[230:233], v[4:7]
	v_mfma_f32_16x16x32_bf16 v[0:3], v[184:187], v[230:233], v[0:3]
	v_mfma_f32_16x16x32_bf16 v[16:19], v[184:187], v[214:217], v[16:19]
	v_mfma_f32_16x16x32_bf16 v[32:35], v[184:187], v[206:209], v[32:35]
	v_mfma_f32_16x16x32_bf16 v[48:51], v[184:187], v[198:201], v[48:51]
	s_barrier
; #define PG8_STAGE(bufoff, gbase, voff) do { _Pragma("unroll") for (int _i = 0; _i < 2; ++_i) \
;         __builtin_amdgcn_global_load_lds((const unsigned*)((const char*)(gbase) + (voff)[_i]), (LAS unsigned*)(lds + (bufoff) + ldsw + _i * 8192), 16, 0, 0); } while (0)
; #define PG8_LDA(dst, b, h) do { _Pragma("unroll") for (int m = 0; m < 4; ++m) _Pragma("unroll") for (int k = 0; k < 2; ++k) dst[m][k] = *(const LAS bf16x8*)(lds + PG8_SA(b, h) + aoff + m * 2048 + k * 1024); } while (0)
; #define PG8_LDB(dst, b, h) do { _Pragma("unroll") for (int n = 0; n < 2; ++n) _Pragma("unroll") for (int k = 0; k < 2; ++k) dst[n][k] = *(const LAS bf16x8*)(lds + PG8_SB(b, h) + boff + n * 2048 + k * 1024); } while (0)
; #define PG8_MMA(ai, bj, At, Bt) do { __builtin_amdgcn_s_setprio(1); _Pragma("unroll") for (int m = 0; m < 4; ++m) _Pragma("unroll") for (int n = 0; n < 2; ++n) _Pragma("unroll") for (int k = 0; k < 2; ++k) \
;         acc[ai][bj][m][n] = __builtin_amdgcn_mfma_f32_16x16x32_bf16(Bt[n][k], At[m][k], acc[ai][bj][m][n], 0, 0, 0); __builtin_amdgcn_s_setprio(0); } while (0)
; #define PG8_WAIT_V(n) asm volatile("s_waitcnt vmcnt(" #n ")" ::: "memory")
; #define PG8_WAIT_L(n) asm volatile("s_waitcnt lgkmcnt(" #n ")" ::: "memory")
; #define PG8_BAR __builtin_amdgcn_s_barrier()
; #define PG8_SCHED __builtin_amdgcn_sched_barrier(0)
; template <class Epi, class Sched>
; __device__ __forceinline__ void gemm_phase(LAS unsigned char* lds, const Gemm g, const Sched& S, const Epi& E, const int tid) {
;     ...
;             PG8_LDB(B0, 1, 0); PG8_LDB(B1, 1, 1); PG8_SCHED; PG8_LDA(At, 1, 0); PG8_STAGE(PG8_SA(0, 1), a2 + hstep, voffA);
;             PG8_WAIT_V(8); PG8_WAIT_L(0); PG8_BAR; PG8_MMA(0, 0, At, B0); PG8_MMA(0, 1, At, B1); PG8_BAR; PG8_SCHED;
	s_add_i32 s63, 0, 0x18000
	v_add_u32_e32 v145, s63, v166
	s_add_i32 s78, 0, 0x1c000
	ds_read_b128 v[146:149], v145
	ds_read_b128 v[150:153], v145 offset:1024
	ds_read_b128 v[154:157], v145 offset:2048
	ds_read_b128 v[158:161], v145 offset:3072
	v_add_u32_e32 v145, s78, v166
	ds_read_b128 v[172:175], v145
	ds_read_b128 v[176:179], v145 offset:1024
	ds_read_b128 v[180:183], v145 offset:2048
	ds_read_b128 v[184:187], v145 offset:3072
	s_add_u32 s70, s70, 0x40000
	s_addc_u32 s71, s71, 0
	s_mov_b32 m0, s82
	v_lshl_add_u64 v[240:241], s[70:71], 0, v[138:139]
	ds_read_b128 v[188:191], v171 offset:32768
	ds_read_b128 v[198:201], v171 offset:33792
	ds_read_b128 v[202:205], v171 offset:34816
	ds_read_b128 v[206:209], v171 offset:35840
	ds_read_b128 v[210:213], v171 offset:36864
	ds_read_b128 v[214:217], v171 offset:37888
	ds_read_b128 v[218:221], v171 offset:38912
	ds_read_b128 v[230:233], v171 offset:39936
	global_load_lds_dwordx4 v[240:241], off
	v_lshl_add_u64 v[240:241], s[70:71], 0, v[136:137]
	s_mov_b32 m0, s83
	s_nop 0
	global_load_lds_dwordx4 v[240:241], off
	s_waitcnt vmcnt(8)
	s_waitcnt lgkmcnt(0)
	s_barrier
	s_waitcnt lgkmcnt(0)
	v_mfma_f32_16x16x32_bf16 v[128:131], v[146:149], v[188:191], v[128:131]
	v_mfma_f32_16x16x32_bf16 v[108:111], v[146:149], v[202:205], v[108:111]
	v_mfma_f32_16x16x32_bf16 v[92:95], v[146:149], v[210:213], v[92:95]
	v_mfma_f32_16x16x32_bf16 v[76:79], v[146:149], v[218:221], v[76:79]
	v_mfma_f32_16x16x32_bf16 v[72:75], v[154:157], v[218:221], v[72:75]
	v_mfma_f32_16x16x32_bf16 v[88:91], v[154:157], v[210:213], v[88:91]
	v_mfma_f32_16x16x32_bf16 v[104:107], v[154:157], v[202:205], v[104:107]
	v_mfma_f32_16x16x32_bf16 v[124:127], v[154:157], v[188:191], v[124:127]
	v_mfma_f32_16x16x32_bf16 v[128:131], v[150:153], v[198:201], v[128:131]
	v_mfma_f32_16x16x32_bf16 v[108:111], v[150:153], v[206:209], v[108:111]
	v_mfma_f32_16x16x32_bf16 v[92:95], v[150:153], v[214:217], v[92:95]
	v_mfma_f32_16x16x32_bf16 v[76:79], v[150:153], v[230:233], v[76:79]
	v_mfma_f32_16x16x32_bf16 v[72:75], v[158:161], v[230:233], v[72:75]
	v_mfma_f32_16x16x32_bf16 v[88:91], v[158:161], v[214:217], v[88:91]
	v_mfma_f32_16x16x32_bf16 v[104:107], v[158:161], v[206:209], v[104:107]
	v_mfma_f32_16x16x32_bf16 v[124:127], v[158:161], v[198:201], v[124:127]
	v_mfma_f32_16x16x32_bf16 v[120:123], v[172:175], v[188:191], v[120:123]
	v_mfma_f32_16x16x32_bf16 v[100:103], v[172:175], v[202:205], v[100:103]
	v_mfma_f32_16x16x32_bf16 v[84:87], v[172:175], v[210:213], v[84:87]
	v_mfma_f32_16x16x32_bf16 v[68:71], v[172:175], v[218:221], v[68:71]
	v_mfma_f32_16x16x32_bf16 v[64:67], v[180:183], v[218:221], v[64:67]
	v_mfma_f32_16x16x32_bf16 v[80:83], v[180:183], v[210:213], v[80:83]
	v_mfma_f32_16x16x32_bf16 v[96:99], v[180:183], v[202:205], v[96:99]
	v_mfma_f32_16x16x32_bf16 v[116:119], v[180:183], v[188:191], v[116:119]
	v_mfma_f32_16x16x32_bf16 v[120:123], v[176:179], v[198:201], v[120:123]
	v_mfma_f32_16x16x32_bf16 v[100:103], v[176:179], v[206:209], v[100:103]
	v_mfma_f32_16x16x32_bf16 v[84:87], v[176:179], v[214:217], v[84:87]
	v_mfma_f32_16x16x32_bf16 v[68:71], v[176:179], v[230:233], v[68:71]
	v_mfma_f32_16x16x32_bf16 v[64:67], v[184:187], v[230:233], v[64:67]
	v_mfma_f32_16x16x32_bf16 v[80:83], v[184:187], v[214:217], v[80:83]
	v_mfma_f32_16x16x32_bf16 v[96:99], v[184:187], v[206:209], v[96:99]
	v_mfma_f32_16x16x32_bf16 v[116:119], v[184:187], v[198:201], v[116:119]
	s_barrier
; #define PG8_STAGE(bufoff, gbase, voff) do { _Pragma("unroll") for (int _i = 0; _i < 2; ++_i) \
;         __builtin_amdgcn_global_load_lds((const unsigned*)((const char*)(gbase) + (voff)[_i]), (LAS unsigned*)(lds + (bufoff) + ldsw + _i * 8192), 16, 0, 0); } while (0)
; #define PG8_LDA(dst, b, h) do { _Pragma("unroll") for (int m = 0; m < 4; ++m) _Pragma("unroll") for (int k = 0; k < 2; ++k) dst[m][k] = *(const LAS bf16x8*)(lds + PG8_SA(b, h) + aoff + m * 2048 + k * 1024); } while (0)
; #define PG8_MMA(ai, bj, At, Bt) do { __builtin_amdgcn_s_setprio(1); _Pragma("unroll") for (int m = 0; m < 4; ++m) _Pragma("unroll") for (int n = 0; n < 2; ++n) _Pragma("unroll") for (int k = 0; k < 2; ++k) \
;         acc[ai][bj][m][n] = __builtin_amdgcn_mfma_f32_16x16x32_bf16(Bt[n][k], At[m][k], acc[ai][bj][m][n], 0, 0, 0); __builtin_amdgcn_s_setprio(0); } while (0)
; #define PG8_WAIT_V(n) asm volatile("s_waitcnt vmcnt(" #n ")" ::: "memory")
; #define PG8_WAIT_L(n) asm volatile("s_waitcnt lgkmcnt(" #n ")" ::: "memory")
; #define PG8_BAR __builtin_amdgcn_s_barrier()
; #define PG8_SCHED __builtin_amdgcn_sched_barrier(0)
; template <class Epi, class Sched>
; __device__ __forceinline__ void gemm_phase(LAS unsigned char* lds, const Gemm g, const Sched& S, const Epi& E, const int tid) {
;     ...
;             PG8_LDA(At, 1, 1); PG8_STAGE(PG8_SB(1, 0), b3, voffB); PG8_STAGE(PG8_SB(1, 1), b3 + hstep, voffB); PG8_STAGE(PG8_SA(1, 0), a3, voffA);
;             PG8_WAIT_V(8); PG8_WAIT_L(0); PG8_BAR; PG8_MMA(1, 0, At, B0); PG8_MMA(1, 1, At, B1); PG8_BAR; PG8_SCHED;
;         }
;         if (wr == 0) PG8_BAR;
	s_add_i32 s63, s63, s74
	v_lshl_add_u64 v[162:163], v[162:163], 0, s[68:69]
	s_mov_b32 m0, s63
	ds_read_b128 v[188:191], v171 offset:49152
	ds_read_b128 v[198:201], v171 offset:50176
	ds_read_b128 v[202:205], v171 offset:51200
	ds_read_b128 v[206:209], v171 offset:52224
	ds_read_b128 v[210:213], v171 offset:53248
	ds_read_b128 v[214:217], v171 offset:54272
	ds_read_b128 v[218:221], v171 offset:55296
	ds_read_b128 v[230:233], v171 offset:56320
	global_load_lds_dwordx4 v[162:163], off
	s_add_i32 m0, s63, 0x2000
	s_add_u32 s66, s66, 0x40080
	v_lshl_add_u64 v[162:163], v[234:235], 0, s[68:69]
	s_addc_u32 s67, s67, 0
	s_add_i32 s63, s78, s74
	global_load_lds_dwordx4 v[162:163], off
	v_lshl_add_u64 v[162:163], s[66:67], 0, v[192:193]
	s_mov_b32 m0, s63
	s_nop 0
	global_load_lds_dwordx4 v[162:163], off
	v_lshl_add_u64 v[162:163], s[66:67], 0, v[134:135]
	s_add_i32 m0, s63, 0x2000
	s_nop 0
	global_load_lds_dwordx4 v[162:163], off
	v_lshl_add_u64 v[162:163], v[236:237], 0, s[68:69]
	s_mov_b32 m0, s93
	s_nop 0
	global_load_lds_dwordx4 v[162:163], off
	v_lshl_add_u64 v[162:163], v[238:239], 0, s[68:69]
	s_mov_b32 m0, s94
	s_nop 0
	global_load_lds_dwordx4 v[162:163], off
	s_waitcnt vmcnt(8)
	s_waitcnt lgkmcnt(0)
	s_barrier
	s_waitcnt lgkmcnt(0)
	v_mfma_f32_16x16x32_bf16 v[60:63], v[146:149], v[188:191], v[60:63]
	v_mfma_f32_16x16x32_bf16 v[44:47], v[146:149], v[202:205], v[44:47]
	v_mfma_f32_16x16x32_bf16 v[28:31], v[146:149], v[210:213], v[28:31]
	v_mfma_f32_16x16x32_bf16 v[12:15], v[146:149], v[218:221], v[12:15]
	v_mfma_f32_16x16x32_bf16 v[8:11], v[154:157], v[218:221], v[8:11]
	v_mfma_f32_16x16x32_bf16 v[24:27], v[154:157], v[210:213], v[24:27]
	v_mfma_f32_16x16x32_bf16 v[40:43], v[154:157], v[202:205], v[40:43]
	v_mfma_f32_16x16x32_bf16 v[56:59], v[154:157], v[188:191], v[56:59]
	v_mfma_f32_16x16x32_bf16 v[60:63], v[150:153], v[198:201], v[60:63]
	v_mfma_f32_16x16x32_bf16 v[44:47], v[150:153], v[206:209], v[44:47]
	v_mfma_f32_16x16x32_bf16 v[28:31], v[150:153], v[214:217], v[28:31]
	v_mfma_f32_16x16x32_bf16 v[12:15], v[150:153], v[230:233], v[12:15]
	v_mfma_f32_16x16x32_bf16 v[8:11], v[158:161], v[230:233], v[8:11]
	v_mfma_f32_16x16x32_bf16 v[24:27], v[158:161], v[214:217], v[24:27]
	v_mfma_f32_16x16x32_bf16 v[40:43], v[158:161], v[206:209], v[40:43]
	v_mfma_f32_16x16x32_bf16 v[56:59], v[158:161], v[198:201], v[56:59]
	v_mfma_f32_16x16x32_bf16 v[52:55], v[172:175], v[188:191], v[52:55]
	v_mfma_f32_16x16x32_bf16 v[36:39], v[172:175], v[202:205], v[36:39]
	v_mfma_f32_16x16x32_bf16 v[20:23], v[172:175], v[210:213], v[20:23]
	v_mfma_f32_16x16x32_bf16 v[4:7], v[172:175], v[218:221], v[4:7]
	v_mfma_f32_16x16x32_bf16 v[0:3], v[180:183], v[218:221], v[0:3]
	v_mfma_f32_16x16x32_bf16 v[16:19], v[180:183], v[210:213], v[16:19]
	v_mfma_f32_16x16x32_bf16 v[32:35], v[180:183], v[202:205], v[32:35]
	v_mfma_f32_16x16x32_bf16 v[48:51], v[180:183], v[188:191], v[48:51]
	v_mfma_f32_16x16x32_bf16 v[52:55], v[176:179], v[198:201], v[52:55]
	v_mfma_f32_16x16x32_bf16 v[36:39], v[176:179], v[206:209], v[36:39]
	v_mfma_f32_16x16x32_bf16 v[20:23], v[176:179], v[214:217], v[20:23]
	v_mfma_f32_16x16x32_bf16 v[4:7], v[176:179], v[230:233], v[4:7]
	v_mfma_f32_16x16x32_bf16 v[0:3], v[184:187], v[230:233], v[0:3]
	v_mfma_f32_16x16x32_bf16 v[16:19], v[184:187], v[214:217], v[16:19]
	v_mfma_f32_16x16x32_bf16 v[32:35], v[184:187], v[206:209], v[32:35]
	v_mfma_f32_16x16x32_bf16 v[48:51], v[184:187], v[198:201], v[48:51]
	s_barrier
	s_add_i32 s61, s61, 2
	s_add_u32 s64, s64, 0x100
	s_addc_u32 s65, s65, 0
	s_add_u32 s59, s59, 0x100
	s_addc_u32 s60, s60, 0
	s_cmp_gt_u32 s61, 13
	s_cbranch_scc0 .LBB0_168
	s_and_b64 vcc, exec, s[50:51]
	s_cbranch_vccz .LBB0_171
	s_barrier

;     __device__ __forceinline__ Pre prefetch(const Unit& u, int tid) const { return prenorm_load(stats, u.pn * BM, sW + (size_t)(u.pn >> 4) * SW_ROWS + u.pm * BM, tid); }
;     __device__ __forceinline__ Pre prefetch(const Unit& u, int tid) const { return prenorm_load(stats, u.pm * BM, sW + (size_t)(u.pm >> 4) * SW_ROWS + u.pn * BM, tid); }
;     __device__ __forceinline__ Pre prefetch(const Unit& u, int tid) const { return prenorm_load(stats, u.pm * BM, sW + (size_t)(u.pm >> 4) * SW_ROWS + u.pn * BM, tid); }
; #define PG8_STAGE(bufoff, gbase, voff) do { _Pragma("unroll") for (int _i = 0; _i < 2; ++_i) \
;         __builtin_amdgcn_global_load_lds((const unsigned*)((const char*)(gbase) + (voff)[_i]), (LAS unsigned*)(lds + (bufoff) + ldsw + _i * 8192), 16, 0, 0); } while (0)
; #define PG8_LDA(dst, b, h) do { _Pragma("unroll") for (int m = 0; m < 4; ++m) _Pragma("unroll") for (int k = 0; k < 2; ++k) dst[m][k] = *(const LAS bf16x8*)(lds + PG8_SA(b, h) + aoff + m * 2048 + k * 1024); } while (0)
; #define PG8_LDB(dst, b, h) do { _Pragma("unroll") for (int n = 0; n < 2; ++n) _Pragma("unroll") for (int k = 0; k < 2; ++k) dst[n][k] = *(const LAS bf16x8*)(lds + PG8_SB(b, h) + boff + n * 2048 + k * 1024); } while (0)
; template <class Epi, class Sched>
; __device__ __forceinline__ void gemm_phase(LAS unsigned char* lds, const Gemm g, const Sched& S, const Epi& E, const int tid) {
;     ...
;         const char* nA = has_next ? (const char*)g.A + (size_t)nxt.pm * tstep : cA; const char* nB = has_next ? (const char*)g.Bt + (size_t)nxt.pn * tstep : cB;
;         const typename Epi::Pre pre = E.prefetch(cur, tid);
;         for (int t = 0; t < nt; t += 2) {
;             const bool last = (t == nt - 2);
;             const char* a1 = cA + (size_t)(t + 1) * kstep;
;             const char* a2 = last ? nA : cA + (size_t)(t + 2) * kstep; const char* b2 = last ? nB : cB + (size_t)(t + 2) * kstep;
;             const char* a3 = a2 + kstep; const char* b3 = b2 + kstep;
;             PG8_LDB(B0, 0, 0); PG8_LDB(B1, 0, 1); PG8_SCHED; PG8_LDA(At, 0, 0); PG8_STAGE(PG8_SA(1, 1), a1 + hstep, voffA);
;             PG8_WAIT_V(8); PG8_WAIT_L(0); PG8_BAR; PG8_MMA(0, 0, At, B0); PG8_MMA(0, 1, At, B1); PG8_BAR; PG8_SCHED;
;             PG8_LDA(At, 0, 1); PG8_STAGE(PG8_SB(0, 0), b2, voffB); PG8_STAGE(PG8_SB(0, 1), b2 + hstep, voffB); PG8_STAGE(PG8_SA(0, 0), a2, voffA);
.LBB0_265:
	s_or_b64 exec, exec, s[38:39]
	s_ashr_i32 s23, s22, 31
	s_lshl_b64 s[38:39], s[22:23], 19
	s_add_u32 s38, s46, s38
	s_addc_u32 s39, s47, s39
	s_and_b64 s[56:57], s[4:5], exec
	s_cselect_b32 s23, s39, s7
	s_cselect_b32 s56, s38, s6
	s_ashr_i32 s55, s54, 31
	s_lshl_b64 s[58:59], s[54:55], 19
	s_add_u32 s62, s35, s58
	s_addc_u32 s63, s84, s59
	s_and_b64 s[58:59], s[4:5], exec
	s_cselect_b32 s55, s63, s65
	s_cselect_b32 s57, s62, s64
	s_add_u32 s6, s6, 0x40080
	s_addc_u32 s7, s7, 0
	s_add_u32 s58, s64, 0x100
	s_addc_u32 s59, s65, 0
	s_mov_b32 s60, -2
	s_add_u32 s61, s6, 0xfffc0080
	s_addc_u32 s64, s7, -1
	s_add_i32 s70, 0, 0x10000
	s_cmp_eq_u32 s60, 12
	s_cselect_b32 s67, s23, s64
	s_cselect_b32 s66, s56, s61
	v_add_u32_e32 v81, s70, v216
	s_cselect_b32 s65, s55, s59
	s_cselect_b32 s64, s57, s58
	s_add_i32 s61, 0, 0x14000
	ds_read_b128 v[88:91], v81
	ds_read_b128 v[92:95], v81 offset:1024
	ds_read_b128 v[144:147], v81 offset:2048
	ds_read_b128 v[148:151], v81 offset:3072
	v_add_u32_e32 v81, s61, v216
	ds_read_b128 v[152:155], v81
	ds_read_b128 v[156:159], v81 offset:1024
	ds_read_b128 v[178:181], v81 offset:2048
	ds_read_b128 v[182:185], v81 offset:3072
	v_lshl_add_u64 v[82:83], s[6:7], 0, v[174:175]
	s_add_i32 m0, s73, 0xc000
	ds_read_b128 v[186:189], v230
	ds_read_b128 v[198:201], v230 offset:1024
	ds_read_b128 v[202:205], v230 offset:2048
	ds_read_b128 v[206:209], v230 offset:3072
	ds_read_b128 v[234:237], v230 offset:4096
	ds_read_b128 v[238:241], v230 offset:5120
	ds_read_b128 v[242:245], v230 offset:6144
	ds_read_b128 v[246:249], v230 offset:7168
	global_load_lds_dwordx4 v[82:83], off
	v_lshl_add_u64 v[82:83], s[6:7], 0, v[176:177]
	s_add_i32 m0, s73, 0xe000
	s_nop 0
	global_load_lds_dwordx4 v[82:83], off
	s_waitcnt vmcnt(8)
	s_waitcnt lgkmcnt(0)
	s_barrier
	s_waitcnt lgkmcnt(0)
	v_mfma_f32_16x16x32_bf16 v[140:143], v[88:91], v[186:189], 0
	v_mfma_f32_16x16x32_bf16 v[124:127], v[88:91], v[202:205], 0
	v_mfma_f32_16x16x32_bf16 v[108:111], v[88:91], v[234:237], 0
	v_mfma_f32_16x16x32_bf16 v[82:85], v[88:91], v[242:245], 0
	v_mfma_f32_16x16x32_bf16 v[76:79], v[144:147], v[242:245], 0
	v_mfma_f32_16x16x32_bf16 v[104:107], v[144:147], v[234:237], 0
	v_mfma_f32_16x16x32_bf16 v[120:123], v[144:147], v[202:205], 0
	v_mfma_f32_16x16x32_bf16 v[136:139], v[144:147], v[186:189], 0
	v_mfma_f32_16x16x32_bf16 v[140:143], v[92:95], v[198:201], v[140:143]
	v_mfma_f32_16x16x32_bf16 v[124:127], v[92:95], v[206:209], v[124:127]
	v_mfma_f32_16x16x32_bf16 v[108:111], v[92:95], v[238:241], v[108:111]
	v_mfma_f32_16x16x32_bf16 v[82:85], v[92:95], v[246:249], v[82:85]
	v_mfma_f32_16x16x32_bf16 v[76:79], v[148:151], v[246:249], v[76:79]
	v_mfma_f32_16x16x32_bf16 v[104:107], v[148:151], v[238:241], v[104:107]
	v_mfma_f32_16x16x32_bf16 v[120:123], v[148:151], v[206:209], v[120:123]
	v_mfma_f32_16x16x32_bf16 v[136:139], v[148:151], v[198:201], v[136:139]
	v_mfma_f32_16x16x32_bf16 v[132:135], v[152:155], v[186:189], 0
	v_mfma_f32_16x16x32_bf16 v[116:119], v[152:155], v[202:205], 0
	v_mfma_f32_16x16x32_bf16 v[100:103], v[152:155], v[234:237], 0
	v_mfma_f32_16x16x32_bf16 v[68:71], v[152:155], v[242:245], 0
	v_mfma_f32_16x16x32_bf16 v[64:67], v[178:181], v[242:245], 0
	v_mfma_f32_16x16x32_bf16 v[96:99], v[178:181], v[234:237], 0
	v_mfma_f32_16x16x32_bf16 v[112:115], v[178:181], v[202:205], 0
	v_mfma_f32_16x16x32_bf16 v[128:131], v[178:181], v[186:189], 0
	v_mfma_f32_16x16x32_bf16 v[132:135], v[156:159], v[198:201], v[132:135]
	v_mfma_f32_16x16x32_bf16 v[116:119], v[156:159], v[206:209], v[116:119]
	v_mfma_f32_16x16x32_bf16 v[100:103], v[156:159], v[238:241], v[100:103]
	v_mfma_f32_16x16x32_bf16 v[68:71], v[156:159], v[246:249], v[68:71]
	v_mfma_f32_16x16x32_bf16 v[64:67], v[182:185], v[246:249], v[64:67]
	v_mfma_f32_16x16x32_bf16 v[96:99], v[182:185], v[238:241], v[96:99]
	v_mfma_f32_16x16x32_bf16 v[112:115], v[182:185], v[206:209], v[112:115]
	v_mfma_f32_16x16x32_bf16 v[128:131], v[182:185], v[198:201], v[128:131]
	s_barrier
	s_add_i32 s70, s70, s12
	v_lshl_add_u64 v[190:191], s[64:65], 0, v[164:165]
	s_mov_b32 m0, s70
	ds_read_b128 v[186:189], v230 offset:16384
	ds_read_b128 v[198:201], v230 offset:17408
	ds_read_b128 v[202:205], v230 offset:18432
	ds_read_b128 v[206:209], v230 offset:19456
	ds_read_b128 v[234:237], v230 offset:20480
	ds_read_b128 v[238:241], v230 offset:21504
	ds_read_b128 v[242:245], v230 offset:22528
	ds_read_b128 v[246:249], v230 offset:23552
	global_load_lds_dwordx4 v[190:191], off
	s_add_i32 m0, s70, 0x2000
	s_add_u32 s70, s64, 0x40000
	v_lshl_add_u64 v[250:251], s[64:65], 0, v[168:169]
	s_addc_u32 s71, s65, 0
	s_add_i32 s61, s61, s12
	global_load_lds_dwordx4 v[250:251], off
	v_lshl_add_u64 v[86:87], s[70:71], 0, v[164:165]
	s_mov_b32 m0, s61
	v_lshl_add_u64 v[224:225], s[66:67], 0, v[162:163]
	global_load_lds_dwordx4 v[86:87], off
	v_lshl_add_u64 v[86:87], s[70:71], 0, v[168:169]
	s_add_i32 m0, s61, 0x2000
	v_lshl_add_u64 v[226:227], s[66:67], 0, v[166:167]
	global_load_lds_dwordx4 v[86:87], off
	s_mov_b32 m0, s73
	s_nop 0
	global_load_lds_dwordx4 v[224:225], off
	s_mov_b32 m0, s74
	s_nop 0
	global_load_lds_dwordx4 v[226:227], off
	s_waitcnt vmcnt(8)
	s_waitcnt lgkmcnt(0)
	s_barrier
; #define PG8_STAGE(bufoff, gbase, voff) do { _Pragma("unroll") for (int _i = 0; _i < 2; ++_i) \
;         __builtin_amdgcn_global_load_lds((const unsigned*)((const char*)(gbase) + (voff)[_i]), (LAS unsigned*)(lds + (bufoff) + ldsw + _i * 8192), 16, 0, 0); } while (0)
; #define PG8_LDA(dst, b, h) do { _Pragma("unroll") for (int m = 0; m < 4; ++m) _Pragma("unroll") for (int k = 0; k < 2; ++k) dst[m][k] = *(const LAS bf16x8*)(lds + PG8_SA(b, h) + aoff + m * 2048 + k * 1024); } while (0)
; #define PG8_LDB(dst, b, h) do { _Pragma("unroll") for (int n = 0; n < 2; ++n) _Pragma("unroll") for (int k = 0; k < 2; ++k) dst[n][k] = *(const LAS bf16x8*)(lds + PG8_SB(b, h) + boff + n * 2048 + k * 1024); } while (0)
; #define PG8_MMA(ai, bj, At, Bt) do { __builtin_amdgcn_s_setprio(1); _Pragma("unroll") for (int m = 0; m < 4; ++m) _Pragma("unroll") for (int n = 0; n < 2; ++n) _Pragma("unroll") for (int k = 0; k < 2; ++k) \
;         acc[ai][bj][m][n] = __builtin_amdgcn_mfma_f32_16x16x32_bf16(Bt[n][k], At[m][k], acc[ai][bj][m][n], 0, 0, 0); __builtin_amdgcn_s_setprio(0); } while (0)
; #define PG8_WAIT_V(n) asm volatile("s_waitcnt vmcnt(" #n ")" ::: "memory")
; #define PG8_WAIT_L(n) asm volatile("s_waitcnt lgkmcnt(" #n ")" ::: "memory")
; #define PG8_BAR __builtin_amdgcn_s_barrier()
; #define PG8_SCHED __builtin_amdgcn_sched_barrier(0)
; template <class Epi, class Sched>
; __device__ __forceinline__ void gemm_phase(LAS unsigned char* lds, const Gemm g, const Sched& S, const Epi& E, const int tid) {
;     ...
;             PG8_WAIT_V(8); PG8_WAIT_L(0); PG8_BAR; PG8_MMA(1, 0, At, B0); PG8_MMA(1, 1, At, B1); PG8_BAR; PG8_SCHED;
;             PG8_LDB(B0, 1, 0); PG8_LDB(B1, 1, 1); PG8_SCHED; PG8_LDA(At, 1, 0); PG8_STAGE(PG8_SA(0, 1), a2 + hstep, voffA);
;             PG8_WAIT_V(8); PG8_WAIT_L(0); PG8_BAR; PG8_MMA(0, 0, At, B0); PG8_MMA(0, 1, At, B1); PG8_BAR; PG8_SCHED;
	s_waitcnt lgkmcnt(0)
	v_mfma_f32_16x16x32_bf16 v[60:63], v[88:91], v[186:189], 0
	v_mfma_f32_16x16x32_bf16 v[44:47], v[88:91], v[202:205], 0
	v_mfma_f32_16x16x32_bf16 v[28:31], v[88:91], v[234:237], 0
	v_mfma_f32_16x16x32_bf16 v[12:15], v[88:91], v[242:245], 0
	v_mfma_f32_16x16x32_bf16 v[8:11], v[144:147], v[242:245], 0
	v_mfma_f32_16x16x32_bf16 v[24:27], v[144:147], v[234:237], 0
	v_mfma_f32_16x16x32_bf16 v[40:43], v[144:147], v[202:205], 0
	v_mfma_f32_16x16x32_bf16 v[56:59], v[144:147], v[186:189], 0
	v_mfma_f32_16x16x32_bf16 v[60:63], v[92:95], v[198:201], v[60:63]
	v_mfma_f32_16x16x32_bf16 v[44:47], v[92:95], v[206:209], v[44:47]
	v_mfma_f32_16x16x32_bf16 v[28:31], v[92:95], v[238:241], v[28:31]
	v_mfma_f32_16x16x32_bf16 v[12:15], v[92:95], v[246:249], v[12:15]
	v_mfma_f32_16x16x32_bf16 v[8:11], v[148:151], v[246:249], v[8:11]
	v_mfma_f32_16x16x32_bf16 v[24:27], v[148:151], v[238:241], v[24:27]
	v_mfma_f32_16x16x32_bf16 v[40:43], v[148:151], v[206:209], v[40:43]
	v_mfma_f32_16x16x32_bf16 v[56:59], v[148:151], v[198:201], v[56:59]
	v_mfma_f32_16x16x32_bf16 v[52:55], v[152:155], v[186:189], 0
	v_mfma_f32_16x16x32_bf16 v[36:39], v[152:155], v[202:205], 0
	v_mfma_f32_16x16x32_bf16 v[20:23], v[152:155], v[234:237], 0
	v_mfma_f32_16x16x32_bf16 v[4:7], v[152:155], v[242:245], 0
	v_mfma_f32_16x16x32_bf16 v[0:3], v[178:181], v[242:245], 0
	v_mfma_f32_16x16x32_bf16 v[16:19], v[178:181], v[234:237], 0
	v_mfma_f32_16x16x32_bf16 v[32:35], v[178:181], v[202:205], 0
	v_mfma_f32_16x16x32_bf16 v[48:51], v[178:181], v[186:189], 0
	v_mfma_f32_16x16x32_bf16 v[52:55], v[156:159], v[198:201], v[52:55]
	v_mfma_f32_16x16x32_bf16 v[36:39], v[156:159], v[206:209], v[36:39]
	v_mfma_f32_16x16x32_bf16 v[20:23], v[156:159], v[238:241], v[20:23]
	v_mfma_f32_16x16x32_bf16 v[4:7], v[156:159], v[246:249], v[4:7]
	v_mfma_f32_16x16x32_bf16 v[0:3], v[182:185], v[246:249], v[0:3]
	v_mfma_f32_16x16x32_bf16 v[16:19], v[182:185], v[238:241], v[16:19]
	v_mfma_f32_16x16x32_bf16 v[32:35], v[182:185], v[206:209], v[32:35]
	v_mfma_f32_16x16x32_bf16 v[48:51], v[182:185], v[198:201], v[48:51]
	s_barrier
	s_add_i32 s61, 0, 0x18000
	v_add_u32_e32 v81, s61, v216
	s_add_i32 s70, 0, 0x1c000
	ds_read_b128 v[88:91], v81
	ds_read_b128 v[92:95], v81 offset:1024
	ds_read_b128 v[144:147], v81 offset:2048
	ds_read_b128 v[148:151], v81 offset:3072
	v_add_u32_e32 v81, s70, v216
	ds_read_b128 v[152:155], v81
	ds_read_b128 v[156:159], v81 offset:1024
	ds_read_b128 v[178:181], v81 offset:2048
	ds_read_b128 v[182:185], v81 offset:3072
	s_add_u32 s66, s66, 0x40000
	s_addc_u32 s67, s67, 0
	s_mov_b32 m0, s75
	v_lshl_add_u64 v[86:87], s[66:67], 0, v[162:163]
	ds_read_b128 v[186:189], v230 offset:32768
	ds_read_b128 v[198:201], v230 offset:33792
	ds_read_b128 v[202:205], v230 offset:34816
	ds_read_b128 v[206:209], v230 offset:35840
	ds_read_b128 v[234:237], v230 offset:36864
	ds_read_b128 v[238:241], v230 offset:37888
	ds_read_b128 v[242:245], v230 offset:38912
	ds_read_b128 v[246:249], v230 offset:39936
	global_load_lds_dwordx4 v[86:87], off
	v_lshl_add_u64 v[86:87], s[66:67], 0, v[166:167]
	s_mov_b32 m0, s81
	s_nop 0
	global_load_lds_dwordx4 v[86:87], off
	s_waitcnt vmcnt(8)
	s_waitcnt lgkmcnt(0)
	s_barrier
	s_waitcnt lgkmcnt(0)
	v_mfma_f32_16x16x32_bf16 v[140:143], v[88:91], v[186:189], v[140:143]
	v_mfma_f32_16x16x32_bf16 v[124:127], v[88:91], v[202:205], v[124:127]
	v_mfma_f32_16x16x32_bf16 v[108:111], v[88:91], v[234:237], v[108:111]
	v_mfma_f32_16x16x32_bf16 v[82:85], v[88:91], v[242:245], v[82:85]
	v_mfma_f32_16x16x32_bf16 v[76:79], v[144:147], v[242:245], v[76:79]
	v_mfma_f32_16x16x32_bf16 v[104:107], v[144:147], v[234:237], v[104:107]
	v_mfma_f32_16x16x32_bf16 v[120:123], v[144:147], v[202:205], v[120:123]
	v_mfma_f32_16x16x32_bf16 v[136:139], v[144:147], v[186:189], v[136:139]
	v_mfma_f32_16x16x32_bf16 v[140:143], v[92:95], v[198:201], v[140:143]
	v_mfma_f32_16x16x32_bf16 v[124:127], v[92:95], v[206:209], v[124:127]
	v_mfma_f32_16x16x32_bf16 v[108:111], v[92:95], v[238:241], v[108:111]
	v_mfma_f32_16x16x32_bf16 v[84:87], v[92:95], v[246:249], v[82:85]
	v_mfma_f32_16x16x32_bf16 v[76:79], v[148:151], v[246:249], v[76:79]
	v_mfma_f32_16x16x32_bf16 v[104:107], v[148:151], v[238:241], v[104:107]
	v_mfma_f32_16x16x32_bf16 v[120:123], v[148:151], v[206:209], v[120:123]
	v_mfma_f32_16x16x32_bf16 v[136:139], v[148:151], v[198:201], v[136:139]
	v_mfma_f32_16x16x32_bf16 v[132:135], v[152:155], v[186:189], v[132:135]
	v_mfma_f32_16x16x32_bf16 v[116:119], v[152:155], v[202:205], v[116:119]
	v_mfma_f32_16x16x32_bf16 v[100:103], v[152:155], v[234:237], v[100:103]
	v_mfma_f32_16x16x32_bf16 v[68:71], v[152:155], v[242:245], v[68:71]
	v_mfma_f32_16x16x32_bf16 v[64:67], v[178:181], v[242:245], v[64:67]
	v_mfma_f32_16x16x32_bf16 v[96:99], v[178:181], v[234:237], v[96:99]
	v_mfma_f32_16x16x32_bf16 v[112:115], v[178:181], v[202:205], v[112:115]
	v_mfma_f32_16x16x32_bf16 v[128:131], v[178:181], v[186:189], v[128:131]
	v_mfma_f32_16x16x32_bf16 v[132:135], v[156:159], v[198:201], v[132:135]
	v_mfma_f32_16x16x32_bf16 v[116:119], v[156:159], v[206:209], v[116:119]
	v_mfma_f32_16x16x32_bf16 v[100:103], v[156:159], v[238:241], v[100:103]
	v_mfma_f32_16x16x32_bf16 v[68:71], v[156:159], v[246:249], v[68:71]
	v_mfma_f32_16x16x32_bf16 v[64:67], v[182:185], v[246:249], v[64:67]
	v_mfma_f32_16x16x32_bf16 v[96:99], v[182:185], v[238:241], v[96:99]
	v_mfma_f32_16x16x32_bf16 v[112:115], v[182:185], v[206:209], v[112:115]
	v_mfma_f32_16x16x32_bf16 v[128:131], v[182:185], v[198:201], v[128:131]
	s_barrier
; #define PG8_STAGE(bufoff, gbase, voff) do { _Pragma("unroll") for (int _i = 0; _i < 2; ++_i) \
;         __builtin_amdgcn_global_load_lds((const unsigned*)((const char*)(gbase) + (voff)[_i]), (LAS unsigned*)(lds + (bufoff) + ldsw + _i * 8192), 16, 0, 0); } while (0)
; #define PG8_LDA(dst, b, h) do { _Pragma("unroll") for (int m = 0; m < 4; ++m) _Pragma("unroll") for (int k = 0; k < 2; ++k) dst[m][k] = *(const LAS bf16x8*)(lds + PG8_SA(b, h) + aoff + m * 2048 + k * 1024); } while (0)
; #define PG8_LDB(dst, b, h) do { _Pragma("unroll") for (int n = 0; n < 2; ++n) _Pragma("unroll") for (int k = 0; k < 2; ++k) dst[n][k] = *(const LAS bf16x8*)(lds + PG8_SB(b, h) + boff + n * 2048 + k * 1024); } while (0)
; #define PG8_MMA(ai, bj, At, Bt) do { __builtin_amdgcn_s_setprio(1); _Pragma("unroll") for (int m = 0; m < 4; ++m) _Pragma("unroll") for (int n = 0; n < 2; ++n) _Pragma("unroll") for (int k = 0; k < 2; ++k) \
;         acc[ai][bj][m][n] = __builtin_amdgcn_mfma_f32_16x16x32_bf16(Bt[n][k], At[m][k], acc[ai][bj][m][n], 0, 0, 0); __builtin_amdgcn_s_setprio(0); } while (0)
; #define PG8_WAIT_V(n) asm volatile("s_waitcnt vmcnt(" #n ")" ::: "memory")
; #define PG8_BAR __builtin_amdgcn_s_barrier()
; template <class Epi, class Sched>
; __device__ __forceinline__ void gemm_phase(LAS unsigned char* lds, const Gemm g, const Sched& S, const Epi& E, const int tid) {
;     ...
;             PG8_LDB(B0, 0, 0); PG8_LDB(B1, 0, 1); PG8_SCHED; PG8_LDA(At, 0, 0); PG8_STAGE(PG8_SA(1, 1), a1 + hstep, voffA);
;             PG8_WAIT_V(8); PG8_WAIT_L(0); PG8_BAR; PG8_MMA(0, 0, At, B0); PG8_MMA(0, 1, At, B1); PG8_BAR; PG8_SCHED;
;             PG8_LDA(At, 0, 1); PG8_STAGE(PG8_SB(0, 0), b2, voffB); PG8_STAGE(PG8_SB(0, 1), b2 + hstep, voffB); PG8_STAGE(PG8_SA(0, 0), a2, voffA);
;             PG8_WAIT_V(8); PG8_WAIT_L(0); PG8_BAR; PG8_MMA(1, 0, At, B0); PG8_MMA(1, 1, At, B1); PG8_BAR; PG8_SCHED;
;             PG8_LDB(B0, 1, 0); PG8_LDB(B1, 1, 1); PG8_SCHED; PG8_LDA(At, 1, 0); PG8_STAGE(PG8_SA(0, 1), a2 + hstep, voffA);
;             PG8_WAIT_V(8); PG8_WAIT_L(0); PG8_BAR; PG8_MMA(0, 0, At, B0); PG8_MMA(0, 1, At, B1); PG8_BAR; PG8_SCHED;
;             PG8_LDA(At, 1, 1); PG8_STAGE(PG8_SB(1, 0), b3, voffB); PG8_STAGE(PG8_SB(1, 1), b3 + hstep, voffB); PG8_STAGE(PG8_SA(1, 0), a3, voffA);
;             PG8_WAIT_V(8); PG8_WAIT_L(0); PG8_BAR; PG8_MMA(1, 0, At, B0); PG8_MMA(1, 1, At, B1); PG8_BAR; PG8_SCHED;
	s_add_i32 s61, s61, s12
	v_lshl_add_u64 v[82:83], v[190:191], 0, s[68:69]
	s_mov_b32 m0, s61
	ds_read_b128 v[186:189], v230 offset:49152
	ds_read_b128 v[198:201], v230 offset:50176
	ds_read_b128 v[202:205], v230 offset:51200
	ds_read_b128 v[206:209], v230 offset:52224
	ds_read_b128 v[234:237], v230 offset:53248
	ds_read_b128 v[238:241], v230 offset:54272
	ds_read_b128 v[242:245], v230 offset:55296
	ds_read_b128 v[246:249], v230 offset:56320
	global_load_lds_dwordx4 v[82:83], off
	s_add_i32 m0, s61, 0x2000
	s_add_u32 s64, s64, 0x40080
	v_lshl_add_u64 v[82:83], v[250:251], 0, s[68:69]
	s_addc_u32 s65, s65, 0
	s_add_i32 s61, s70, s12
	global_load_lds_dwordx4 v[82:83], off
	v_lshl_add_u64 v[82:83], s[64:65], 0, v[164:165]
	s_mov_b32 m0, s61
	s_nop 0
	global_load_lds_dwordx4 v[82:83], off
	v_lshl_add_u64 v[82:83], s[64:65], 0, v[168:169]
	s_add_i32 m0, s61, 0x2000
	s_nop 0
	global_load_lds_dwordx4 v[82:83], off
	v_lshl_add_u64 v[82:83], v[224:225], 0, s[68:69]
	s_mov_b32 m0, s82
	s_nop 0
	global_load_lds_dwordx4 v[82:83], off
	v_lshl_add_u64 v[82:83], v[226:227], 0, s[68:69]
	s_mov_b32 m0, s83
	s_nop 0
	global_load_lds_dwordx4 v[82:83], off
	s_waitcnt vmcnt(8)
	s_waitcnt lgkmcnt(0)
	s_barrier
	s_waitcnt lgkmcnt(0)
	v_mfma_f32_16x16x32_bf16 v[60:63], v[88:91], v[186:189], v[60:63]
	v_mfma_f32_16x16x32_bf16 v[44:47], v[88:91], v[202:205], v[44:47]
	v_mfma_f32_16x16x32_bf16 v[28:31], v[88:91], v[234:237], v[28:31]
	v_mfma_f32_16x16x32_bf16 v[12:15], v[88:91], v[242:245], v[12:15]
	v_mfma_f32_16x16x32_bf16 v[8:11], v[144:147], v[242:245], v[8:11]
	v_mfma_f32_16x16x32_bf16 v[24:27], v[144:147], v[234:237], v[24:27]
	v_mfma_f32_16x16x32_bf16 v[40:43], v[144:147], v[202:205], v[40:43]
	v_mfma_f32_16x16x32_bf16 v[56:59], v[144:147], v[186:189], v[56:59]
	v_mfma_f32_16x16x32_bf16 v[60:63], v[92:95], v[198:201], v[60:63]
	v_mfma_f32_16x16x32_bf16 v[44:47], v[92:95], v[206:209], v[44:47]
	v_mfma_f32_16x16x32_bf16 v[28:31], v[92:95], v[238:241], v[28:31]
	v_mfma_f32_16x16x32_bf16 v[12:15], v[92:95], v[246:249], v[12:15]
	v_mfma_f32_16x16x32_bf16 v[8:11], v[148:151], v[246:249], v[8:11]
	v_mfma_f32_16x16x32_bf16 v[24:27], v[148:151], v[238:241], v[24:27]
	v_mfma_f32_16x16x32_bf16 v[40:43], v[148:151], v[206:209], v[40:43]
	v_mfma_f32_16x16x32_bf16 v[56:59], v[148:151], v[198:201], v[56:59]
	v_mfma_f32_16x16x32_bf16 v[52:55], v[152:155], v[186:189], v[52:55]
	v_mfma_f32_16x16x32_bf16 v[36:39], v[152:155], v[202:205], v[36:39]
	v_mfma_f32_16x16x32_bf16 v[20:23], v[152:155], v[234:237], v[20:23]
	v_mfma_f32_16x16x32_bf16 v[4:7], v[152:155], v[242:245], v[4:7]
	v_mfma_f32_16x16x32_bf16 v[0:3], v[178:181], v[242:245], v[0:3]
	v_mfma_f32_16x16x32_bf16 v[16:19], v[178:181], v[234:237], v[16:19]
	v_mfma_f32_16x16x32_bf16 v[32:35], v[178:181], v[202:205], v[32:35]
	v_mfma_f32_16x16x32_bf16 v[48:51], v[178:181], v[186:189], v[48:51]
	v_mfma_f32_16x16x32_bf16 v[52:55], v[156:159], v[198:201], v[52:55]
	v_mfma_f32_16x16x32_bf16 v[36:39], v[156:159], v[206:209], v[36:39]
	v_mfma_f32_16x16x32_bf16 v[20:23], v[156:159], v[238:241], v[20:23]
	v_mfma_f32_16x16x32_bf16 v[4:7], v[156:159], v[246:249], v[4:7]
	v_mfma_f32_16x16x32_bf16 v[0:3], v[182:185], v[246:249], v[0:3]
	v_mfma_f32_16x16x32_bf16 v[16:19], v[182:185], v[238:241], v[16:19]
	v_mfma_f32_16x16x32_bf16 v[32:35], v[182:185], v[206:209], v[32:35]
	v_mfma_f32_16x16x32_bf16 v[48:51], v[182:185], v[198:201], v[48:51]
	s_barrier
	s_add_i32 s60, s60, 2
	s_add_u32 s6, s6, 0x100
	s_addc_u32 s7, s7, 0
	s_add_u32 s58, s58, 0x100
	s_addc_u32 s59, s59, 0
	s_cmp_gt_u32 s60, 13
.LBB0_266:
	s_add_u32 s61, s6, 0xfffc0080
	s_addc_u32 s64, s7, -1
	s_add_i32 s70, 0, 0x10000
	s_cmp_eq_u32 s60, 12
	s_cselect_b32 s67, s23, s64
	s_cselect_b32 s66, s56, s61
	v_add_u32_e32 v81, s70, v216
	s_cselect_b32 s65, s55, s59
	s_cselect_b32 s64, s57, s58
	s_add_i32 s61, 0, 0x14000
	ds_read_b128 v[88:91], v81
	ds_read_b128 v[92:95], v81 offset:1024
	ds_read_b128 v[144:147], v81 offset:2048
	ds_read_b128 v[148:151], v81 offset:3072
	v_add_u32_e32 v81, s61, v216
	ds_read_b128 v[152:155], v81
	ds_read_b128 v[156:159], v81 offset:1024
	ds_read_b128 v[178:181], v81 offset:2048
	ds_read_b128 v[182:185], v81 offset:3072
	v_lshl_add_u64 v[82:83], s[6:7], 0, v[174:175]
	s_add_i32 m0, s73, 0xc000
	ds_read_b128 v[186:189], v230
	ds_read_b128 v[198:201], v230 offset:1024
	ds_read_b128 v[202:205], v230 offset:2048
	ds_read_b128 v[206:209], v230 offset:3072
	ds_read_b128 v[234:237], v230 offset:4096
	ds_read_b128 v[238:241], v230 offset:5120
	ds_read_b128 v[242:245], v230 offset:6144
	ds_read_b128 v[246:249], v230 offset:7168
	global_load_lds_dwordx4 v[82:83], off
	v_lshl_add_u64 v[82:83], s[6:7], 0, v[176:177]
	s_add_i32 m0, s73, 0xe000
	s_nop 0
	global_load_lds_dwordx4 v[82:83], off
	s_waitcnt vmcnt(8)
	s_waitcnt lgkmcnt(0)
	s_barrier
; #define PG8_STAGE(bufoff, gbase, voff) do { _Pragma("unroll") for (int _i = 0; _i < 2; ++_i) \
;         __builtin_amdgcn_global_load_lds((const unsigned*)((const char*)(gbase) + (voff)[_i]), (LAS unsigned*)(lds + (bufoff) + ldsw + _i * 8192), 16, 0, 0); } while (0)
; #define PG8_LDA(dst, b, h) do { _Pragma("unroll") for (int m = 0; m < 4; ++m) _Pragma("unroll") for (int k = 0; k < 2; ++k) dst[m][k] = *(const LAS bf16x8*)(lds + PG8_SA(b, h) + aoff + m * 2048 + k * 1024); } while (0)
; #define PG8_MMA(ai, bj, At, Bt) do { __builtin_amdgcn_s_setprio(1); _Pragma("unroll") for (int m = 0; m < 4; ++m) _Pragma("unroll") for (int n = 0; n < 2; ++n) _Pragma("unroll") for (int k = 0; k < 2; ++k) \
;         acc[ai][bj][m][n] = __builtin_amdgcn_mfma_f32_16x16x32_bf16(Bt[n][k], At[m][k], acc[ai][bj][m][n], 0, 0, 0); __builtin_amdgcn_s_setprio(0); } while (0)
; #define PG8_WAIT_V(n) asm volatile("s_waitcnt vmcnt(" #n ")" ::: "memory")
; #define PG8_WAIT_L(n) asm volatile("s_waitcnt lgkmcnt(" #n ")" ::: "memory")
; #define PG8_BAR __builtin_amdgcn_s_barrier()
; #define PG8_SCHED __builtin_amdgcn_sched_barrier(0)
; template <class Epi, class Sched>
; __device__ __forceinline__ void gemm_phase(LAS unsigned char* lds, const Gemm g, const Sched& S, const Epi& E, const int tid) {
;     ...
;             PG8_WAIT_V(8); PG8_WAIT_L(0); PG8_BAR; PG8_MMA(0, 0, At, B0); PG8_MMA(0, 1, At, B1); PG8_BAR; PG8_SCHED;
;             PG8_LDA(At, 0, 1); PG8_STAGE(PG8_SB(0, 0), b2, voffB); PG8_STAGE(PG8_SB(0, 1), b2 + hstep, voffB); PG8_STAGE(PG8_SA(0, 0), a2, voffA);
;             PG8_WAIT_V(8); PG8_WAIT_L(0); PG8_BAR; PG8_MMA(1, 0, At, B0); PG8_MMA(1, 1, At, B1); PG8_BAR; PG8_SCHED;
	s_waitcnt lgkmcnt(0)
	v_mfma_f32_16x16x32_bf16 v[140:143], v[88:91], v[186:189], v[140:143]
	v_mfma_f32_16x16x32_bf16 v[124:127], v[88:91], v[202:205], v[124:127]
	v_mfma_f32_16x16x32_bf16 v[108:111], v[88:91], v[234:237], v[108:111]
	v_mfma_f32_16x16x32_bf16 v[82:85], v[88:91], v[242:245], v[84:87]
	v_mfma_f32_16x16x32_bf16 v[76:79], v[144:147], v[242:245], v[76:79]
	v_mfma_f32_16x16x32_bf16 v[104:107], v[144:147], v[234:237], v[104:107]
	v_mfma_f32_16x16x32_bf16 v[120:123], v[144:147], v[202:205], v[120:123]
	v_mfma_f32_16x16x32_bf16 v[136:139], v[144:147], v[186:189], v[136:139]
	v_mfma_f32_16x16x32_bf16 v[140:143], v[92:95], v[198:201], v[140:143]
	v_mfma_f32_16x16x32_bf16 v[124:127], v[92:95], v[206:209], v[124:127]
	v_mfma_f32_16x16x32_bf16 v[108:111], v[92:95], v[238:241], v[108:111]
	v_mfma_f32_16x16x32_bf16 v[82:85], v[92:95], v[246:249], v[82:85]
	v_mfma_f32_16x16x32_bf16 v[76:79], v[148:151], v[246:249], v[76:79]
	v_mfma_f32_16x16x32_bf16 v[104:107], v[148:151], v[238:241], v[104:107]
	v_mfma_f32_16x16x32_bf16 v[120:123], v[148:151], v[206:209], v[120:123]
	v_mfma_f32_16x16x32_bf16 v[136:139], v[148:151], v[198:201], v[136:139]
	v_mfma_f32_16x16x32_bf16 v[132:135], v[152:155], v[186:189], v[132:135]
	v_mfma_f32_16x16x32_bf16 v[116:119], v[152:155], v[202:205], v[116:119]
	v_mfma_f32_16x16x32_bf16 v[100:103], v[152:155], v[234:237], v[100:103]
	v_mfma_f32_16x16x32_bf16 v[68:71], v[152:155], v[242:245], v[68:71]
	v_mfma_f32_16x16x32_bf16 v[64:67], v[178:181], v[242:245], v[64:67]
	v_mfma_f32_16x16x32_bf16 v[96:99], v[178:181], v[234:237], v[96:99]
	v_mfma_f32_16x16x32_bf16 v[112:115], v[178:181], v[202:205], v[112:115]
	v_mfma_f32_16x16x32_bf16 v[128:131], v[178:181], v[186:189], v[128:131]
	v_mfma_f32_16x16x32_bf16 v[132:135], v[156:159], v[198:201], v[132:135]
	v_mfma_f32_16x16x32_bf16 v[116:119], v[156:159], v[206:209], v[116:119]
	v_mfma_f32_16x16x32_bf16 v[100:103], v[156:159], v[238:241], v[100:103]
	v_mfma_f32_16x16x32_bf16 v[68:71], v[156:159], v[246:249], v[68:71]
	v_mfma_f32_16x16x32_bf16 v[64:67], v[182:185], v[246:249], v[64:67]
	v_mfma_f32_16x16x32_bf16 v[96:99], v[182:185], v[238:241], v[96:99]
	v_mfma_f32_16x16x32_bf16 v[112:115], v[182:185], v[206:209], v[112:115]
	v_mfma_f32_16x16x32_bf16 v[128:131], v[182:185], v[198:201], v[128:131]
	s_barrier
	s_add_i32 s70, s70, s12
	v_lshl_add_u64 v[190:191], s[64:65], 0, v[164:165]
	s_mov_b32 m0, s70
	ds_read_b128 v[186:189], v230 offset:16384
	ds_read_b128 v[198:201], v230 offset:17408
	ds_read_b128 v[202:205], v230 offset:18432
	ds_read_b128 v[206:209], v230 offset:19456
	ds_read_b128 v[234:237], v230 offset:20480
	ds_read_b128 v[238:241], v230 offset:21504
	ds_read_b128 v[242:245], v230 offset:22528
	ds_read_b128 v[246:249], v230 offset:23552
	global_load_lds_dwordx4 v[190:191], off
	s_add_i32 m0, s70, 0x2000
	s_add_u32 s70, s64, 0x40000
	v_lshl_add_u64 v[250:251], s[64:65], 0, v[168:169]
	s_addc_u32 s71, s65, 0
	s_add_i32 s61, s61, s12
	global_load_lds_dwordx4 v[250:251], off
	v_lshl_add_u64 v[86:87], s[70:71], 0, v[164:165]
	s_mov_b32 m0, s61
	v_lshl_add_u64 v[224:225], s[66:67], 0, v[162:163]
	global_load_lds_dwordx4 v[86:87], off
	v_lshl_add_u64 v[86:87], s[70:71], 0, v[168:169]
	s_add_i32 m0, s61, 0x2000
	v_lshl_add_u64 v[226:227], s[66:67], 0, v[166:167]
	global_load_lds_dwordx4 v[86:87], off
	s_mov_b32 m0, s73
	s_nop 0
	global_load_lds_dwordx4 v[224:225], off
	s_mov_b32 m0, s74
	s_nop 0
	global_load_lds_dwordx4 v[226:227], off
	s_waitcnt vmcnt(8)
	s_waitcnt lgkmcnt(0)
	s_barrier
	s_waitcnt lgkmcnt(0)
	v_mfma_f32_16x16x32_bf16 v[60:63], v[88:91], v[186:189], v[60:63]
	v_mfma_f32_16x16x32_bf16 v[44:47], v[88:91], v[202:205], v[44:47]
	v_mfma_f32_16x16x32_bf16 v[28:31], v[88:91], v[234:237], v[28:31]
	v_mfma_f32_16x16x32_bf16 v[12:15], v[88:91], v[242:245], v[12:15]
	v_mfma_f32_16x16x32_bf16 v[8:11], v[144:147], v[242:245], v[8:11]
	v_mfma_f32_16x16x32_bf16 v[24:27], v[144:147], v[234:237], v[24:27]
	v_mfma_f32_16x16x32_bf16 v[40:43], v[144:147], v[202:205], v[40:43]
	v_mfma_f32_16x16x32_bf16 v[56:59], v[144:147], v[186:189], v[56:59]
	v_mfma_f32_16x16x32_bf16 v[60:63], v[92:95], v[198:201], v[60:63]
	v_mfma_f32_16x16x32_bf16 v[44:47], v[92:95], v[206:209], v[44:47]
	v_mfma_f32_16x16x32_bf16 v[28:31], v[92:95], v[238:241], v[28:31]
	v_mfma_f32_16x16x32_bf16 v[12:15], v[92:95], v[246:249], v[12:15]
	v_mfma_f32_16x16x32_bf16 v[8:11], v[148:151], v[246:249], v[8:11]
	v_mfma_f32_16x16x32_bf16 v[24:27], v[148:151], v[238:241], v[24:27]
	v_mfma_f32_16x16x32_bf16 v[40:43], v[148:151], v[206:209], v[40:43]
	v_mfma_f32_16x16x32_bf16 v[56:59], v[148:151], v[198:201], v[56:59]
	v_mfma_f32_16x16x32_bf16 v[52:55], v[152:155], v[186:189], v[52:55]
	v_mfma_f32_16x16x32_bf16 v[36:39], v[152:155], v[202:205], v[36:39]
	v_mfma_f32_16x16x32_bf16 v[20:23], v[152:155], v[234:237], v[20:23]
	v_mfma_f32_16x16x32_bf16 v[4:7], v[152:155], v[242:245], v[4:7]
	v_mfma_f32_16x16x32_bf16 v[0:3], v[178:181], v[242:245], v[0:3]
	v_mfma_f32_16x16x32_bf16 v[16:19], v[178:181], v[234:237], v[16:19]
	v_mfma_f32_16x16x32_bf16 v[32:35], v[178:181], v[202:205], v[32:35]
	v_mfma_f32_16x16x32_bf16 v[48:51], v[178:181], v[186:189], v[48:51]
	v_mfma_f32_16x16x32_bf16 v[52:55], v[156:159], v[198:201], v[52:55]
	v_mfma_f32_16x16x32_bf16 v[36:39], v[156:159], v[206:209], v[36:39]
	v_mfma_f32_16x16x32_bf16 v[20:23], v[156:159], v[238:241], v[20:23]
	v_mfma_f32_16x16x32_bf16 v[4:7], v[156:159], v[246:249], v[4:7]
	v_mfma_f32_16x16x32_bf16 v[0:3], v[182:185], v[246:249], v[0:3]
	v_mfma_f32_16x16x32_bf16 v[16:19], v[182:185], v[238:241], v[16:19]
	v_mfma_f32_16x16x32_bf16 v[32:35], v[182:185], v[206:209], v[32:35]
	v_mfma_f32_16x16x32_bf16 v[48:51], v[182:185], v[198:201], v[48:51]
	s_barrier
; #define PG8_STAGE(bufoff, gbase, voff) do { _Pragma("unroll") for (int _i = 0; _i < 2; ++_i) \
;         __builtin_amdgcn_global_load_lds((const unsigned*)((const char*)(gbase) + (voff)[_i]), (LAS unsigned*)(lds + (bufoff) + ldsw + _i * 8192), 16, 0, 0); } while (0)
; #define PG8_LDA(dst, b, h) do { _Pragma("unroll") for (int m = 0; m < 4; ++m) _Pragma("unroll") for (int k = 0; k < 2; ++k) dst[m][k] = *(const LAS bf16x8*)(lds + PG8_SA(b, h) + aoff + m * 2048 + k * 1024); } while (0)
; #define PG8_LDB(dst, b, h) do { _Pragma("unroll") for (int n = 0; n < 2; ++n) _Pragma("unroll") for (int k = 0; k < 2; ++k) dst[n][k] = *(const LAS bf16x8*)(lds + PG8_SB(b, h) + boff + n * 2048 + k * 1024); } while (0)
; #define PG8_MMA(ai, bj, At, Bt) do { __builtin_amdgcn_s_setprio(1); _Pragma("unroll") for (int m = 0; m < 4; ++m) _Pragma("unroll") for (int n = 0; n < 2; ++n) _Pragma("unroll") for (int k = 0; k < 2; ++k) \
;         acc[ai][bj][m][n] = __builtin_amdgcn_mfma_f32_16x16x32_bf16(Bt[n][k], At[m][k], acc[ai][bj][m][n], 0, 0, 0); __builtin_amdgcn_s_setprio(0); } while (0)
; #define PG8_WAIT_V(n) asm volatile("s_waitcnt vmcnt(" #n ")" ::: "memory")
; #define PG8_WAIT_L(n) asm volatile("s_waitcnt lgkmcnt(" #n ")" ::: "memory")
; #define PG8_BAR __builtin_amdgcn_s_barrier()
; #define PG8_SCHED __builtin_amdgcn_sched_barrier(0)
; template <class Epi, class Sched>
; __device__ __forceinline__ void gemm_phase(LAS unsigned char* lds, const Gemm g, const Sched& S, const Epi& E, const int tid) {
;     ...
;             PG8_LDB(B0, 1, 0); PG8_LDB(B1, 1, 1); PG8_SCHED; PG8_LDA(At, 1, 0); PG8_STAGE(PG8_SA(0, 1), a2 + hstep, voffA);
;             PG8_WAIT_V(8); PG8_WAIT_L(0); PG8_BAR; PG8_MMA(0, 0, At, B0); PG8_MMA(0, 1, At, B1); PG8_BAR; PG8_SCHED;
	s_add_i32 s61, 0, 0x18000
	v_add_u32_e32 v81, s61, v216
	s_add_i32 s70, 0, 0x1c000
	ds_read_b128 v[88:91], v81
	ds_read_b128 v[92:95], v81 offset:1024
	ds_read_b128 v[144:147], v81 offset:2048
	ds_read_b128 v[148:151], v81 offset:3072
	v_add_u32_e32 v81, s70, v216
	ds_read_b128 v[152:155], v81
	ds_read_b128 v[156:159], v81 offset:1024
	ds_read_b128 v[178:181], v81 offset:2048
	ds_read_b128 v[182:185], v81 offset:3072
	s_add_u32 s66, s66, 0x40000
	s_addc_u32 s67, s67, 0
	s_mov_b32 m0, s75
	v_lshl_add_u64 v[86:87], s[66:67], 0, v[162:163]
	ds_read_b128 v[186:189], v230 offset:32768
	ds_read_b128 v[198:201], v230 offset:33792
	ds_read_b128 v[202:205], v230 offset:34816
	ds_read_b128 v[206:209], v230 offset:35840
	ds_read_b128 v[234:237], v230 offset:36864
	ds_read_b128 v[238:241], v230 offset:37888
	ds_read_b128 v[242:245], v230 offset:38912
	ds_read_b128 v[246:249], v230 offset:39936
	global_load_lds_dwordx4 v[86:87], off
	v_lshl_add_u64 v[86:87], s[66:67], 0, v[166:167]
	s_mov_b32 m0, s81
	s_nop 0
	global_load_lds_dwordx4 v[86:87], off
	s_waitcnt vmcnt(8)
	s_waitcnt lgkmcnt(0)
	s_barrier
	s_waitcnt lgkmcnt(0)
	v_mfma_f32_16x16x32_bf16 v[140:143], v[88:91], v[186:189], v[140:143]
	v_mfma_f32_16x16x32_bf16 v[124:127], v[88:91], v[202:205], v[124:127]
	v_mfma_f32_16x16x32_bf16 v[108:111], v[88:91], v[234:237], v[108:111]
	v_mfma_f32_16x16x32_bf16 v[82:85], v[88:91], v[242:245], v[82:85]
	v_mfma_f32_16x16x32_bf16 v[76:79], v[144:147], v[242:245], v[76:79]
	v_mfma_f32_16x16x32_bf16 v[104:107], v[144:147], v[234:237], v[104:107]
	v_mfma_f32_16x16x32_bf16 v[120:123], v[144:147], v[202:205], v[120:123]
	v_mfma_f32_16x16x32_bf16 v[136:139], v[144:147], v[186:189], v[136:139]
	v_mfma_f32_16x16x32_bf16 v[140:143], v[92:95], v[198:201], v[140:143]
	v_mfma_f32_16x16x32_bf16 v[124:127], v[92:95], v[206:209], v[124:127]
	v_mfma_f32_16x16x32_bf16 v[108:111], v[92:95], v[238:241], v[108:111]
	v_mfma_f32_16x16x32_bf16 v[84:87], v[92:95], v[246:249], v[82:85]
	v_mfma_f32_16x16x32_bf16 v[76:79], v[148:151], v[246:249], v[76:79]
	v_mfma_f32_16x16x32_bf16 v[104:107], v[148:151], v[238:241], v[104:107]
	v_mfma_f32_16x16x32_bf16 v[120:123], v[148:151], v[206:209], v[120:123]
	v_mfma_f32_16x16x32_bf16 v[136:139], v[148:151], v[198:201], v[136:139]
	v_mfma_f32_16x16x32_bf16 v[132:135], v[152:155], v[186:189], v[132:135]
	v_mfma_f32_16x16x32_bf16 v[116:119], v[152:155], v[202:205], v[116:119]
	v_mfma_f32_16x16x32_bf16 v[100:103], v[152:155], v[234:237], v[100:103]
	v_mfma_f32_16x16x32_bf16 v[68:71], v[152:155], v[242:245], v[68:71]
	v_mfma_f32_16x16x32_bf16 v[64:67], v[178:181], v[242:245], v[64:67]
	v_mfma_f32_16x16x32_bf16 v[96:99], v[178:181], v[234:237], v[96:99]
	v_mfma_f32_16x16x32_bf16 v[112:115], v[178:181], v[202:205], v[112:115]
	v_mfma_f32_16x16x32_bf16 v[128:131], v[178:181], v[186:189], v[128:131]
	v_mfma_f32_16x16x32_bf16 v[132:135], v[156:159], v[198:201], v[132:135]
	v_mfma_f32_16x16x32_bf16 v[116:119], v[156:159], v[206:209], v[116:119]
	v_mfma_f32_16x16x32_bf16 v[100:103], v[156:159], v[238:241], v[100:103]
	v_mfma_f32_16x16x32_bf16 v[68:71], v[156:159], v[246:249], v[68:71]
	v_mfma_f32_16x16x32_bf16 v[64:67], v[182:185], v[246:249], v[64:67]
	v_mfma_f32_16x16x32_bf16 v[96:99], v[182:185], v[238:241], v[96:99]
	v_mfma_f32_16x16x32_bf16 v[112:115], v[182:185], v[206:209], v[112:115]
	v_mfma_f32_16x16x32_bf16 v[128:131], v[182:185], v[198:201], v[128:131]
	s_barrier
; #define PG8_STAGE(bufoff, gbase, voff) do { _Pragma("unroll") for (int _i = 0; _i < 2; ++_i) \
;         __builtin_amdgcn_global_load_lds((const unsigned*)((const char*)(gbase) + (voff)[_i]), (LAS unsigned*)(lds + (bufoff) + ldsw + _i * 8192), 16, 0, 0); } while (0)
; #define PG8_LDA(dst, b, h) do { _Pragma("unroll") for (int m = 0; m < 4; ++m) _Pragma("unroll") for (int k = 0; k < 2; ++k) dst[m][k] = *(const LAS bf16x8*)(lds + PG8_SA(b, h) + aoff + m * 2048 + k * 1024); } while (0)
; #define PG8_MMA(ai, bj, At, Bt) do { __builtin_amdgcn_s_setprio(1); _Pragma("unroll") for (int m = 0; m < 4; ++m) _Pragma("unroll") for (int n = 0; n < 2; ++n) _Pragma("unroll") for (int k = 0; k < 2; ++k) \
;         acc[ai][bj][m][n] = __builtin_amdgcn_mfma_f32_16x16x32_bf16(Bt[n][k], At[m][k], acc[ai][bj][m][n], 0, 0, 0); __builtin_amdgcn_s_setprio(0); } while (0)
; #define PG8_WAIT_V(n) asm volatile("s_waitcnt vmcnt(" #n ")" ::: "memory")
; #define PG8_WAIT_L(n) asm volatile("s_waitcnt lgkmcnt(" #n ")" ::: "memory")
; #define PG8_BAR __builtin_amdgcn_s_barrier()
; #define PG8_SCHED __builtin_amdgcn_sched_barrier(0)
; template <class Epi, class Sched>
; __device__ __forceinline__ void gemm_phase(LAS unsigned char* lds, const Gemm g, const Sched& S, const Epi& E, const int tid) {
;     ...
;             PG8_LDA(At, 1, 1); PG8_STAGE(PG8_SB(1, 0), b3, voffB); PG8_STAGE(PG8_SB(1, 1), b3 + hstep, voffB); PG8_STAGE(PG8_SA(1, 0), a3, voffA);
;             PG8_WAIT_V(8); PG8_WAIT_L(0); PG8_BAR; PG8_MMA(1, 0, At, B0); PG8_MMA(1, 1, At, B1); PG8_BAR; PG8_SCHED;
;         }
;         if (wr == 0) PG8_BAR;
	s_add_i32 s61, s61, s12
	v_lshl_add_u64 v[82:83], v[190:191], 0, s[68:69]
	s_mov_b32 m0, s61
	ds_read_b128 v[186:189], v230 offset:49152
	ds_read_b128 v[198:201], v230 offset:50176
	ds_read_b128 v[202:205], v230 offset:51200
	ds_read_b128 v[206:209], v230 offset:52224
	ds_read_b128 v[234:237], v230 offset:53248
	ds_read_b128 v[238:241], v230 offset:54272
	ds_read_b128 v[242:245], v230 offset:55296
	ds_read_b128 v[246:249], v230 offset:56320
	global_load_lds_dwordx4 v[82:83], off
	s_add_i32 m0, s61, 0x2000
	s_add_u32 s64, s64, 0x40080
	v_lshl_add_u64 v[82:83], v[250:251], 0, s[68:69]
	s_addc_u32 s65, s65, 0
	s_add_i32 s61, s70, s12
	global_load_lds_dwordx4 v[82:83], off
	v_lshl_add_u64 v[82:83], s[64:65], 0, v[164:165]
	s_mov_b32 m0, s61
	s_nop 0
	global_load_lds_dwordx4 v[82:83], off
	v_lshl_add_u64 v[82:83], s[64:65], 0, v[168:169]
	s_add_i32 m0, s61, 0x2000
	s_nop 0
	global_load_lds_dwordx4 v[82:83], off
	v_lshl_add_u64 v[82:83], v[224:225], 0, s[68:69]
	s_mov_b32 m0, s82
	s_nop 0
	global_load_lds_dwordx4 v[82:83], off
	v_lshl_add_u64 v[82:83], v[226:227], 0, s[68:69]
	s_mov_b32 m0, s83
	s_nop 0
	global_load_lds_dwordx4 v[82:83], off
	s_waitcnt vmcnt(8)
	s_waitcnt lgkmcnt(0)
	s_barrier
	s_waitcnt lgkmcnt(0)
	v_mfma_f32_16x16x32_bf16 v[60:63], v[88:91], v[186:189], v[60:63]
	v_mfma_f32_16x16x32_bf16 v[44:47], v[88:91], v[202:205], v[44:47]
	v_mfma_f32_16x16x32_bf16 v[28:31], v[88:91], v[234:237], v[28:31]
	v_mfma_f32_16x16x32_bf16 v[12:15], v[88:91], v[242:245], v[12:15]
	v_mfma_f32_16x16x32_bf16 v[8:11], v[144:147], v[242:245], v[8:11]
	v_mfma_f32_16x16x32_bf16 v[24:27], v[144:147], v[234:237], v[24:27]
	v_mfma_f32_16x16x32_bf16 v[40:43], v[144:147], v[202:205], v[40:43]
	v_mfma_f32_16x16x32_bf16 v[56:59], v[144:147], v[186:189], v[56:59]
	v_mfma_f32_16x16x32_bf16 v[60:63], v[92:95], v[198:201], v[60:63]
	v_mfma_f32_16x16x32_bf16 v[44:47], v[92:95], v[206:209], v[44:47]
	v_mfma_f32_16x16x32_bf16 v[28:31], v[92:95], v[238:241], v[28:31]
	v_mfma_f32_16x16x32_bf16 v[12:15], v[92:95], v[246:249], v[12:15]
	v_mfma_f32_16x16x32_bf16 v[8:11], v[148:151], v[246:249], v[8:11]
	v_mfma_f32_16x16x32_bf16 v[24:27], v[148:151], v[238:241], v[24:27]
	v_mfma_f32_16x16x32_bf16 v[40:43], v[148:151], v[206:209], v[40:43]
	v_mfma_f32_16x16x32_bf16 v[56:59], v[148:151], v[198:201], v[56:59]
	v_mfma_f32_16x16x32_bf16 v[52:55], v[152:155], v[186:189], v[52:55]
	v_mfma_f32_16x16x32_bf16 v[36:39], v[152:155], v[202:205], v[36:39]
	v_mfma_f32_16x16x32_bf16 v[20:23], v[152:155], v[234:237], v[20:23]
	v_mfma_f32_16x16x32_bf16 v[4:7], v[152:155], v[242:245], v[4:7]
	v_mfma_f32_16x16x32_bf16 v[0:3], v[178:181], v[242:245], v[0:3]
	v_mfma_f32_16x16x32_bf16 v[16:19], v[178:181], v[234:237], v[16:19]
	v_mfma_f32_16x16x32_bf16 v[32:35], v[178:181], v[202:205], v[32:35]
	v_mfma_f32_16x16x32_bf16 v[48:51], v[178:181], v[186:189], v[48:51]
	v_mfma_f32_16x16x32_bf16 v[52:55], v[156:159], v[198:201], v[52:55]
	v_mfma_f32_16x16x32_bf16 v[36:39], v[156:159], v[206:209], v[36:39]
	v_mfma_f32_16x16x32_bf16 v[20:23], v[156:159], v[238:241], v[20:23]
	v_mfma_f32_16x16x32_bf16 v[4:7], v[156:159], v[246:249], v[4:7]
	v_mfma_f32_16x16x32_bf16 v[0:3], v[182:185], v[246:249], v[0:3]
	v_mfma_f32_16x16x32_bf16 v[16:19], v[182:185], v[238:241], v[16:19]
	v_mfma_f32_16x16x32_bf16 v[32:35], v[182:185], v[206:209], v[32:35]
	v_mfma_f32_16x16x32_bf16 v[48:51], v[182:185], v[198:201], v[48:51]
	s_barrier
	s_add_i32 s60, s60, 2
	s_add_u32 s6, s6, 0x100
	s_addc_u32 s7, s7, 0
	s_add_u32 s58, s58, 0x100
	s_addc_u32 s59, s59, 0
	s_cmp_gt_u32 s60, 13
	s_cbranch_scc0 .LBB0_266
	s_and_b64 vcc, exec, s[50:51]
	s_cbranch_vccz .LBB0_269
	s_barrier

;     __device__ __forceinline__ Pre prefetch(const Unit& u, int tid) const { return prenorm_load(stats, u.pn * BM, sW + (size_t)(u.pn >> 4) * SW_ROWS + u.pm * BM, tid); }
;     __device__ __forceinline__ Pre prefetch(const Unit& u, int tid) const { return prenorm_load(stats, u.pm * BM, sW + (size_t)(u.pm >> 4) * SW_ROWS + u.pn * BM, tid); }
;     __device__ __forceinline__ Pre prefetch(const Unit& u, int tid) const { return prenorm_load(stats, u.pm * BM, sW + (size_t)(u.pm >> 4) * SW_ROWS + u.pn * BM, tid); }
; #define PG8_STAGE(bufoff, gbase, voff) do { _Pragma("unroll") for (int _i = 0; _i < 2; ++_i) \
;         __builtin_amdgcn_global_load_lds((const unsigned*)((const char*)(gbase) + (voff)[_i]), (LAS unsigned*)(lds + (bufoff) + ldsw + _i * 8192), 16, 0, 0); } while (0)
; #define PG8_LDA(dst, b, h) do { _Pragma("unroll") for (int m = 0; m < 4; ++m) _Pragma("unroll") for (int k = 0; k < 2; ++k) dst[m][k] = *(const LAS bf16x8*)(lds + PG8_SA(b, h) + aoff + m * 2048 + k * 1024); } while (0)
; #define PG8_LDB(dst, b, h) do { _Pragma("unroll") for (int n = 0; n < 2; ++n) _Pragma("unroll") for (int k = 0; k < 2; ++k) dst[n][k] = *(const LAS bf16x8*)(lds + PG8_SB(b, h) + boff + n * 2048 + k * 1024); } while (0)
; template <class Epi, class Sched>
; __device__ __forceinline__ void gemm_phase(LAS unsigned char* lds, const Gemm g, const Sched& S, const Epi& E, const int tid) {
;     ...
;         const char* nA = has_next ? (const char*)g.A + (size_t)nxt.pm * tstep : cA; const char* nB = has_next ? (const char*)g.Bt + (size_t)nxt.pn * tstep : cB;
;         const typename Epi::Pre pre = E.prefetch(cur, tid);
;         for (int t = 0; t < nt; t += 2) {
;             const bool last = (t == nt - 2);
;             const char* a1 = cA + (size_t)(t + 1) * kstep;
;             const char* a2 = last ? nA : cA + (size_t)(t + 2) * kstep; const char* b2 = last ? nB : cB + (size_t)(t + 2) * kstep;
;             const char* a3 = a2 + kstep; const char* b3 = b2 + kstep;
;             PG8_LDB(B0, 0, 0); PG8_LDB(B1, 0, 1); PG8_SCHED; PG8_LDA(At, 0, 0); PG8_STAGE(PG8_SA(1, 1), a1 + hstep, voffA);
;             PG8_WAIT_V(8); PG8_WAIT_L(0); PG8_BAR; PG8_MMA(0, 0, At, B0); PG8_MMA(0, 1, At, B1); PG8_BAR; PG8_SCHED;
;             PG8_LDA(At, 0, 1); PG8_STAGE(PG8_SB(0, 0), b2, voffB); PG8_STAGE(PG8_SB(0, 1), b2 + hstep, voffB); PG8_STAGE(PG8_SA(0, 0), a2, voffA);
.LBB0_325:
	s_or_b64 exec, exec, s[50:51]
	s_ashr_i32 s39, s38, 31
	s_lshl_b64 s[50:51], s[38:39], 19
	s_add_u32 s50, s85, s50
	s_addc_u32 s51, s86, s51
	s_and_b64 s[54:55], s[4:5], exec
	s_cselect_b32 s39, s51, s63
	s_cselect_b32 s74, s50, s62
	s_ashr_i32 s23, s22, 31
	s_lshl_b64 s[54:55], s[22:23], 19
	s_add_u32 s54, s46, s54
	s_addc_u32 s55, s47, s55
	s_and_b64 s[66:67], s[4:5], exec
	s_cselect_b32 s23, s55, s65
	s_cselect_b32 s75, s54, s64
	s_add_u32 s62, s62, 0x40080
	s_addc_u32 s63, s63, 0
	s_add_u32 s78, s64, 0x100
	s_addc_u32 s79, s65, 0
	s_mov_b32 s81, -2
	s_waitcnt lgkmcnt(0)
	s_add_u32 s64, s62, 0xfffc0080
	s_addc_u32 s65, s63, -1
	s_add_i32 s82, 0, 0x10000
	s_cmp_eq_u32 s81, 12
	s_cselect_b32 s67, s39, s65
	s_cselect_b32 s66, s74, s64
	v_add_u32_e32 v69, s82, v154
	s_cselect_b32 s65, s23, s79
	s_cselect_b32 s64, s75, s78
	s_add_i32 s90, 0, 0x14000
	ds_read_b128 v[70:73], v69
	ds_read_b128 v[74:77], v69 offset:1024
	ds_read_b128 v[172:175], v69 offset:2048
	ds_read_b128 v[176:179], v69 offset:3072
	v_add_u32_e32 v69, s90, v154
	ds_read_b128 v[180:183], v69
	ds_read_b128 v[184:187], v69 offset:1024
	ds_read_b128 v[188:191], v69 offset:2048
	ds_read_b128 v[198:201], v69 offset:3072
	v_lshl_add_u64 v[78:79], s[62:63], 0, v[144:145]
	s_add_i32 m0, s53, 0xc000
	ds_read_b128 v[202:205], v171
	ds_read_b128 v[206:209], v171 offset:1024
	ds_read_b128 v[210:213], v171 offset:2048
	ds_read_b128 v[214:217], v171 offset:3072
	ds_read_b128 v[218:221], v171 offset:4096
	ds_read_b128 v[230:233], v171 offset:5120
	ds_read_b128 v[234:237], v171 offset:6144
	ds_read_b128 v[238:241], v171 offset:7168
	global_load_lds_dwordx4 v[78:79], off
	v_lshl_add_u64 v[78:79], s[62:63], 0, v[146:147]
	s_add_i32 m0, s53, 0xe000
	s_nop 0
	global_load_lds_dwordx4 v[78:79], off
	s_waitcnt vmcnt(8)
	s_waitcnt lgkmcnt(0)
	s_barrier
	s_waitcnt lgkmcnt(0)
	v_mfma_f32_16x16x32_bf16 v[140:143], v[70:73], v[202:205], 0
	v_mfma_f32_16x16x32_bf16 v[132:135], v[70:73], v[210:213], 0
	v_mfma_f32_16x16x32_bf16 v[116:119], v[70:73], v[218:221], 0
	v_mfma_f32_16x16x32_bf16 v[100:103], v[70:73], v[234:237], 0
	v_mfma_f32_16x16x32_bf16 v[96:99], v[172:175], v[234:237], 0
	v_mfma_f32_16x16x32_bf16 v[112:115], v[172:175], v[218:221], 0
	v_mfma_f32_16x16x32_bf16 v[128:131], v[172:175], v[210:213], 0
	v_mfma_f32_16x16x32_bf16 v[136:139], v[172:175], v[202:205], 0
	v_mfma_f32_16x16x32_bf16 v[140:143], v[74:77], v[206:209], v[140:143]
	v_mfma_f32_16x16x32_bf16 v[132:135], v[74:77], v[214:217], v[132:135]
	v_mfma_f32_16x16x32_bf16 v[116:119], v[74:77], v[230:233], v[116:119]
	v_mfma_f32_16x16x32_bf16 v[100:103], v[74:77], v[238:241], v[100:103]
	v_mfma_f32_16x16x32_bf16 v[96:99], v[176:179], v[238:241], v[96:99]
	v_mfma_f32_16x16x32_bf16 v[112:115], v[176:179], v[230:233], v[112:115]
	v_mfma_f32_16x16x32_bf16 v[128:131], v[176:179], v[214:217], v[128:131]
	v_mfma_f32_16x16x32_bf16 v[136:139], v[176:179], v[206:209], v[136:139]
	v_mfma_f32_16x16x32_bf16 v[124:127], v[180:183], v[202:205], 0
	v_mfma_f32_16x16x32_bf16 v[108:111], v[180:183], v[210:213], 0
	v_mfma_f32_16x16x32_bf16 v[92:95], v[180:183], v[218:221], 0
	v_mfma_f32_16x16x32_bf16 v[84:87], v[180:183], v[234:237], 0
	v_mfma_f32_16x16x32_bf16 v[78:81], v[188:191], v[234:237], 0
	v_mfma_f32_16x16x32_bf16 v[88:91], v[188:191], v[218:221], 0
	v_mfma_f32_16x16x32_bf16 v[104:107], v[188:191], v[210:213], 0
	v_mfma_f32_16x16x32_bf16 v[120:123], v[188:191], v[202:205], 0
	v_mfma_f32_16x16x32_bf16 v[124:127], v[184:187], v[206:209], v[124:127]
	v_mfma_f32_16x16x32_bf16 v[108:111], v[184:187], v[214:217], v[108:111]
	v_mfma_f32_16x16x32_bf16 v[92:95], v[184:187], v[230:233], v[92:95]
	v_mfma_f32_16x16x32_bf16 v[84:87], v[184:187], v[238:241], v[84:87]
	v_mfma_f32_16x16x32_bf16 v[78:81], v[198:201], v[238:241], v[78:81]
	v_mfma_f32_16x16x32_bf16 v[88:91], v[198:201], v[230:233], v[88:91]
	v_mfma_f32_16x16x32_bf16 v[104:107], v[198:201], v[214:217], v[104:107]
	v_mfma_f32_16x16x32_bf16 v[120:123], v[198:201], v[206:209], v[120:123]
	s_barrier
	s_add_i32 s82, s82, s52
	v_lshl_add_u64 v[224:225], s[64:65], 0, v[164:165]
	s_mov_b32 m0, s82
	ds_read_b128 v[202:205], v171 offset:16384
	ds_read_b128 v[206:209], v171 offset:17408
	ds_read_b128 v[210:213], v171 offset:18432
	ds_read_b128 v[214:217], v171 offset:19456
	ds_read_b128 v[218:221], v171 offset:20480
	ds_read_b128 v[230:233], v171 offset:21504
	ds_read_b128 v[234:237], v171 offset:22528
	ds_read_b128 v[238:241], v171 offset:23552
	global_load_lds_dwordx4 v[224:225], off
	s_add_i32 m0, s82, 0x2000
	s_add_u32 s82, s64, 0x40000
	v_lshl_add_u64 v[226:227], s[64:65], 0, v[168:169]
	s_addc_u32 s83, s65, 0
	s_add_i32 s90, s90, s52
	global_load_lds_dwordx4 v[226:227], off
	v_lshl_add_u64 v[82:83], s[82:83], 0, v[164:165]
	s_mov_b32 m0, s90
	v_lshl_add_u64 v[242:243], s[66:67], 0, v[162:163]
	global_load_lds_dwordx4 v[82:83], off
	v_lshl_add_u64 v[82:83], s[82:83], 0, v[168:169]
	s_add_i32 m0, s90, 0x2000
	v_lshl_add_u64 v[244:245], s[66:67], 0, v[166:167]
	global_load_lds_dwordx4 v[82:83], off
	s_mov_b32 m0, s53
	s_nop 0
	global_load_lds_dwordx4 v[242:243], off
	s_mov_b32 m0, s56
	s_nop 0
	global_load_lds_dwordx4 v[244:245], off
	s_waitcnt vmcnt(8)
	s_waitcnt lgkmcnt(0)
	s_barrier
; #define PG8_STAGE(bufoff, gbase, voff) do { _Pragma("unroll") for (int _i = 0; _i < 2; ++_i) \
;         __builtin_amdgcn_global_load_lds((const unsigned*)((const char*)(gbase) + (voff)[_i]), (LAS unsigned*)(lds + (bufoff) + ldsw + _i * 8192), 16, 0, 0); } while (0)
; #define PG8_LDA(dst, b, h) do { _Pragma("unroll") for (int m = 0; m < 4; ++m) _Pragma("unroll") for (int k = 0; k < 2; ++k) dst[m][k] = *(const LAS bf16x8*)(lds + PG8_SA(b, h) + aoff + m * 2048 + k * 1024); } while (0)
; #define PG8_LDB(dst, b, h) do { _Pragma("unroll") for (int n = 0; n < 2; ++n) _Pragma("unroll") for (int k = 0; k < 2; ++k) dst[n][k] = *(const LAS bf16x8*)(lds + PG8_SB(b, h) + boff + n * 2048 + k * 1024); } while (0)
; #define PG8_MMA(ai, bj, At, Bt) do { __builtin_amdgcn_s_setprio(1); _Pragma("unroll") for (int m = 0; m < 4; ++m) _Pragma("unroll") for (int n = 0; n < 2; ++n) _Pragma("unroll") for (int k = 0; k < 2; ++k) \
;         acc[ai][bj][m][n] = __builtin_amdgcn_mfma_f32_16x16x32_bf16(Bt[n][k], At[m][k], acc[ai][bj][m][n], 0, 0, 0); __builtin_amdgcn_s_setprio(0); } while (0)
; #define PG8_WAIT_V(n) asm volatile("s_waitcnt vmcnt(" #n ")" ::: "memory")
; #define PG8_WAIT_L(n) asm volatile("s_waitcnt lgkmcnt(" #n ")" ::: "memory")
; #define PG8_BAR __builtin_amdgcn_s_barrier()
; #define PG8_SCHED __builtin_amdgcn_sched_barrier(0)
; template <class Epi, class Sched>
; __device__ __forceinline__ void gemm_phase(LAS unsigned char* lds, const Gemm g, const Sched& S, const Epi& E, const int tid) {
;     ...
;             PG8_WAIT_V(8); PG8_WAIT_L(0); PG8_BAR; PG8_MMA(1, 0, At, B0); PG8_MMA(1, 1, At, B1); PG8_BAR; PG8_SCHED;
;             PG8_LDB(B0, 1, 0); PG8_LDB(B1, 1, 1); PG8_SCHED; PG8_LDA(At, 1, 0); PG8_STAGE(PG8_SA(0, 1), a2 + hstep, voffA);
;             PG8_WAIT_V(8); PG8_WAIT_L(0); PG8_BAR; PG8_MMA(0, 0, At, B0); PG8_MMA(0, 1, At, B1); PG8_BAR; PG8_SCHED;
	s_waitcnt lgkmcnt(0)
	v_mfma_f32_16x16x32_bf16 v[60:63], v[70:73], v[202:205], 0
	v_mfma_f32_16x16x32_bf16 v[52:55], v[70:73], v[210:213], 0
	v_mfma_f32_16x16x32_bf16 v[28:31], v[70:73], v[218:221], 0
	v_mfma_f32_16x16x32_bf16 v[16:19], v[70:73], v[234:237], 0
	v_mfma_f32_16x16x32_bf16 v[8:11], v[172:175], v[234:237], 0
	v_mfma_f32_16x16x32_bf16 v[24:27], v[172:175], v[218:221], 0
	v_mfma_f32_16x16x32_bf16 v[44:47], v[172:175], v[210:213], 0
	v_mfma_f32_16x16x32_bf16 v[56:59], v[172:175], v[202:205], 0
	v_mfma_f32_16x16x32_bf16 v[60:63], v[74:77], v[206:209], v[60:63]
	v_mfma_f32_16x16x32_bf16 v[52:55], v[74:77], v[214:217], v[52:55]
	v_mfma_f32_16x16x32_bf16 v[28:31], v[74:77], v[230:233], v[28:31]
	v_mfma_f32_16x16x32_bf16 v[16:19], v[74:77], v[238:241], v[16:19]
	v_mfma_f32_16x16x32_bf16 v[8:11], v[176:179], v[238:241], v[8:11]
	v_mfma_f32_16x16x32_bf16 v[24:27], v[176:179], v[230:233], v[24:27]
	v_mfma_f32_16x16x32_bf16 v[44:47], v[176:179], v[214:217], v[44:47]
	v_mfma_f32_16x16x32_bf16 v[56:59], v[176:179], v[206:209], v[56:59]
	v_mfma_f32_16x16x32_bf16 v[48:51], v[180:183], v[202:205], 0
	v_mfma_f32_16x16x32_bf16 v[36:39], v[180:183], v[210:213], 0
	v_mfma_f32_16x16x32_bf16 v[20:23], v[180:183], v[218:221], 0
	v_mfma_f32_16x16x32_bf16 v[4:7], v[180:183], v[234:237], 0
	v_mfma_f32_16x16x32_bf16 v[0:3], v[188:191], v[234:237], 0
	v_mfma_f32_16x16x32_bf16 v[12:15], v[188:191], v[218:221], 0
	v_mfma_f32_16x16x32_bf16 v[32:35], v[188:191], v[210:213], 0
	v_mfma_f32_16x16x32_bf16 v[40:43], v[188:191], v[202:205], 0
	v_mfma_f32_16x16x32_bf16 v[48:51], v[184:187], v[206:209], v[48:51]
	v_mfma_f32_16x16x32_bf16 v[36:39], v[184:187], v[214:217], v[36:39]
	v_mfma_f32_16x16x32_bf16 v[20:23], v[184:187], v[230:233], v[20:23]
	v_mfma_f32_16x16x32_bf16 v[4:7], v[184:187], v[238:241], v[4:7]
	v_mfma_f32_16x16x32_bf16 v[0:3], v[198:201], v[238:241], v[0:3]
	v_mfma_f32_16x16x32_bf16 v[12:15], v[198:201], v[230:233], v[12:15]
	v_mfma_f32_16x16x32_bf16 v[32:35], v[198:201], v[214:217], v[32:35]
	v_mfma_f32_16x16x32_bf16 v[40:43], v[198:201], v[206:209], v[40:43]
	s_barrier
	s_add_i32 s82, 0, 0x18000
	v_add_u32_e32 v69, s82, v154
	s_add_i32 s83, 0, 0x1c000
	ds_read_b128 v[70:73], v69
	ds_read_b128 v[74:77], v69 offset:1024
	ds_read_b128 v[172:175], v69 offset:2048
	ds_read_b128 v[176:179], v69 offset:3072
	v_add_u32_e32 v69, s83, v154
	ds_read_b128 v[180:183], v69
	ds_read_b128 v[184:187], v69 offset:1024
	ds_read_b128 v[188:191], v69 offset:2048
	ds_read_b128 v[198:201], v69 offset:3072
	s_add_u32 s66, s66, 0x40000
	s_addc_u32 s67, s67, 0
	s_mov_b32 m0, s57
	v_lshl_add_u64 v[82:83], s[66:67], 0, v[162:163]
	ds_read_b128 v[202:205], v171 offset:32768
	ds_read_b128 v[206:209], v171 offset:33792
	ds_read_b128 v[210:213], v171 offset:34816
	ds_read_b128 v[214:217], v171 offset:35840
	ds_read_b128 v[218:221], v171 offset:36864
	ds_read_b128 v[230:233], v171 offset:37888
	ds_read_b128 v[234:237], v171 offset:38912
	ds_read_b128 v[238:241], v171 offset:39936
	global_load_lds_dwordx4 v[82:83], off
	v_lshl_add_u64 v[82:83], s[66:67], 0, v[166:167]
	s_mov_b32 m0, s58
	s_nop 0
	global_load_lds_dwordx4 v[82:83], off
	s_waitcnt vmcnt(8)
	s_waitcnt lgkmcnt(0)
	s_barrier
	s_waitcnt lgkmcnt(0)
	v_mfma_f32_16x16x32_bf16 v[140:143], v[70:73], v[202:205], v[140:143]
	v_mfma_f32_16x16x32_bf16 v[132:135], v[70:73], v[210:213], v[132:135]
	v_mfma_f32_16x16x32_bf16 v[116:119], v[70:73], v[218:221], v[116:119]
	v_mfma_f32_16x16x32_bf16 v[100:103], v[70:73], v[234:237], v[100:103]
	v_mfma_f32_16x16x32_bf16 v[96:99], v[172:175], v[234:237], v[96:99]
	v_mfma_f32_16x16x32_bf16 v[112:115], v[172:175], v[218:221], v[112:115]
	v_mfma_f32_16x16x32_bf16 v[128:131], v[172:175], v[210:213], v[128:131]
	v_mfma_f32_16x16x32_bf16 v[136:139], v[172:175], v[202:205], v[136:139]
	v_mfma_f32_16x16x32_bf16 v[140:143], v[74:77], v[206:209], v[140:143]
	v_mfma_f32_16x16x32_bf16 v[132:135], v[74:77], v[214:217], v[132:135]
	v_mfma_f32_16x16x32_bf16 v[116:119], v[74:77], v[230:233], v[116:119]
	v_mfma_f32_16x16x32_bf16 v[100:103], v[74:77], v[238:241], v[100:103]
	v_mfma_f32_16x16x32_bf16 v[96:99], v[176:179], v[238:241], v[96:99]
	v_mfma_f32_16x16x32_bf16 v[112:115], v[176:179], v[230:233], v[112:115]
	v_mfma_f32_16x16x32_bf16 v[128:131], v[176:179], v[214:217], v[128:131]
	v_mfma_f32_16x16x32_bf16 v[136:139], v[176:179], v[206:209], v[136:139]
	v_mfma_f32_16x16x32_bf16 v[124:127], v[180:183], v[202:205], v[124:127]
	v_mfma_f32_16x16x32_bf16 v[108:111], v[180:183], v[210:213], v[108:111]
	v_mfma_f32_16x16x32_bf16 v[92:95], v[180:183], v[218:221], v[92:95]
	v_mfma_f32_16x16x32_bf16 v[82:85], v[180:183], v[234:237], v[84:87]
	v_mfma_f32_16x16x32_bf16 v[78:81], v[188:191], v[234:237], v[78:81]
	v_mfma_f32_16x16x32_bf16 v[88:91], v[188:191], v[218:221], v[88:91]
	v_mfma_f32_16x16x32_bf16 v[104:107], v[188:191], v[210:213], v[104:107]
	v_mfma_f32_16x16x32_bf16 v[120:123], v[188:191], v[202:205], v[120:123]
	v_mfma_f32_16x16x32_bf16 v[124:127], v[184:187], v[206:209], v[124:127]
	v_mfma_f32_16x16x32_bf16 v[108:111], v[184:187], v[214:217], v[108:111]
	v_mfma_f32_16x16x32_bf16 v[92:95], v[184:187], v[230:233], v[92:95]
	v_mfma_f32_16x16x32_bf16 v[84:87], v[184:187], v[238:241], v[82:85]
	v_mfma_f32_16x16x32_bf16 v[80:83], v[198:201], v[238:241], v[78:81]
	v_mfma_f32_16x16x32_bf16 v[88:91], v[198:201], v[230:233], v[88:91]
	v_mfma_f32_16x16x32_bf16 v[104:107], v[198:201], v[214:217], v[104:107]
	v_mfma_f32_16x16x32_bf16 v[120:123], v[198:201], v[206:209], v[120:123]
	s_barrier
; #define PG8_STAGE(bufoff, gbase, voff) do { _Pragma("unroll") for (int _i = 0; _i < 2; ++_i) \
;         __builtin_amdgcn_global_load_lds((const unsigned*)((const char*)(gbase) + (voff)[_i]), (LAS unsigned*)(lds + (bufoff) + ldsw + _i * 8192), 16, 0, 0); } while (0)
; #define PG8_LDA(dst, b, h) do { _Pragma("unroll") for (int m = 0; m < 4; ++m) _Pragma("unroll") for (int k = 0; k < 2; ++k) dst[m][k] = *(const LAS bf16x8*)(lds + PG8_SA(b, h) + aoff + m * 2048 + k * 1024); } while (0)
; #define PG8_LDB(dst, b, h) do { _Pragma("unroll") for (int n = 0; n < 2; ++n) _Pragma("unroll") for (int k = 0; k < 2; ++k) dst[n][k] = *(const LAS bf16x8*)(lds + PG8_SB(b, h) + boff + n * 2048 + k * 1024); } while (0)
; #define PG8_MMA(ai, bj, At, Bt) do { __builtin_amdgcn_s_setprio(1); _Pragma("unroll") for (int m = 0; m < 4; ++m) _Pragma("unroll") for (int n = 0; n < 2; ++n) _Pragma("unroll") for (int k = 0; k < 2; ++k) \
;         acc[ai][bj][m][n] = __builtin_amdgcn_mfma_f32_16x16x32_bf16(Bt[n][k], At[m][k], acc[ai][bj][m][n], 0, 0, 0); __builtin_amdgcn_s_setprio(0); } while (0)
; #define PG8_WAIT_V(n) asm volatile("s_waitcnt vmcnt(" #n ")" ::: "memory")
; #define PG8_BAR __builtin_amdgcn_s_barrier()
; template <class Epi, class Sched>
; __device__ __forceinline__ void gemm_phase(LAS unsigned char* lds, const Gemm g, const Sched& S, const Epi& E, const int tid) {
;     ...
;             PG8_LDB(B0, 0, 0); PG8_LDB(B1, 0, 1); PG8_SCHED; PG8_LDA(At, 0, 0); PG8_STAGE(PG8_SA(1, 1), a1 + hstep, voffA);
;             PG8_WAIT_V(8); PG8_WAIT_L(0); PG8_BAR; PG8_MMA(0, 0, At, B0); PG8_MMA(0, 1, At, B1); PG8_BAR; PG8_SCHED;
;             PG8_LDA(At, 0, 1); PG8_STAGE(PG8_SB(0, 0), b2, voffB); PG8_STAGE(PG8_SB(0, 1), b2 + hstep, voffB); PG8_STAGE(PG8_SA(0, 0), a2, voffA);
;             PG8_WAIT_V(8); PG8_WAIT_L(0); PG8_BAR; PG8_MMA(1, 0, At, B0); PG8_MMA(1, 1, At, B1); PG8_BAR; PG8_SCHED;
;             PG8_LDB(B0, 1, 0); PG8_LDB(B1, 1, 1); PG8_SCHED; PG8_LDA(At, 1, 0); PG8_STAGE(PG8_SA(0, 1), a2 + hstep, voffA);
;             PG8_WAIT_V(8); PG8_WAIT_L(0); PG8_BAR; PG8_MMA(0, 0, At, B0); PG8_MMA(0, 1, At, B1); PG8_BAR; PG8_SCHED;
;             PG8_LDA(At, 1, 1); PG8_STAGE(PG8_SB(1, 0), b3, voffB); PG8_STAGE(PG8_SB(1, 1), b3 + hstep, voffB); PG8_STAGE(PG8_SA(1, 0), a3, voffA);
;             PG8_WAIT_V(8); PG8_WAIT_L(0); PG8_BAR; PG8_MMA(1, 0, At, B0); PG8_MMA(1, 1, At, B1); PG8_BAR; PG8_SCHED;
	s_add_i32 s66, s82, s52
	v_lshl_add_u64 v[78:79], v[224:225], 0, s[68:69]
	s_mov_b32 m0, s66
	ds_read_b128 v[202:205], v171 offset:49152
	ds_read_b128 v[206:209], v171 offset:50176
	ds_read_b128 v[210:213], v171 offset:51200
	ds_read_b128 v[214:217], v171 offset:52224
	ds_read_b128 v[218:221], v171 offset:53248
	ds_read_b128 v[230:233], v171 offset:54272
	ds_read_b128 v[234:237], v171 offset:55296
	ds_read_b128 v[238:241], v171 offset:56320
	global_load_lds_dwordx4 v[78:79], off
	s_add_i32 m0, s66, 0x2000
	s_add_u32 s64, s64, 0x40080
	v_lshl_add_u64 v[78:79], v[226:227], 0, s[68:69]
	s_addc_u32 s65, s65, 0
	s_add_i32 s66, s83, s52
	global_load_lds_dwordx4 v[78:79], off
	v_lshl_add_u64 v[78:79], s[64:65], 0, v[164:165]
	s_mov_b32 m0, s66
	s_nop 0
	global_load_lds_dwordx4 v[78:79], off
	v_lshl_add_u64 v[78:79], s[64:65], 0, v[168:169]
	s_add_i32 m0, s66, 0x2000
	s_nop 0
	global_load_lds_dwordx4 v[78:79], off
	v_lshl_add_u64 v[78:79], v[242:243], 0, s[68:69]
	s_mov_b32 m0, s61
	s_nop 0
	global_load_lds_dwordx4 v[78:79], off
	v_lshl_add_u64 v[78:79], v[244:245], 0, s[68:69]
	s_mov_b32 m0, s70
	s_nop 0
	global_load_lds_dwordx4 v[78:79], off
	s_waitcnt vmcnt(8)
	s_waitcnt lgkmcnt(0)
	s_barrier
	s_waitcnt lgkmcnt(0)
	v_mfma_f32_16x16x32_bf16 v[60:63], v[70:73], v[202:205], v[60:63]
	v_mfma_f32_16x16x32_bf16 v[52:55], v[70:73], v[210:213], v[52:55]
	v_mfma_f32_16x16x32_bf16 v[28:31], v[70:73], v[218:221], v[28:31]
	v_mfma_f32_16x16x32_bf16 v[16:19], v[70:73], v[234:237], v[16:19]
	v_mfma_f32_16x16x32_bf16 v[8:11], v[172:175], v[234:237], v[8:11]
	v_mfma_f32_16x16x32_bf16 v[24:27], v[172:175], v[218:221], v[24:27]
	v_mfma_f32_16x16x32_bf16 v[44:47], v[172:175], v[210:213], v[44:47]
	v_mfma_f32_16x16x32_bf16 v[56:59], v[172:175], v[202:205], v[56:59]
	v_mfma_f32_16x16x32_bf16 v[60:63], v[74:77], v[206:209], v[60:63]
	v_mfma_f32_16x16x32_bf16 v[52:55], v[74:77], v[214:217], v[52:55]
	v_mfma_f32_16x16x32_bf16 v[28:31], v[74:77], v[230:233], v[28:31]
	v_mfma_f32_16x16x32_bf16 v[16:19], v[74:77], v[238:241], v[16:19]
	v_mfma_f32_16x16x32_bf16 v[8:11], v[176:179], v[238:241], v[8:11]
	v_mfma_f32_16x16x32_bf16 v[24:27], v[176:179], v[230:233], v[24:27]
	v_mfma_f32_16x16x32_bf16 v[44:47], v[176:179], v[214:217], v[44:47]
	v_mfma_f32_16x16x32_bf16 v[56:59], v[176:179], v[206:209], v[56:59]
	v_mfma_f32_16x16x32_bf16 v[48:51], v[180:183], v[202:205], v[48:51]
	v_mfma_f32_16x16x32_bf16 v[36:39], v[180:183], v[210:213], v[36:39]
	v_mfma_f32_16x16x32_bf16 v[20:23], v[180:183], v[218:221], v[20:23]
	v_mfma_f32_16x16x32_bf16 v[4:7], v[180:183], v[234:237], v[4:7]
	v_mfma_f32_16x16x32_bf16 v[0:3], v[188:191], v[234:237], v[0:3]
	v_mfma_f32_16x16x32_bf16 v[12:15], v[188:191], v[218:221], v[12:15]
	v_mfma_f32_16x16x32_bf16 v[32:35], v[188:191], v[210:213], v[32:35]
	v_mfma_f32_16x16x32_bf16 v[40:43], v[188:191], v[202:205], v[40:43]
	v_mfma_f32_16x16x32_bf16 v[48:51], v[184:187], v[206:209], v[48:51]
	v_mfma_f32_16x16x32_bf16 v[36:39], v[184:187], v[214:217], v[36:39]
	v_mfma_f32_16x16x32_bf16 v[20:23], v[184:187], v[230:233], v[20:23]
	v_mfma_f32_16x16x32_bf16 v[4:7], v[184:187], v[238:241], v[4:7]
	v_mfma_f32_16x16x32_bf16 v[0:3], v[198:201], v[238:241], v[0:3]
	v_mfma_f32_16x16x32_bf16 v[12:15], v[198:201], v[230:233], v[12:15]
	v_mfma_f32_16x16x32_bf16 v[32:35], v[198:201], v[214:217], v[32:35]
	v_mfma_f32_16x16x32_bf16 v[40:43], v[198:201], v[206:209], v[40:43]
	s_barrier
	s_add_i32 s81, s81, 2
	s_add_u32 s62, s62, 0x100
	s_addc_u32 s63, s63, 0
	s_add_u32 s78, s78, 0x100
	s_addc_u32 s79, s79, 0
	s_cmp_gt_u32 s81, 13
.LBB0_326:
	s_add_u32 s64, s62, 0xfffc0080
	s_addc_u32 s65, s63, -1
	s_add_i32 s82, 0, 0x10000
	s_cmp_eq_u32 s81, 12
	s_cselect_b32 s67, s39, s65
	s_cselect_b32 s66, s74, s64
	v_add_u32_e32 v69, s82, v154
	s_cselect_b32 s65, s23, s79
	s_cselect_b32 s64, s75, s78
	s_add_i32 s90, 0, 0x14000
	ds_read_b128 v[70:73], v69
	ds_read_b128 v[74:77], v69 offset:1024
	ds_read_b128 v[172:175], v69 offset:2048
	ds_read_b128 v[176:179], v69 offset:3072
	v_add_u32_e32 v69, s90, v154
	ds_read_b128 v[180:183], v69
	ds_read_b128 v[184:187], v69 offset:1024
	ds_read_b128 v[188:191], v69 offset:2048
	ds_read_b128 v[198:201], v69 offset:3072
	v_lshl_add_u64 v[78:79], s[62:63], 0, v[144:145]
	s_add_i32 m0, s53, 0xc000
	ds_read_b128 v[202:205], v171
	ds_read_b128 v[206:209], v171 offset:1024
	ds_read_b128 v[210:213], v171 offset:2048
	ds_read_b128 v[214:217], v171 offset:3072
	ds_read_b128 v[218:221], v171 offset:4096
	ds_read_b128 v[230:233], v171 offset:5120
	ds_read_b128 v[234:237], v171 offset:6144
	ds_read_b128 v[238:241], v171 offset:7168
	global_load_lds_dwordx4 v[78:79], off
	v_lshl_add_u64 v[78:79], s[62:63], 0, v[146:147]
	s_add_i32 m0, s53, 0xe000
	s_nop 0
	global_load_lds_dwordx4 v[78:79], off
	s_waitcnt vmcnt(8)
	s_waitcnt lgkmcnt(0)
	s_barrier
; #define PG8_STAGE(bufoff, gbase, voff) do { _Pragma("unroll") for (int _i = 0; _i < 2; ++_i) \
;         __builtin_amdgcn_global_load_lds((const unsigned*)((const char*)(gbase) + (voff)[_i]), (LAS unsigned*)(lds + (bufoff) + ldsw + _i * 8192), 16, 0, 0); } while (0)
; #define PG8_LDA(dst, b, h) do { _Pragma("unroll") for (int m = 0; m < 4; ++m) _Pragma("unroll") for (int k = 0; k < 2; ++k) dst[m][k] = *(const LAS bf16x8*)(lds + PG8_SA(b, h) + aoff + m * 2048 + k * 1024); } while (0)
; #define PG8_MMA(ai, bj, At, Bt) do { __builtin_amdgcn_s_setprio(1); _Pragma("unroll") for (int m = 0; m < 4; ++m) _Pragma("unroll") for (int n = 0; n < 2; ++n) _Pragma("unroll") for (int k = 0; k < 2; ++k) \
;         acc[ai][bj][m][n] = __builtin_amdgcn_mfma_f32_16x16x32_bf16(Bt[n][k], At[m][k], acc[ai][bj][m][n], 0, 0, 0); __builtin_amdgcn_s_setprio(0); } while (0)
; #define PG8_WAIT_V(n) asm volatile("s_waitcnt vmcnt(" #n ")" ::: "memory")
; #define PG8_WAIT_L(n) asm volatile("s_waitcnt lgkmcnt(" #n ")" ::: "memory")
; #define PG8_BAR __builtin_amdgcn_s_barrier()
; #define PG8_SCHED __builtin_amdgcn_sched_barrier(0)
; template <class Epi, class Sched>
; __device__ __forceinline__ void gemm_phase(LAS unsigned char* lds, const Gemm g, const Sched& S, const Epi& E, const int tid) {
;     ...
;             PG8_WAIT_V(8); PG8_WAIT_L(0); PG8_BAR; PG8_MMA(0, 0, At, B0); PG8_MMA(0, 1, At, B1); PG8_BAR; PG8_SCHED;
;             PG8_LDA(At, 0, 1); PG8_STAGE(PG8_SB(0, 0), b2, voffB); PG8_STAGE(PG8_SB(0, 1), b2 + hstep, voffB); PG8_STAGE(PG8_SA(0, 0), a2, voffA);
;             PG8_WAIT_V(8); PG8_WAIT_L(0); PG8_BAR; PG8_MMA(1, 0, At, B0); PG8_MMA(1, 1, At, B1); PG8_BAR; PG8_SCHED;
	s_waitcnt lgkmcnt(0)
	v_mfma_f32_16x16x32_bf16 v[140:143], v[70:73], v[202:205], v[140:143]
	v_mfma_f32_16x16x32_bf16 v[132:135], v[70:73], v[210:213], v[132:135]
	v_mfma_f32_16x16x32_bf16 v[116:119], v[70:73], v[218:221], v[116:119]
	v_mfma_f32_16x16x32_bf16 v[100:103], v[70:73], v[234:237], v[100:103]
	v_mfma_f32_16x16x32_bf16 v[96:99], v[172:175], v[234:237], v[96:99]
	v_mfma_f32_16x16x32_bf16 v[112:115], v[172:175], v[218:221], v[112:115]
	v_mfma_f32_16x16x32_bf16 v[128:131], v[172:175], v[210:213], v[128:131]
	v_mfma_f32_16x16x32_bf16 v[136:139], v[172:175], v[202:205], v[136:139]
	v_mfma_f32_16x16x32_bf16 v[140:143], v[74:77], v[206:209], v[140:143]
	v_mfma_f32_16x16x32_bf16 v[132:135], v[74:77], v[214:217], v[132:135]
	v_mfma_f32_16x16x32_bf16 v[116:119], v[74:77], v[230:233], v[116:119]
	v_mfma_f32_16x16x32_bf16 v[100:103], v[74:77], v[238:241], v[100:103]
	v_mfma_f32_16x16x32_bf16 v[96:99], v[176:179], v[238:241], v[96:99]
	v_mfma_f32_16x16x32_bf16 v[112:115], v[176:179], v[230:233], v[112:115]
	v_mfma_f32_16x16x32_bf16 v[128:131], v[176:179], v[214:217], v[128:131]
	v_mfma_f32_16x16x32_bf16 v[136:139], v[176:179], v[206:209], v[136:139]
	v_mfma_f32_16x16x32_bf16 v[124:127], v[180:183], v[202:205], v[124:127]
	v_mfma_f32_16x16x32_bf16 v[108:111], v[180:183], v[210:213], v[108:111]
	v_mfma_f32_16x16x32_bf16 v[92:95], v[180:183], v[218:221], v[92:95]
	v_mfma_f32_16x16x32_bf16 v[84:87], v[180:183], v[234:237], v[84:87]
	v_mfma_f32_16x16x32_bf16 v[78:81], v[188:191], v[234:237], v[80:83]
	v_mfma_f32_16x16x32_bf16 v[88:91], v[188:191], v[218:221], v[88:91]
	v_mfma_f32_16x16x32_bf16 v[104:107], v[188:191], v[210:213], v[104:107]
	v_mfma_f32_16x16x32_bf16 v[120:123], v[188:191], v[202:205], v[120:123]
	v_mfma_f32_16x16x32_bf16 v[124:127], v[184:187], v[206:209], v[124:127]
	v_mfma_f32_16x16x32_bf16 v[108:111], v[184:187], v[214:217], v[108:111]
	v_mfma_f32_16x16x32_bf16 v[92:95], v[184:187], v[230:233], v[92:95]
	v_mfma_f32_16x16x32_bf16 v[84:87], v[184:187], v[238:241], v[84:87]
	v_mfma_f32_16x16x32_bf16 v[78:81], v[198:201], v[238:241], v[78:81]
	v_mfma_f32_16x16x32_bf16 v[88:91], v[198:201], v[230:233], v[88:91]
	v_mfma_f32_16x16x32_bf16 v[104:107], v[198:201], v[214:217], v[104:107]
	v_mfma_f32_16x16x32_bf16 v[120:123], v[198:201], v[206:209], v[120:123]
	s_barrier
	s_add_i32 s82, s82, s52
	v_lshl_add_u64 v[224:225], s[64:65], 0, v[164:165]
	s_mov_b32 m0, s82
	ds_read_b128 v[202:205], v171 offset:16384
	ds_read_b128 v[206:209], v171 offset:17408
	ds_read_b128 v[210:213], v171 offset:18432
	ds_read_b128 v[214:217], v171 offset:19456
	ds_read_b128 v[218:221], v171 offset:20480
	ds_read_b128 v[230:233], v171 offset:21504
	ds_read_b128 v[234:237], v171 offset:22528
	ds_read_b128 v[238:241], v171 offset:23552
	global_load_lds_dwordx4 v[224:225], off
	s_add_i32 m0, s82, 0x2000
	s_add_u32 s82, s64, 0x40000
	v_lshl_add_u64 v[226:227], s[64:65], 0, v[168:169]
	s_addc_u32 s83, s65, 0
	s_add_i32 s90, s90, s52
	global_load_lds_dwordx4 v[226:227], off
	v_lshl_add_u64 v[82:83], s[82:83], 0, v[164:165]
	s_mov_b32 m0, s90
	v_lshl_add_u64 v[242:243], s[66:67], 0, v[162:163]
	global_load_lds_dwordx4 v[82:83], off
	v_lshl_add_u64 v[82:83], s[82:83], 0, v[168:169]
	s_add_i32 m0, s90, 0x2000
	v_lshl_add_u64 v[244:245], s[66:67], 0, v[166:167]
	global_load_lds_dwordx4 v[82:83], off
	s_mov_b32 m0, s53
	s_nop 0
	global_load_lds_dwordx4 v[242:243], off
	s_mov_b32 m0, s56
	s_nop 0
	global_load_lds_dwordx4 v[244:245], off
	s_waitcnt vmcnt(8)
	s_waitcnt lgkmcnt(0)
	s_barrier
	s_waitcnt lgkmcnt(0)
	v_mfma_f32_16x16x32_bf16 v[60:63], v[70:73], v[202:205], v[60:63]
	v_mfma_f32_16x16x32_bf16 v[52:55], v[70:73], v[210:213], v[52:55]
	v_mfma_f32_16x16x32_bf16 v[28:31], v[70:73], v[218:221], v[28:31]
	v_mfma_f32_16x16x32_bf16 v[16:19], v[70:73], v[234:237], v[16:19]
	v_mfma_f32_16x16x32_bf16 v[8:11], v[172:175], v[234:237], v[8:11]
	v_mfma_f32_16x16x32_bf16 v[24:27], v[172:175], v[218:221], v[24:27]
	v_mfma_f32_16x16x32_bf16 v[44:47], v[172:175], v[210:213], v[44:47]
	v_mfma_f32_16x16x32_bf16 v[56:59], v[172:175], v[202:205], v[56:59]
	v_mfma_f32_16x16x32_bf16 v[60:63], v[74:77], v[206:209], v[60:63]
	v_mfma_f32_16x16x32_bf16 v[52:55], v[74:77], v[214:217], v[52:55]
	v_mfma_f32_16x16x32_bf16 v[28:31], v[74:77], v[230:233], v[28:31]
	v_mfma_f32_16x16x32_bf16 v[16:19], v[74:77], v[238:241], v[16:19]
	v_mfma_f32_16x16x32_bf16 v[8:11], v[176:179], v[238:241], v[8:11]
	v_mfma_f32_16x16x32_bf16 v[24:27], v[176:179], v[230:233], v[24:27]
	v_mfma_f32_16x16x32_bf16 v[44:47], v[176:179], v[214:217], v[44:47]
	v_mfma_f32_16x16x32_bf16 v[56:59], v[176:179], v[206:209], v[56:59]
	v_mfma_f32_16x16x32_bf16 v[48:51], v[180:183], v[202:205], v[48:51]
	v_mfma_f32_16x16x32_bf16 v[36:39], v[180:183], v[210:213], v[36:39]
	v_mfma_f32_16x16x32_bf16 v[20:23], v[180:183], v[218:221], v[20:23]
	v_mfma_f32_16x16x32_bf16 v[4:7], v[180:183], v[234:237], v[4:7]
	v_mfma_f32_16x16x32_bf16 v[0:3], v[188:191], v[234:237], v[0:3]
	v_mfma_f32_16x16x32_bf16 v[12:15], v[188:191], v[218:221], v[12:15]
	v_mfma_f32_16x16x32_bf16 v[32:35], v[188:191], v[210:213], v[32:35]
	v_mfma_f32_16x16x32_bf16 v[40:43], v[188:191], v[202:205], v[40:43]
	v_mfma_f32_16x16x32_bf16 v[48:51], v[184:187], v[206:209], v[48:51]
	v_mfma_f32_16x16x32_bf16 v[36:39], v[184:187], v[214:217], v[36:39]
	v_mfma_f32_16x16x32_bf16 v[20:23], v[184:187], v[230:233], v[20:23]
	v_mfma_f32_16x16x32_bf16 v[4:7], v[184:187], v[238:241], v[4:7]
	v_mfma_f32_16x16x32_bf16 v[0:3], v[198:201], v[238:241], v[0:3]
	v_mfma_f32_16x16x32_bf16 v[12:15], v[198:201], v[230:233], v[12:15]
	v_mfma_f32_16x16x32_bf16 v[32:35], v[198:201], v[214:217], v[32:35]
	v_mfma_f32_16x16x32_bf16 v[40:43], v[198:201], v[206:209], v[40:43]
	s_barrier
; #define PG8_STAGE(bufoff, gbase, voff) do { _Pragma("unroll") for (int _i = 0; _i < 2; ++_i) \
;         __builtin_amdgcn_global_load_lds((const unsigned*)((const char*)(gbase) + (voff)[_i]), (LAS unsigned*)(lds + (bufoff) + ldsw + _i * 8192), 16, 0, 0); } while (0)
; #define PG8_LDA(dst, b, h) do { _Pragma("unroll") for (int m = 0; m < 4; ++m) _Pragma("unroll") for (int k = 0; k < 2; ++k) dst[m][k] = *(const LAS bf16x8*)(lds + PG8_SA(b, h) + aoff + m * 2048 + k * 1024); } while (0)
; #define PG8_LDB(dst, b, h) do { _Pragma("unroll") for (int n = 0; n < 2; ++n) _Pragma("unroll") for (int k = 0; k < 2; ++k) dst[n][k] = *(const LAS bf16x8*)(lds + PG8_SB(b, h) + boff + n * 2048 + k * 1024); } while (0)
; #define PG8_MMA(ai, bj, At, Bt) do { __builtin_amdgcn_s_setprio(1); _Pragma("unroll") for (int m = 0; m < 4; ++m) _Pragma("unroll") for (int n = 0; n < 2; ++n) _Pragma("unroll") for (int k = 0; k < 2; ++k) \
;         acc[ai][bj][m][n] = __builtin_amdgcn_mfma_f32_16x16x32_bf16(Bt[n][k], At[m][k], acc[ai][bj][m][n], 0, 0, 0); __builtin_amdgcn_s_setprio(0); } while (0)
; #define PG8_WAIT_V(n) asm volatile("s_waitcnt vmcnt(" #n ")" ::: "memory")
; #define PG8_WAIT_L(n) asm volatile("s_waitcnt lgkmcnt(" #n ")" ::: "memory")
; #define PG8_BAR __builtin_amdgcn_s_barrier()
; #define PG8_SCHED __builtin_amdgcn_sched_barrier(0)
; template <class Epi, class Sched>
; __device__ __forceinline__ void gemm_phase(LAS unsigned char* lds, const Gemm g, const Sched& S, const Epi& E, const int tid) {
;     ...
;             PG8_LDB(B0, 1, 0); PG8_LDB(B1, 1, 1); PG8_SCHED; PG8_LDA(At, 1, 0); PG8_STAGE(PG8_SA(0, 1), a2 + hstep, voffA);
;             PG8_WAIT_V(8); PG8_WAIT_L(0); PG8_BAR; PG8_MMA(0, 0, At, B0); PG8_MMA(0, 1, At, B1); PG8_BAR; PG8_SCHED;
	s_add_i32 s82, 0, 0x18000
	v_add_u32_e32 v69, s82, v154
	s_add_i32 s83, 0, 0x1c000
	ds_read_b128 v[70:73], v69
	ds_read_b128 v[74:77], v69 offset:1024
	ds_read_b128 v[172:175], v69 offset:2048
	ds_read_b128 v[176:179], v69 offset:3072
	v_add_u32_e32 v69, s83, v154
	ds_read_b128 v[180:183], v69
	ds_read_b128 v[184:187], v69 offset:1024
	ds_read_b128 v[188:191], v69 offset:2048
	ds_read_b128 v[198:201], v69 offset:3072
	s_add_u32 s66, s66, 0x40000
	s_addc_u32 s67, s67, 0
	s_mov_b32 m0, s57
	v_lshl_add_u64 v[82:83], s[66:67], 0, v[162:163]
	ds_read_b128 v[202:205], v171 offset:32768
	ds_read_b128 v[206:209], v171 offset:33792
	ds_read_b128 v[210:213], v171 offset:34816
	ds_read_b128 v[214:217], v171 offset:35840
	ds_read_b128 v[218:221], v171 offset:36864
	ds_read_b128 v[230:233], v171 offset:37888
	ds_read_b128 v[234:237], v171 offset:38912
	ds_read_b128 v[238:241], v171 offset:39936
	global_load_lds_dwordx4 v[82:83], off
	v_lshl_add_u64 v[82:83], s[66:67], 0, v[166:167]
	s_mov_b32 m0, s58
	s_nop 0
	global_load_lds_dwordx4 v[82:83], off
	s_waitcnt vmcnt(8)
	s_waitcnt lgkmcnt(0)
	s_barrier
	s_waitcnt lgkmcnt(0)
	v_mfma_f32_16x16x32_bf16 v[140:143], v[70:73], v[202:205], v[140:143]
	v_mfma_f32_16x16x32_bf16 v[132:135], v[70:73], v[210:213], v[132:135]
	v_mfma_f32_16x16x32_bf16 v[116:119], v[70:73], v[218:221], v[116:119]
	v_mfma_f32_16x16x32_bf16 v[100:103], v[70:73], v[234:237], v[100:103]
	v_mfma_f32_16x16x32_bf16 v[96:99], v[172:175], v[234:237], v[96:99]
	v_mfma_f32_16x16x32_bf16 v[112:115], v[172:175], v[218:221], v[112:115]
	v_mfma_f32_16x16x32_bf16 v[128:131], v[172:175], v[210:213], v[128:131]
	v_mfma_f32_16x16x32_bf16 v[136:139], v[172:175], v[202:205], v[136:139]
	v_mfma_f32_16x16x32_bf16 v[140:143], v[74:77], v[206:209], v[140:143]
	v_mfma_f32_16x16x32_bf16 v[132:135], v[74:77], v[214:217], v[132:135]
	v_mfma_f32_16x16x32_bf16 v[116:119], v[74:77], v[230:233], v[116:119]
	v_mfma_f32_16x16x32_bf16 v[100:103], v[74:77], v[238:241], v[100:103]
	v_mfma_f32_16x16x32_bf16 v[96:99], v[176:179], v[238:241], v[96:99]
	v_mfma_f32_16x16x32_bf16 v[112:115], v[176:179], v[230:233], v[112:115]
	v_mfma_f32_16x16x32_bf16 v[128:131], v[176:179], v[214:217], v[128:131]
	v_mfma_f32_16x16x32_bf16 v[136:139], v[176:179], v[206:209], v[136:139]
	v_mfma_f32_16x16x32_bf16 v[124:127], v[180:183], v[202:205], v[124:127]
	v_mfma_f32_16x16x32_bf16 v[108:111], v[180:183], v[210:213], v[108:111]
	v_mfma_f32_16x16x32_bf16 v[92:95], v[180:183], v[218:221], v[92:95]
	v_mfma_f32_16x16x32_bf16 v[82:85], v[180:183], v[234:237], v[84:87]
	v_mfma_f32_16x16x32_bf16 v[78:81], v[188:191], v[234:237], v[78:81]
	v_mfma_f32_16x16x32_bf16 v[88:91], v[188:191], v[218:221], v[88:91]
	v_mfma_f32_16x16x32_bf16 v[104:107], v[188:191], v[210:213], v[104:107]
	v_mfma_f32_16x16x32_bf16 v[120:123], v[188:191], v[202:205], v[120:123]
	v_mfma_f32_16x16x32_bf16 v[124:127], v[184:187], v[206:209], v[124:127]
	v_mfma_f32_16x16x32_bf16 v[108:111], v[184:187], v[214:217], v[108:111]
	v_mfma_f32_16x16x32_bf16 v[92:95], v[184:187], v[230:233], v[92:95]
	v_mfma_f32_16x16x32_bf16 v[84:87], v[184:187], v[238:241], v[82:85]
	v_mfma_f32_16x16x32_bf16 v[80:83], v[198:201], v[238:241], v[78:81]
	v_mfma_f32_16x16x32_bf16 v[88:91], v[198:201], v[230:233], v[88:91]
	v_mfma_f32_16x16x32_bf16 v[104:107], v[198:201], v[214:217], v[104:107]
	v_mfma_f32_16x16x32_bf16 v[120:123], v[198:201], v[206:209], v[120:123]
	s_barrier
; #define PG8_STAGE(bufoff, gbase, voff) do { _Pragma("unroll") for (int _i = 0; _i < 2; ++_i) \
;         __builtin_amdgcn_global_load_lds((const unsigned*)((const char*)(gbase) + (voff)[_i]), (LAS unsigned*)(lds + (bufoff) + ldsw + _i * 8192), 16, 0, 0); } while (0)
; #define PG8_LDA(dst, b, h) do { _Pragma("unroll") for (int m = 0; m < 4; ++m) _Pragma("unroll") for (int k = 0; k < 2; ++k) dst[m][k] = *(const LAS bf16x8*)(lds + PG8_SA(b, h) + aoff + m * 2048 + k * 1024); } while (0)
; #define PG8_MMA(ai, bj, At, Bt) do { __builtin_amdgcn_s_setprio(1); _Pragma("unroll") for (int m = 0; m < 4; ++m) _Pragma("unroll") for (int n = 0; n < 2; ++n) _Pragma("unroll") for (int k = 0; k < 2; ++k) \
;         acc[ai][bj][m][n] = __builtin_amdgcn_mfma_f32_16x16x32_bf16(Bt[n][k], At[m][k], acc[ai][bj][m][n], 0, 0, 0); __builtin_amdgcn_s_setprio(0); } while (0)
; #define PG8_WAIT_V(n) asm volatile("s_waitcnt vmcnt(" #n ")" ::: "memory")
; #define PG8_WAIT_L(n) asm volatile("s_waitcnt lgkmcnt(" #n ")" ::: "memory")
; #define PG8_BAR __builtin_amdgcn_s_barrier()
; #define PG8_SCHED __builtin_amdgcn_sched_barrier(0)
; template <class Epi, class Sched>
; __device__ __forceinline__ void gemm_phase(LAS unsigned char* lds, const Gemm g, const Sched& S, const Epi& E, const int tid) {
;     ...
;             PG8_LDA(At, 1, 1); PG8_STAGE(PG8_SB(1, 0), b3, voffB); PG8_STAGE(PG8_SB(1, 1), b3 + hstep, voffB); PG8_STAGE(PG8_SA(1, 0), a3, voffA);
;             PG8_WAIT_V(8); PG8_WAIT_L(0); PG8_BAR; PG8_MMA(1, 0, At, B0); PG8_MMA(1, 1, At, B1); PG8_BAR; PG8_SCHED;
;         }
;         if (wr == 0) PG8_BAR;
	s_add_i32 s66, s82, s52
	v_lshl_add_u64 v[78:79], v[224:225], 0, s[68:69]
	s_mov_b32 m0, s66
	ds_read_b128 v[202:205], v171 offset:49152
	ds_read_b128 v[206:209], v171 offset:50176
	ds_read_b128 v[210:213], v171 offset:51200
	ds_read_b128 v[214:217], v171 offset:52224
	ds_read_b128 v[218:221], v171 offset:53248
	ds_read_b128 v[230:233], v171 offset:54272
	ds_read_b128 v[234:237], v171 offset:55296
	ds_read_b128 v[238:241], v171 offset:56320
	global_load_lds_dwordx4 v[78:79], off
	s_add_i32 m0, s66, 0x2000
	s_add_u32 s64, s64, 0x40080
	v_lshl_add_u64 v[78:79], v[226:227], 0, s[68:69]
	s_addc_u32 s65, s65, 0
	s_add_i32 s66, s83, s52
	global_load_lds_dwordx4 v[78:79], off
	v_lshl_add_u64 v[78:79], s[64:65], 0, v[164:165]
	s_mov_b32 m0, s66
	s_nop 0
	global_load_lds_dwordx4 v[78:79], off
	v_lshl_add_u64 v[78:79], s[64:65], 0, v[168:169]
	s_add_i32 m0, s66, 0x2000
	s_nop 0
	global_load_lds_dwordx4 v[78:79], off
	v_lshl_add_u64 v[78:79], v[242:243], 0, s[68:69]
	s_mov_b32 m0, s61
	s_nop 0
	global_load_lds_dwordx4 v[78:79], off
	v_lshl_add_u64 v[78:79], v[244:245], 0, s[68:69]
	s_mov_b32 m0, s70
	s_nop 0
	global_load_lds_dwordx4 v[78:79], off
	s_waitcnt vmcnt(8)
	s_waitcnt lgkmcnt(0)
	s_barrier
	s_waitcnt lgkmcnt(0)
	v_mfma_f32_16x16x32_bf16 v[60:63], v[70:73], v[202:205], v[60:63]
	v_mfma_f32_16x16x32_bf16 v[52:55], v[70:73], v[210:213], v[52:55]
	v_mfma_f32_16x16x32_bf16 v[28:31], v[70:73], v[218:221], v[28:31]
	v_mfma_f32_16x16x32_bf16 v[16:19], v[70:73], v[234:237], v[16:19]
	v_mfma_f32_16x16x32_bf16 v[8:11], v[172:175], v[234:237], v[8:11]
	v_mfma_f32_16x16x32_bf16 v[24:27], v[172:175], v[218:221], v[24:27]
	v_mfma_f32_16x16x32_bf16 v[44:47], v[172:175], v[210:213], v[44:47]
	v_mfma_f32_16x16x32_bf16 v[56:59], v[172:175], v[202:205], v[56:59]
	v_mfma_f32_16x16x32_bf16 v[60:63], v[74:77], v[206:209], v[60:63]
	v_mfma_f32_16x16x32_bf16 v[52:55], v[74:77], v[214:217], v[52:55]
	v_mfma_f32_16x16x32_bf16 v[28:31], v[74:77], v[230:233], v[28:31]
	v_mfma_f32_16x16x32_bf16 v[16:19], v[74:77], v[238:241], v[16:19]
	v_mfma_f32_16x16x32_bf16 v[8:11], v[176:179], v[238:241], v[8:11]
	v_mfma_f32_16x16x32_bf16 v[24:27], v[176:179], v[230:233], v[24:27]
	v_mfma_f32_16x16x32_bf16 v[44:47], v[176:179], v[214:217], v[44:47]
	v_mfma_f32_16x16x32_bf16 v[56:59], v[176:179], v[206:209], v[56:59]
	v_mfma_f32_16x16x32_bf16 v[48:51], v[180:183], v[202:205], v[48:51]
	v_mfma_f32_16x16x32_bf16 v[36:39], v[180:183], v[210:213], v[36:39]
	v_mfma_f32_16x16x32_bf16 v[20:23], v[180:183], v[218:221], v[20:23]
	v_mfma_f32_16x16x32_bf16 v[4:7], v[180:183], v[234:237], v[4:7]
	v_mfma_f32_16x16x32_bf16 v[0:3], v[188:191], v[234:237], v[0:3]
	v_mfma_f32_16x16x32_bf16 v[12:15], v[188:191], v[218:221], v[12:15]
	v_mfma_f32_16x16x32_bf16 v[32:35], v[188:191], v[210:213], v[32:35]
	v_mfma_f32_16x16x32_bf16 v[40:43], v[188:191], v[202:205], v[40:43]
	v_mfma_f32_16x16x32_bf16 v[48:51], v[184:187], v[206:209], v[48:51]
	v_mfma_f32_16x16x32_bf16 v[36:39], v[184:187], v[214:217], v[36:39]
	v_mfma_f32_16x16x32_bf16 v[20:23], v[184:187], v[230:233], v[20:23]
	v_mfma_f32_16x16x32_bf16 v[4:7], v[184:187], v[238:241], v[4:7]
	v_mfma_f32_16x16x32_bf16 v[0:3], v[198:201], v[238:241], v[0:3]
	v_mfma_f32_16x16x32_bf16 v[12:15], v[198:201], v[230:233], v[12:15]
	v_mfma_f32_16x16x32_bf16 v[32:35], v[198:201], v[214:217], v[32:35]
	v_mfma_f32_16x16x32_bf16 v[40:43], v[198:201], v[206:209], v[40:43]
	s_barrier
	s_add_i32 s81, s81, 2
	s_add_u32 s62, s62, 0x100
	s_addc_u32 s63, s63, 0
	s_add_u32 s78, s78, 0x100
	s_addc_u32 s79, s79, 0
	s_cmp_gt_u32 s81, 13
	s_cbranch_scc0 .LBB0_326
	s_and_b64 vcc, exec, s[8:9]
	s_cbranch_vccz .LBB0_329
	s_barrier

;     __device__ __forceinline__ Pre prefetch(const Unit& u, int tid) const { return prenorm_load(stats, u.pn * BM, sW + (size_t)(u.pn >> 4) * SW_ROWS + u.pm * BM, tid); }
;     __device__ __forceinline__ Pre prefetch(const Unit& u, int tid) const { return prenorm_load(stats, u.pm * BM, sW + (size_t)(u.pm >> 4) * SW_ROWS + u.pn * BM, tid); }
;     __device__ __forceinline__ Pre prefetch(const Unit& u, int tid) const { return prenorm_load(stats, u.pm * BM, sW + (size_t)(u.pm >> 4) * SW_ROWS + u.pn * BM, tid); }
; #define PG8_STAGE(bufoff, gbase, voff) do { _Pragma("unroll") for (int _i = 0; _i < 2; ++_i) \
;         __builtin_amdgcn_global_load_lds((const unsigned*)((const char*)(gbase) + (voff)[_i]), (LAS unsigned*)(lds + (bufoff) + ldsw + _i * 8192), 16, 0, 0); } while (0)
; #define PG8_LDA(dst, b, h) do { _Pragma("unroll") for (int m = 0; m < 4; ++m) _Pragma("unroll") for (int k = 0; k < 2; ++k) dst[m][k] = *(const LAS bf16x8*)(lds + PG8_SA(b, h) + aoff + m * 2048 + k * 1024); } while (0)
; #define PG8_LDB(dst, b, h) do { _Pragma("unroll") for (int n = 0; n < 2; ++n) _Pragma("unroll") for (int k = 0; k < 2; ++k) dst[n][k] = *(const LAS bf16x8*)(lds + PG8_SB(b, h) + boff + n * 2048 + k * 1024); } while (0)
; template <class Epi, class Sched>
; __device__ __forceinline__ void gemm_phase(LAS unsigned char* lds, const Gemm g, const Sched& S, const Epi& E, const int tid) {
;     ...
;         const char* nA = has_next ? (const char*)g.A + (size_t)nxt.pm * tstep : cA; const char* nB = has_next ? (const char*)g.Bt + (size_t)nxt.pn * tstep : cB;
;         const typename Epi::Pre pre = E.prefetch(cur, tid);
;         for (int t = 0; t < nt; t += 2) {
;             const bool last = (t == nt - 2);
;             const char* a1 = cA + (size_t)(t + 1) * kstep;
;             const char* a2 = last ? nA : cA + (size_t)(t + 2) * kstep; const char* b2 = last ? nB : cB + (size_t)(t + 2) * kstep;
;             const char* a3 = a2 + kstep; const char* b3 = b2 + kstep;
;             PG8_LDB(B0, 0, 0); PG8_LDB(B1, 0, 1); PG8_SCHED; PG8_LDA(At, 0, 0); PG8_STAGE(PG8_SA(1, 1), a1 + hstep, voffA);
;             PG8_WAIT_V(8); PG8_WAIT_L(0); PG8_BAR; PG8_MMA(0, 0, At, B0); PG8_MMA(0, 1, At, B1); PG8_BAR; PG8_SCHED;
;             PG8_LDA(At, 0, 1); PG8_STAGE(PG8_SB(0, 0), b2, voffB); PG8_STAGE(PG8_SB(0, 1), b2 + hstep, voffB); PG8_STAGE(PG8_SA(0, 0), a2, voffA);
.LBB0_565:
.LBB0_566:
	s_or_b64 exec, exec, s[82:83]
	s_add_u32 vcc_lo, s80, 0x80
	s_addc_u32 vcc_hi, s81, 0
	s_add_u32 s61, s74, 0x100
	s_addc_u32 s67, s75, 0
	s_mov_b32 s74, 0
	s_add_i32 s80, s74, 2
	s_add_u32 s81, vcc_lo, 0x80
	s_addc_u32 s75, vcc_hi, 0
	s_add_i32 s3, 0, 0x10000
	s_cmp_eq_u32 s57, s74
	s_cselect_b32 s75, s71, s75
	s_cselect_b32 s74, s70, s81
	v_add_u32_e32 v70, s3, v232
	s_cselect_b32 s83, s73, s67
	s_cselect_b32 s82, s72, s61
	s_add_i32 s81, 0, 0x14000
	ds_read_b128 v[58:61], v70
	ds_read_b128 v[62:65], v70 offset:1024
	ds_read_b128 v[66:69], v70 offset:2048
	ds_read_b128 v[80:83], v70 offset:3072
	v_add_u32_e32 v70, s81, v232
	ds_read_b128 v[84:87], v70
	ds_read_b128 v[88:91], v70 offset:1024
	ds_read_b128 v[92:95], v70 offset:2048
	ds_read_b128 v[152:155], v70 offset:3072
	v_lshl_add_u64 v[70:71], vcc, 0, v[204:205]
	s_add_i32 m0, s97, 0xc000
	ds_read_b128 v[164:167], v240
	ds_read_b128 v[168:171], v240 offset:1024
	ds_read_b128 v[172:175], v240 offset:2048
	ds_read_b128 v[176:179], v240 offset:3072
	ds_read_b128 v[180:183], v240 offset:4096
	ds_read_b128 v[184:187], v240 offset:5120
	ds_read_b128 v[188:191], v240 offset:6144
	ds_read_b128 v[208:211], v240 offset:7168
	global_load_lds_dwordx4 v[70:71], off
	v_lshl_add_u64 v[70:71], vcc, 0, v[206:207]
	s_add_i32 m0, s97, 0xe000
	s_nop 0
	global_load_lds_dwordx4 v[70:71], off
	s_waitcnt vmcnt(8)
	s_waitcnt lgkmcnt(0)
	s_barrier
	s_waitcnt lgkmcnt(0)
	v_mfma_f32_16x16x32_bf16 v[160:163], v[58:61], v[164:167], 0
	v_mfma_f32_16x16x32_bf16 v[140:143], v[58:61], v[172:175], 0
	v_mfma_f32_16x16x32_bf16 v[124:127], v[58:61], v[180:183], 0
	v_mfma_f32_16x16x32_bf16 v[108:111], v[58:61], v[188:191], 0
	v_mfma_f32_16x16x32_bf16 v[104:107], v[66:69], v[188:191], 0
	v_mfma_f32_16x16x32_bf16 v[120:123], v[66:69], v[180:183], 0
	v_mfma_f32_16x16x32_bf16 v[136:139], v[66:69], v[172:175], 0
	v_mfma_f32_16x16x32_bf16 v[156:159], v[66:69], v[164:167], 0
	v_mfma_f32_16x16x32_bf16 v[160:163], v[62:65], v[168:171], v[160:163]
	v_mfma_f32_16x16x32_bf16 v[140:143], v[62:65], v[176:179], v[140:143]
	v_mfma_f32_16x16x32_bf16 v[124:127], v[62:65], v[184:187], v[124:127]
	v_mfma_f32_16x16x32_bf16 v[108:111], v[62:65], v[208:211], v[108:111]
	v_mfma_f32_16x16x32_bf16 v[104:107], v[80:83], v[208:211], v[104:107]
	v_mfma_f32_16x16x32_bf16 v[120:123], v[80:83], v[184:187], v[120:123]
	v_mfma_f32_16x16x32_bf16 v[136:139], v[80:83], v[176:179], v[136:139]
	v_mfma_f32_16x16x32_bf16 v[156:159], v[80:83], v[168:171], v[156:159]
	v_mfma_f32_16x16x32_bf16 v[148:151], v[84:87], v[164:167], 0
	v_mfma_f32_16x16x32_bf16 v[132:135], v[84:87], v[172:175], 0
	v_mfma_f32_16x16x32_bf16 v[116:119], v[84:87], v[180:183], 0
	v_mfma_f32_16x16x32_bf16 v[100:103], v[84:87], v[188:191], 0
	v_mfma_f32_16x16x32_bf16 v[96:99], v[92:95], v[188:191], 0
	v_mfma_f32_16x16x32_bf16 v[112:115], v[92:95], v[180:183], 0
	v_mfma_f32_16x16x32_bf16 v[128:131], v[92:95], v[172:175], 0
	v_mfma_f32_16x16x32_bf16 v[144:147], v[92:95], v[164:167], 0
	v_mfma_f32_16x16x32_bf16 v[148:151], v[88:91], v[168:171], v[148:151]
	v_mfma_f32_16x16x32_bf16 v[132:135], v[88:91], v[176:179], v[132:135]
	v_mfma_f32_16x16x32_bf16 v[116:119], v[88:91], v[184:187], v[116:119]
	v_mfma_f32_16x16x32_bf16 v[100:103], v[88:91], v[208:211], v[100:103]
	v_mfma_f32_16x16x32_bf16 v[96:99], v[152:155], v[208:211], v[96:99]
	v_mfma_f32_16x16x32_bf16 v[112:115], v[152:155], v[184:187], v[112:115]
	v_mfma_f32_16x16x32_bf16 v[128:131], v[152:155], v[176:179], v[128:131]
	v_mfma_f32_16x16x32_bf16 v[144:147], v[152:155], v[168:171], v[144:147]
	s_barrier
	s_add_i32 s3, s3, s94
	v_lshl_add_u64 v[212:213], s[82:83], 0, v[192:193]
	s_mov_b32 m0, s3
	ds_read_b128 v[164:167], v240 offset:16384
	ds_read_b128 v[168:171], v240 offset:17408
	ds_read_b128 v[172:175], v240 offset:18432
	ds_read_b128 v[176:179], v240 offset:19456
	ds_read_b128 v[180:183], v240 offset:20480
	ds_read_b128 v[184:187], v240 offset:21504
	ds_read_b128 v[188:191], v240 offset:22528
	ds_read_b128 v[208:211], v240 offset:23552
	global_load_lds_dwordx4 v[212:213], off
	s_add_i32 m0, s3, 0x2000
	v_lshl_add_u64 v[214:215], s[82:83], 0, v[198:199]
	s_add_u32 s82, s82, s12
	s_addc_u32 s83, s83, 0
	s_add_i32 s3, s81, s94
	global_load_lds_dwordx4 v[214:215], off
	v_lshl_add_u64 v[216:217], s[82:83], 0, v[192:193]
	s_mov_b32 m0, s3
	v_lshl_add_u64 v[218:219], s[82:83], 0, v[198:199]
	global_load_lds_dwordx4 v[216:217], off
	s_add_i32 m0, s3, 0x2000
	v_lshl_add_u64 v[220:221], s[74:75], 0, v[202:203]
	global_load_lds_dwordx4 v[218:219], off
	s_mov_b32 m0, s97
	v_lshl_add_u64 v[224:225], s[74:75], 0, v[200:201]
	global_load_lds_dwordx4 v[220:221], off
	s_mov_b32 m0, s98
	s_nop 0
	global_load_lds_dwordx4 v[224:225], off
	s_waitcnt vmcnt(8)
	s_waitcnt lgkmcnt(0)
	s_barrier
; #define PG8_STAGE(bufoff, gbase, voff) do { _Pragma("unroll") for (int _i = 0; _i < 2; ++_i) \
;         __builtin_amdgcn_global_load_lds((const unsigned*)((const char*)(gbase) + (voff)[_i]), (LAS unsigned*)(lds + (bufoff) + ldsw + _i * 8192), 16, 0, 0); } while (0)
; #define PG8_LDA(dst, b, h) do { _Pragma("unroll") for (int m = 0; m < 4; ++m) _Pragma("unroll") for (int k = 0; k < 2; ++k) dst[m][k] = *(const LAS bf16x8*)(lds + PG8_SA(b, h) + aoff + m * 2048 + k * 1024); } while (0)
; #define PG8_LDB(dst, b, h) do { _Pragma("unroll") for (int n = 0; n < 2; ++n) _Pragma("unroll") for (int k = 0; k < 2; ++k) dst[n][k] = *(const LAS bf16x8*)(lds + PG8_SB(b, h) + boff + n * 2048 + k * 1024); } while (0)
; #define PG8_MMA(ai, bj, At, Bt) do { __builtin_amdgcn_s_setprio(1); _Pragma("unroll") for (int m = 0; m < 4; ++m) _Pragma("unroll") for (int n = 0; n < 2; ++n) _Pragma("unroll") for (int k = 0; k < 2; ++k) \
;         acc[ai][bj][m][n] = __builtin_amdgcn_mfma_f32_16x16x32_bf16(Bt[n][k], At[m][k], acc[ai][bj][m][n], 0, 0, 0); __builtin_amdgcn_s_setprio(0); } while (0)
; #define PG8_WAIT_V(n) asm volatile("s_waitcnt vmcnt(" #n ")" ::: "memory")
; #define PG8_WAIT_L(n) asm volatile("s_waitcnt lgkmcnt(" #n ")" ::: "memory")
; #define PG8_BAR __builtin_amdgcn_s_barrier()
; #define PG8_SCHED __builtin_amdgcn_sched_barrier(0)
; template <class Epi, class Sched>
; __device__ __forceinline__ void gemm_phase(LAS unsigned char* lds, const Gemm g, const Sched& S, const Epi& E, const int tid) {
;     ...
;             PG8_WAIT_V(8); PG8_WAIT_L(0); PG8_BAR; PG8_MMA(0, 0, At, B0); PG8_MMA(0, 1, At, B1); PG8_BAR; PG8_SCHED;
;             PG8_LDA(At, 0, 1); PG8_STAGE(PG8_SB(0, 0), b2, voffB); PG8_STAGE(PG8_SB(0, 1), b2 + hstep, voffB); PG8_STAGE(PG8_SA(0, 0), a2, voffA);
;             PG8_WAIT_V(8); PG8_WAIT_L(0); PG8_BAR; PG8_MMA(1, 0, At, B0); PG8_MMA(1, 1, At, B1); PG8_BAR; PG8_SCHED;
;             PG8_LDB(B0, 1, 0); PG8_LDB(B1, 1, 1); PG8_SCHED; PG8_LDA(At, 1, 0); PG8_STAGE(PG8_SA(0, 1), a2 + hstep, voffA);
;             PG8_WAIT_V(8); PG8_WAIT_L(0); PG8_BAR; PG8_MMA(0, 0, At, B0); PG8_MMA(0, 1, At, B1); PG8_BAR; PG8_SCHED;
	s_waitcnt lgkmcnt(0)
	v_mfma_f32_16x16x32_bf16 v[76:79], v[58:61], v[164:167], 0
	v_mfma_f32_16x16x32_bf16 v[44:47], v[58:61], v[172:175], 0
	v_mfma_f32_16x16x32_bf16 v[28:31], v[58:61], v[180:183], 0
	v_mfma_f32_16x16x32_bf16 v[12:15], v[58:61], v[188:191], 0
	v_mfma_f32_16x16x32_bf16 v[8:11], v[66:69], v[188:191], 0
	v_mfma_f32_16x16x32_bf16 v[24:27], v[66:69], v[180:183], 0
	v_mfma_f32_16x16x32_bf16 v[40:43], v[66:69], v[172:175], 0
	v_mfma_f32_16x16x32_bf16 v[70:73], v[66:69], v[164:167], 0
	v_mfma_f32_16x16x32_bf16 v[76:79], v[62:65], v[168:171], v[76:79]
	v_mfma_f32_16x16x32_bf16 v[44:47], v[62:65], v[176:179], v[44:47]
	v_mfma_f32_16x16x32_bf16 v[28:31], v[62:65], v[184:187], v[28:31]
	v_mfma_f32_16x16x32_bf16 v[12:15], v[62:65], v[208:211], v[12:15]
	v_mfma_f32_16x16x32_bf16 v[8:11], v[80:83], v[208:211], v[8:11]
	v_mfma_f32_16x16x32_bf16 v[24:27], v[80:83], v[184:187], v[24:27]
	v_mfma_f32_16x16x32_bf16 v[40:43], v[80:83], v[176:179], v[40:43]
	v_mfma_f32_16x16x32_bf16 v[70:73], v[80:83], v[168:171], v[70:73]
	v_mfma_f32_16x16x32_bf16 v[52:55], v[84:87], v[164:167], 0
	v_mfma_f32_16x16x32_bf16 v[36:39], v[84:87], v[172:175], 0
	v_mfma_f32_16x16x32_bf16 v[20:23], v[84:87], v[180:183], 0
	v_mfma_f32_16x16x32_bf16 v[4:7], v[84:87], v[188:191], 0
	v_mfma_f32_16x16x32_bf16 v[0:3], v[92:95], v[188:191], 0
	v_mfma_f32_16x16x32_bf16 v[16:19], v[92:95], v[180:183], 0
	v_mfma_f32_16x16x32_bf16 v[32:35], v[92:95], v[172:175], 0
	v_mfma_f32_16x16x32_bf16 v[48:51], v[92:95], v[164:167], 0
	v_mfma_f32_16x16x32_bf16 v[52:55], v[88:91], v[168:171], v[52:55]
	v_mfma_f32_16x16x32_bf16 v[36:39], v[88:91], v[176:179], v[36:39]
	v_mfma_f32_16x16x32_bf16 v[20:23], v[88:91], v[184:187], v[20:23]
	v_mfma_f32_16x16x32_bf16 v[4:7], v[88:91], v[208:211], v[4:7]
	v_mfma_f32_16x16x32_bf16 v[0:3], v[152:155], v[208:211], v[0:3]
	v_mfma_f32_16x16x32_bf16 v[16:19], v[152:155], v[184:187], v[16:19]
	v_mfma_f32_16x16x32_bf16 v[32:35], v[152:155], v[176:179], v[32:35]
	v_mfma_f32_16x16x32_bf16 v[48:51], v[152:155], v[168:171], v[48:51]
	s_barrier
	s_add_i32 s3, 0, 0x18000
	v_add_u32_e32 v74, s3, v232
	s_add_i32 s81, 0, 0x1c000
	ds_read_b128 v[58:61], v74
	ds_read_b128 v[62:65], v74 offset:1024
	ds_read_b128 v[66:69], v74 offset:2048
	ds_read_b128 v[80:83], v74 offset:3072
	v_add_u32_e32 v74, s81, v232
	ds_read_b128 v[84:87], v74
	ds_read_b128 v[88:91], v74 offset:1024
	ds_read_b128 v[92:95], v74 offset:2048
	ds_read_b128 v[152:155], v74 offset:3072
	s_add_u32 s74, s74, s12
	s_addc_u32 s75, s75, 0
	s_mov_b32 m0, s99
	v_lshl_add_u64 v[74:75], s[74:75], 0, v[202:203]
	ds_read_b128 v[164:167], v240 offset:32768
	ds_read_b128 v[168:171], v240 offset:33792
	ds_read_b128 v[172:175], v240 offset:34816
	ds_read_b128 v[176:179], v240 offset:35840
	ds_read_b128 v[180:183], v240 offset:36864
	ds_read_b128 v[184:187], v240 offset:37888
	ds_read_b128 v[188:191], v240 offset:38912
	ds_read_b128 v[208:211], v240 offset:39936
	global_load_lds_dwordx4 v[74:75], off
	v_lshl_add_u64 v[74:75], s[74:75], 0, v[200:201]
	s_mov_b32 m0, s78
	s_nop 0
	global_load_lds_dwordx4 v[74:75], off
	s_waitcnt vmcnt(8)
	s_waitcnt lgkmcnt(0)
	s_barrier
	s_waitcnt lgkmcnt(0)
	v_mfma_f32_16x16x32_bf16 v[160:163], v[58:61], v[164:167], v[160:163]
	v_mfma_f32_16x16x32_bf16 v[140:143], v[58:61], v[172:175], v[140:143]
	v_mfma_f32_16x16x32_bf16 v[124:127], v[58:61], v[180:183], v[124:127]
	v_mfma_f32_16x16x32_bf16 v[108:111], v[58:61], v[188:191], v[108:111]
	v_mfma_f32_16x16x32_bf16 v[104:107], v[66:69], v[188:191], v[104:107]
	v_mfma_f32_16x16x32_bf16 v[120:123], v[66:69], v[180:183], v[120:123]
	v_mfma_f32_16x16x32_bf16 v[136:139], v[66:69], v[172:175], v[136:139]
	v_mfma_f32_16x16x32_bf16 v[156:159], v[66:69], v[164:167], v[156:159]
	v_mfma_f32_16x16x32_bf16 v[160:163], v[62:65], v[168:171], v[160:163]
	v_mfma_f32_16x16x32_bf16 v[140:143], v[62:65], v[176:179], v[140:143]
	v_mfma_f32_16x16x32_bf16 v[124:127], v[62:65], v[184:187], v[124:127]
	v_mfma_f32_16x16x32_bf16 v[108:111], v[62:65], v[208:211], v[108:111]
	v_mfma_f32_16x16x32_bf16 v[104:107], v[80:83], v[208:211], v[104:107]
	v_mfma_f32_16x16x32_bf16 v[120:123], v[80:83], v[184:187], v[120:123]
	v_mfma_f32_16x16x32_bf16 v[136:139], v[80:83], v[176:179], v[136:139]
	v_mfma_f32_16x16x32_bf16 v[156:159], v[80:83], v[168:171], v[156:159]
	v_mfma_f32_16x16x32_bf16 v[148:151], v[84:87], v[164:167], v[148:151]
	v_mfma_f32_16x16x32_bf16 v[132:135], v[84:87], v[172:175], v[132:135]
	v_mfma_f32_16x16x32_bf16 v[116:119], v[84:87], v[180:183], v[116:119]
	v_mfma_f32_16x16x32_bf16 v[100:103], v[84:87], v[188:191], v[100:103]
	v_mfma_f32_16x16x32_bf16 v[96:99], v[92:95], v[188:191], v[96:99]
	v_mfma_f32_16x16x32_bf16 v[112:115], v[92:95], v[180:183], v[112:115]
	v_mfma_f32_16x16x32_bf16 v[128:131], v[92:95], v[172:175], v[128:131]
	v_mfma_f32_16x16x32_bf16 v[144:147], v[92:95], v[164:167], v[144:147]
	v_mfma_f32_16x16x32_bf16 v[148:151], v[88:91], v[168:171], v[148:151]
	v_mfma_f32_16x16x32_bf16 v[132:135], v[88:91], v[176:179], v[132:135]
	v_mfma_f32_16x16x32_bf16 v[116:119], v[88:91], v[184:187], v[116:119]
	v_mfma_f32_16x16x32_bf16 v[100:103], v[88:91], v[208:211], v[100:103]
	v_mfma_f32_16x16x32_bf16 v[96:99], v[152:155], v[208:211], v[96:99]
	v_mfma_f32_16x16x32_bf16 v[112:115], v[152:155], v[184:187], v[112:115]
	v_mfma_f32_16x16x32_bf16 v[128:131], v[152:155], v[176:179], v[128:131]
	v_mfma_f32_16x16x32_bf16 v[144:147], v[152:155], v[168:171], v[144:147]
	s_barrier
; #define PG8_STAGE(bufoff, gbase, voff) do { _Pragma("unroll") for (int _i = 0; _i < 2; ++_i) \
;         __builtin_amdgcn_global_load_lds((const unsigned*)((const char*)(gbase) + (voff)[_i]), (LAS unsigned*)(lds + (bufoff) + ldsw + _i * 8192), 16, 0, 0); } while (0)
; #define PG8_LDA(dst, b, h) do { _Pragma("unroll") for (int m = 0; m < 4; ++m) _Pragma("unroll") for (int k = 0; k < 2; ++k) dst[m][k] = *(const LAS bf16x8*)(lds + PG8_SA(b, h) + aoff + m * 2048 + k * 1024); } while (0)
; #define PG8_LDB(dst, b, h) do { _Pragma("unroll") for (int n = 0; n < 2; ++n) _Pragma("unroll") for (int k = 0; k < 2; ++k) dst[n][k] = *(const LAS bf16x8*)(lds + PG8_SB(b, h) + boff + n * 2048 + k * 1024); } while (0)
; #define PG8_WAIT_V(n) asm volatile("s_waitcnt vmcnt(" #n ")" ::: "memory")
; #define PG8_BAR __builtin_amdgcn_s_barrier()
; template <class Epi, class Sched>
; __device__ __forceinline__ void gemm_phase(LAS unsigned char* lds, const Gemm g, const Sched& S, const Epi& E, const int tid) {
;     ...
;         for (int t = 0; t < nt; t += 2) {
;             const bool last = (t == nt - 2);
;             const char* a1 = cA + (size_t)(t + 1) * kstep;
;             const char* a2 = last ? nA : cA + (size_t)(t + 2) * kstep; const char* b2 = last ? nB : cB + (size_t)(t + 2) * kstep;
;             const char* a3 = a2 + kstep; const char* b3 = b2 + kstep;
;             PG8_LDB(B0, 0, 0); PG8_LDB(B1, 0, 1); PG8_SCHED; PG8_LDA(At, 0, 0); PG8_STAGE(PG8_SA(1, 1), a1 + hstep, voffA);
;             PG8_WAIT_V(8); PG8_WAIT_L(0); PG8_BAR; PG8_MMA(0, 0, At, B0); PG8_MMA(0, 1, At, B1); PG8_BAR; PG8_SCHED;
;             PG8_LDA(At, 0, 1); PG8_STAGE(PG8_SB(0, 0), b2, voffB); PG8_STAGE(PG8_SB(0, 1), b2 + hstep, voffB); PG8_STAGE(PG8_SA(0, 0), a2, voffA);
;             PG8_WAIT_V(8); PG8_WAIT_L(0); PG8_BAR; PG8_MMA(1, 0, At, B0); PG8_MMA(1, 1, At, B1); PG8_BAR; PG8_SCHED;
;             PG8_LDB(B0, 1, 0); PG8_LDB(B1, 1, 1); PG8_SCHED; PG8_LDA(At, 1, 0); PG8_STAGE(PG8_SA(0, 1), a2 + hstep, voffA);
;             PG8_WAIT_V(8); PG8_WAIT_L(0); PG8_BAR; PG8_MMA(0, 0, At, B0); PG8_MMA(0, 1, At, B1); PG8_BAR; PG8_SCHED;
;             PG8_LDA(At, 1, 1); PG8_STAGE(PG8_SB(1, 0), b3, voffB); PG8_STAGE(PG8_SB(1, 1), b3 + hstep, voffB); PG8_STAGE(PG8_SA(1, 0), a3, voffA);
;             PG8_WAIT_V(8); PG8_WAIT_L(0); PG8_BAR; PG8_MMA(1, 0, At, B0); PG8_MMA(1, 1, At, B1); PG8_BAR; PG8_SCHED;
	s_add_i32 s3, s3, s94
	v_lshl_add_u64 v[74:75], v[212:213], 0, s[68:69]
	s_mov_b32 m0, s3
	ds_read_b128 v[164:167], v240 offset:49152
	ds_read_b128 v[168:171], v240 offset:50176
	ds_read_b128 v[172:175], v240 offset:51200
	ds_read_b128 v[176:179], v240 offset:52224
	ds_read_b128 v[180:183], v240 offset:53248
	ds_read_b128 v[184:187], v240 offset:54272
	ds_read_b128 v[188:191], v240 offset:55296
	ds_read_b128 v[208:211], v240 offset:56320
	global_load_lds_dwordx4 v[74:75], off
	v_lshl_add_u64 v[74:75], v[214:215], 0, s[68:69]
	s_add_i32 m0, s3, 0x2000
	s_add_i32 s3, s81, s94
	global_load_lds_dwordx4 v[74:75], off
	v_lshl_add_u64 v[74:75], v[216:217], 0, s[68:69]
	s_mov_b32 m0, s3
	s_nop 0
	global_load_lds_dwordx4 v[74:75], off
	v_lshl_add_u64 v[74:75], v[218:219], 0, s[68:69]
	s_add_i32 m0, s3, 0x2000
	s_nop 0
	global_load_lds_dwordx4 v[74:75], off
	v_lshl_add_u64 v[74:75], v[220:221], 0, s[68:69]
	s_mov_b32 m0, s53
	s_nop 0
	global_load_lds_dwordx4 v[74:75], off
	v_lshl_add_u64 v[74:75], v[224:225], 0, s[68:69]
	s_mov_b32 m0, s56
	s_nop 0
	global_load_lds_dwordx4 v[74:75], off
	s_waitcnt vmcnt(8)
	s_waitcnt lgkmcnt(0)
	s_barrier
	s_waitcnt lgkmcnt(0)
	v_mfma_f32_16x16x32_bf16 v[74:77], v[58:61], v[164:167], v[76:79]
	v_mfma_f32_16x16x32_bf16 v[44:47], v[58:61], v[172:175], v[44:47]
	v_mfma_f32_16x16x32_bf16 v[28:31], v[58:61], v[180:183], v[28:31]
	v_mfma_f32_16x16x32_bf16 v[12:15], v[58:61], v[188:191], v[12:15]
	v_mfma_f32_16x16x32_bf16 v[8:11], v[66:69], v[188:191], v[8:11]
	v_mfma_f32_16x16x32_bf16 v[24:27], v[66:69], v[180:183], v[24:27]
	v_mfma_f32_16x16x32_bf16 v[40:43], v[66:69], v[172:175], v[40:43]
	v_mfma_f32_16x16x32_bf16 v[70:73], v[66:69], v[164:167], v[70:73]
	v_mfma_f32_16x16x32_bf16 v[76:79], v[62:65], v[168:171], v[74:77]
	v_mfma_f32_16x16x32_bf16 v[44:47], v[62:65], v[176:179], v[44:47]
	v_mfma_f32_16x16x32_bf16 v[28:31], v[62:65], v[184:187], v[28:31]
	v_mfma_f32_16x16x32_bf16 v[12:15], v[62:65], v[208:211], v[12:15]
	v_mfma_f32_16x16x32_bf16 v[8:11], v[80:83], v[208:211], v[8:11]
	v_mfma_f32_16x16x32_bf16 v[24:27], v[80:83], v[184:187], v[24:27]
	v_mfma_f32_16x16x32_bf16 v[40:43], v[80:83], v[176:179], v[40:43]
	v_mfma_f32_16x16x32_bf16 v[72:75], v[80:83], v[168:171], v[70:73]
	v_mfma_f32_16x16x32_bf16 v[52:55], v[84:87], v[164:167], v[52:55]
	v_mfma_f32_16x16x32_bf16 v[36:39], v[84:87], v[172:175], v[36:39]
	v_mfma_f32_16x16x32_bf16 v[20:23], v[84:87], v[180:183], v[20:23]
	v_mfma_f32_16x16x32_bf16 v[4:7], v[84:87], v[188:191], v[4:7]
	v_mfma_f32_16x16x32_bf16 v[0:3], v[92:95], v[188:191], v[0:3]
	v_mfma_f32_16x16x32_bf16 v[16:19], v[92:95], v[180:183], v[16:19]
	v_mfma_f32_16x16x32_bf16 v[32:35], v[92:95], v[172:175], v[32:35]
	v_mfma_f32_16x16x32_bf16 v[48:51], v[92:95], v[164:167], v[48:51]
	v_mfma_f32_16x16x32_bf16 v[52:55], v[88:91], v[168:171], v[52:55]
	v_mfma_f32_16x16x32_bf16 v[36:39], v[88:91], v[176:179], v[36:39]
	v_mfma_f32_16x16x32_bf16 v[20:23], v[88:91], v[184:187], v[20:23]
	v_mfma_f32_16x16x32_bf16 v[4:7], v[88:91], v[208:211], v[4:7]
	v_mfma_f32_16x16x32_bf16 v[0:3], v[152:155], v[208:211], v[0:3]
	v_mfma_f32_16x16x32_bf16 v[16:19], v[152:155], v[184:187], v[16:19]
	v_mfma_f32_16x16x32_bf16 v[32:35], v[152:155], v[176:179], v[32:35]
	v_mfma_f32_16x16x32_bf16 v[48:51], v[152:155], v[168:171], v[48:51]
	s_barrier
	s_add_u32 vcc_lo, vcc_lo, 0x100
	s_addc_u32 vcc_hi, vcc_hi, 0
	s_add_u32 s61, s61, 0x100
	s_addc_u32 s67, s67, 0
	s_cmp_ge_u32 s80, s52
	s_mov_b32 s74, s80
.LBB0_567:
	s_add_i32 s80, s74, 2
	s_add_u32 s81, vcc_lo, 0x80
	s_addc_u32 s75, vcc_hi, 0
	s_add_i32 s3, 0, 0x10000
	s_cmp_eq_u32 s57, s74
	s_cselect_b32 s75, s71, s75
	s_cselect_b32 s74, s70, s81
	v_add_u32_e32 v70, s3, v232
	s_cselect_b32 s83, s73, s67
	s_cselect_b32 s82, s72, s61
	s_add_i32 s81, 0, 0x14000
	ds_read_b128 v[58:61], v70
	ds_read_b128 v[62:65], v70 offset:1024
	ds_read_b128 v[66:69], v70 offset:2048
	ds_read_b128 v[80:83], v70 offset:3072
	v_add_u32_e32 v70, s81, v232
	ds_read_b128 v[84:87], v70
	ds_read_b128 v[88:91], v70 offset:1024
	ds_read_b128 v[92:95], v70 offset:2048
	ds_read_b128 v[152:155], v70 offset:3072
	v_lshl_add_u64 v[70:71], vcc, 0, v[204:205]
	s_add_i32 m0, s97, 0xc000
	ds_read_b128 v[164:167], v240
	ds_read_b128 v[168:171], v240 offset:1024
	ds_read_b128 v[172:175], v240 offset:2048
	ds_read_b128 v[176:179], v240 offset:3072
	ds_read_b128 v[180:183], v240 offset:4096
	ds_read_b128 v[184:187], v240 offset:5120
	ds_read_b128 v[188:191], v240 offset:6144
	ds_read_b128 v[208:211], v240 offset:7168
	global_load_lds_dwordx4 v[70:71], off
	v_lshl_add_u64 v[70:71], vcc, 0, v[206:207]
	s_add_i32 m0, s97, 0xe000
	s_nop 0
	global_load_lds_dwordx4 v[70:71], off
	s_waitcnt vmcnt(8)
	s_waitcnt lgkmcnt(0)
	s_barrier
; #define PG8_STAGE(bufoff, gbase, voff) do { _Pragma("unroll") for (int _i = 0; _i < 2; ++_i) \
;         __builtin_amdgcn_global_load_lds((const unsigned*)((const char*)(gbase) + (voff)[_i]), (LAS unsigned*)(lds + (bufoff) + ldsw + _i * 8192), 16, 0, 0); } while (0)
; #define PG8_LDA(dst, b, h) do { _Pragma("unroll") for (int m = 0; m < 4; ++m) _Pragma("unroll") for (int k = 0; k < 2; ++k) dst[m][k] = *(const LAS bf16x8*)(lds + PG8_SA(b, h) + aoff + m * 2048 + k * 1024); } while (0)
; #define PG8_MMA(ai, bj, At, Bt) do { __builtin_amdgcn_s_setprio(1); _Pragma("unroll") for (int m = 0; m < 4; ++m) _Pragma("unroll") for (int n = 0; n < 2; ++n) _Pragma("unroll") for (int k = 0; k < 2; ++k) \
;         acc[ai][bj][m][n] = __builtin_amdgcn_mfma_f32_16x16x32_bf16(Bt[n][k], At[m][k], acc[ai][bj][m][n], 0, 0, 0); __builtin_amdgcn_s_setprio(0); } while (0)
; #define PG8_WAIT_V(n) asm volatile("s_waitcnt vmcnt(" #n ")" ::: "memory")
; #define PG8_WAIT_L(n) asm volatile("s_waitcnt lgkmcnt(" #n ")" ::: "memory")
; #define PG8_BAR __builtin_amdgcn_s_barrier()
; #define PG8_SCHED __builtin_amdgcn_sched_barrier(0)
; template <class Epi, class Sched>
; __device__ __forceinline__ void gemm_phase(LAS unsigned char* lds, const Gemm g, const Sched& S, const Epi& E, const int tid) {
;     ...
;             PG8_WAIT_V(8); PG8_WAIT_L(0); PG8_BAR; PG8_MMA(0, 0, At, B0); PG8_MMA(0, 1, At, B1); PG8_BAR; PG8_SCHED;
;             PG8_LDA(At, 0, 1); PG8_STAGE(PG8_SB(0, 0), b2, voffB); PG8_STAGE(PG8_SB(0, 1), b2 + hstep, voffB); PG8_STAGE(PG8_SA(0, 0), a2, voffA);
;             PG8_WAIT_V(8); PG8_WAIT_L(0); PG8_BAR; PG8_MMA(1, 0, At, B0); PG8_MMA(1, 1, At, B1); PG8_BAR; PG8_SCHED;
	s_waitcnt lgkmcnt(0)
	v_mfma_f32_16x16x32_bf16 v[160:163], v[58:61], v[164:167], v[160:163]
	v_mfma_f32_16x16x32_bf16 v[140:143], v[58:61], v[172:175], v[140:143]
	v_mfma_f32_16x16x32_bf16 v[124:127], v[58:61], v[180:183], v[124:127]
	v_mfma_f32_16x16x32_bf16 v[108:111], v[58:61], v[188:191], v[108:111]
	v_mfma_f32_16x16x32_bf16 v[104:107], v[66:69], v[188:191], v[104:107]
	v_mfma_f32_16x16x32_bf16 v[120:123], v[66:69], v[180:183], v[120:123]
	v_mfma_f32_16x16x32_bf16 v[136:139], v[66:69], v[172:175], v[136:139]
	v_mfma_f32_16x16x32_bf16 v[156:159], v[66:69], v[164:167], v[156:159]
	v_mfma_f32_16x16x32_bf16 v[160:163], v[62:65], v[168:171], v[160:163]
	v_mfma_f32_16x16x32_bf16 v[140:143], v[62:65], v[176:179], v[140:143]
	v_mfma_f32_16x16x32_bf16 v[124:127], v[62:65], v[184:187], v[124:127]
	v_mfma_f32_16x16x32_bf16 v[108:111], v[62:65], v[208:211], v[108:111]
	v_mfma_f32_16x16x32_bf16 v[104:107], v[80:83], v[208:211], v[104:107]
	v_mfma_f32_16x16x32_bf16 v[120:123], v[80:83], v[184:187], v[120:123]
	v_mfma_f32_16x16x32_bf16 v[136:139], v[80:83], v[176:179], v[136:139]
	v_mfma_f32_16x16x32_bf16 v[156:159], v[80:83], v[168:171], v[156:159]
	v_mfma_f32_16x16x32_bf16 v[148:151], v[84:87], v[164:167], v[148:151]
	v_mfma_f32_16x16x32_bf16 v[132:135], v[84:87], v[172:175], v[132:135]
	v_mfma_f32_16x16x32_bf16 v[116:119], v[84:87], v[180:183], v[116:119]
	v_mfma_f32_16x16x32_bf16 v[100:103], v[84:87], v[188:191], v[100:103]
	v_mfma_f32_16x16x32_bf16 v[96:99], v[92:95], v[188:191], v[96:99]
	v_mfma_f32_16x16x32_bf16 v[112:115], v[92:95], v[180:183], v[112:115]
	v_mfma_f32_16x16x32_bf16 v[128:131], v[92:95], v[172:175], v[128:131]
	v_mfma_f32_16x16x32_bf16 v[144:147], v[92:95], v[164:167], v[144:147]
	v_mfma_f32_16x16x32_bf16 v[148:151], v[88:91], v[168:171], v[148:151]
	v_mfma_f32_16x16x32_bf16 v[132:135], v[88:91], v[176:179], v[132:135]
	v_mfma_f32_16x16x32_bf16 v[116:119], v[88:91], v[184:187], v[116:119]
	v_mfma_f32_16x16x32_bf16 v[100:103], v[88:91], v[208:211], v[100:103]
	v_mfma_f32_16x16x32_bf16 v[96:99], v[152:155], v[208:211], v[96:99]
	v_mfma_f32_16x16x32_bf16 v[112:115], v[152:155], v[184:187], v[112:115]
	v_mfma_f32_16x16x32_bf16 v[128:131], v[152:155], v[176:179], v[128:131]
	v_mfma_f32_16x16x32_bf16 v[144:147], v[152:155], v[168:171], v[144:147]
	s_barrier
	s_add_i32 s3, s3, s94
	v_lshl_add_u64 v[212:213], s[82:83], 0, v[192:193]
	s_mov_b32 m0, s3
	ds_read_b128 v[164:167], v240 offset:16384
	ds_read_b128 v[168:171], v240 offset:17408
	ds_read_b128 v[172:175], v240 offset:18432
	ds_read_b128 v[176:179], v240 offset:19456
	ds_read_b128 v[180:183], v240 offset:20480
	ds_read_b128 v[184:187], v240 offset:21504
	ds_read_b128 v[188:191], v240 offset:22528
	ds_read_b128 v[208:211], v240 offset:23552
	global_load_lds_dwordx4 v[212:213], off
	s_add_i32 m0, s3, 0x2000
	v_lshl_add_u64 v[214:215], s[82:83], 0, v[198:199]
	s_add_u32 s82, s82, s12
	s_addc_u32 s83, s83, 0
	s_add_i32 s3, s81, s94
	global_load_lds_dwordx4 v[214:215], off
	v_lshl_add_u64 v[216:217], s[82:83], 0, v[192:193]
	s_mov_b32 m0, s3
	v_lshl_add_u64 v[218:219], s[82:83], 0, v[198:199]
	global_load_lds_dwordx4 v[216:217], off
	s_add_i32 m0, s3, 0x2000
	v_lshl_add_u64 v[220:221], s[74:75], 0, v[202:203]
	global_load_lds_dwordx4 v[218:219], off
	s_mov_b32 m0, s97
	v_lshl_add_u64 v[224:225], s[74:75], 0, v[200:201]
	global_load_lds_dwordx4 v[220:221], off
	s_mov_b32 m0, s98
	s_nop 0
	global_load_lds_dwordx4 v[224:225], off
	s_waitcnt vmcnt(8)
	s_waitcnt lgkmcnt(0)
	s_barrier
	s_waitcnt lgkmcnt(0)
	v_mfma_f32_16x16x32_bf16 v[76:79], v[58:61], v[164:167], v[76:79]
	v_mfma_f32_16x16x32_bf16 v[44:47], v[58:61], v[172:175], v[44:47]
	v_mfma_f32_16x16x32_bf16 v[28:31], v[58:61], v[180:183], v[28:31]
	v_mfma_f32_16x16x32_bf16 v[12:15], v[58:61], v[188:191], v[12:15]
	v_mfma_f32_16x16x32_bf16 v[8:11], v[66:69], v[188:191], v[8:11]
	v_mfma_f32_16x16x32_bf16 v[24:27], v[66:69], v[180:183], v[24:27]
	v_mfma_f32_16x16x32_bf16 v[40:43], v[66:69], v[172:175], v[40:43]
	v_mfma_f32_16x16x32_bf16 v[70:73], v[66:69], v[164:167], v[72:75]
	v_mfma_f32_16x16x32_bf16 v[76:79], v[62:65], v[168:171], v[76:79]
	v_mfma_f32_16x16x32_bf16 v[44:47], v[62:65], v[176:179], v[44:47]
	v_mfma_f32_16x16x32_bf16 v[28:31], v[62:65], v[184:187], v[28:31]
	v_mfma_f32_16x16x32_bf16 v[12:15], v[62:65], v[208:211], v[12:15]
	v_mfma_f32_16x16x32_bf16 v[8:11], v[80:83], v[208:211], v[8:11]
	v_mfma_f32_16x16x32_bf16 v[24:27], v[80:83], v[184:187], v[24:27]
	v_mfma_f32_16x16x32_bf16 v[40:43], v[80:83], v[176:179], v[40:43]
	v_mfma_f32_16x16x32_bf16 v[70:73], v[80:83], v[168:171], v[70:73]
	v_mfma_f32_16x16x32_bf16 v[52:55], v[84:87], v[164:167], v[52:55]
	v_mfma_f32_16x16x32_bf16 v[36:39], v[84:87], v[172:175], v[36:39]
	v_mfma_f32_16x16x32_bf16 v[20:23], v[84:87], v[180:183], v[20:23]
	v_mfma_f32_16x16x32_bf16 v[4:7], v[84:87], v[188:191], v[4:7]
	v_mfma_f32_16x16x32_bf16 v[0:3], v[92:95], v[188:191], v[0:3]
	v_mfma_f32_16x16x32_bf16 v[16:19], v[92:95], v[180:183], v[16:19]
	v_mfma_f32_16x16x32_bf16 v[32:35], v[92:95], v[172:175], v[32:35]
	v_mfma_f32_16x16x32_bf16 v[48:51], v[92:95], v[164:167], v[48:51]
	v_mfma_f32_16x16x32_bf16 v[52:55], v[88:91], v[168:171], v[52:55]
	v_mfma_f32_16x16x32_bf16 v[36:39], v[88:91], v[176:179], v[36:39]
	v_mfma_f32_16x16x32_bf16 v[20:23], v[88:91], v[184:187], v[20:23]
	v_mfma_f32_16x16x32_bf16 v[4:7], v[88:91], v[208:211], v[4:7]
	v_mfma_f32_16x16x32_bf16 v[0:3], v[152:155], v[208:211], v[0:3]
	v_mfma_f32_16x16x32_bf16 v[16:19], v[152:155], v[184:187], v[16:19]
	v_mfma_f32_16x16x32_bf16 v[32:35], v[152:155], v[176:179], v[32:35]
	v_mfma_f32_16x16x32_bf16 v[48:51], v[152:155], v[168:171], v[48:51]
	s_barrier
; #define PG8_STAGE(bufoff, gbase, voff) do { _Pragma("unroll") for (int _i = 0; _i < 2; ++_i) \
;         __builtin_amdgcn_global_load_lds((const unsigned*)((const char*)(gbase) + (voff)[_i]), (LAS unsigned*)(lds + (bufoff) + ldsw + _i * 8192), 16, 0, 0); } while (0)
; #define PG8_LDA(dst, b, h) do { _Pragma("unroll") for (int m = 0; m < 4; ++m) _Pragma("unroll") for (int k = 0; k < 2; ++k) dst[m][k] = *(const LAS bf16x8*)(lds + PG8_SA(b, h) + aoff + m * 2048 + k * 1024); } while (0)
; #define PG8_LDB(dst, b, h) do { _Pragma("unroll") for (int n = 0; n < 2; ++n) _Pragma("unroll") for (int k = 0; k < 2; ++k) dst[n][k] = *(const LAS bf16x8*)(lds + PG8_SB(b, h) + boff + n * 2048 + k * 1024); } while (0)
; #define PG8_MMA(ai, bj, At, Bt) do { __builtin_amdgcn_s_setprio(1); _Pragma("unroll") for (int m = 0; m < 4; ++m) _Pragma("unroll") for (int n = 0; n < 2; ++n) _Pragma("unroll") for (int k = 0; k < 2; ++k) \
;         acc[ai][bj][m][n] = __builtin_amdgcn_mfma_f32_16x16x32_bf16(Bt[n][k], At[m][k], acc[ai][bj][m][n], 0, 0, 0); __builtin_amdgcn_s_setprio(0); } while (0)
; #define PG8_WAIT_V(n) asm volatile("s_waitcnt vmcnt(" #n ")" ::: "memory")
; #define PG8_WAIT_L(n) asm volatile("s_waitcnt lgkmcnt(" #n ")" ::: "memory")
; #define PG8_BAR __builtin_amdgcn_s_barrier()
; #define PG8_SCHED __builtin_amdgcn_sched_barrier(0)
; template <class Epi, class Sched>
; __device__ __forceinline__ void gemm_phase(LAS unsigned char* lds, const Gemm g, const Sched& S, const Epi& E, const int tid) {
;     ...
;             PG8_LDB(B0, 1, 0); PG8_LDB(B1, 1, 1); PG8_SCHED; PG8_LDA(At, 1, 0); PG8_STAGE(PG8_SA(0, 1), a2 + hstep, voffA);
;             PG8_WAIT_V(8); PG8_WAIT_L(0); PG8_BAR; PG8_MMA(0, 0, At, B0); PG8_MMA(0, 1, At, B1); PG8_BAR; PG8_SCHED;
;             PG8_LDA(At, 1, 1); PG8_STAGE(PG8_SB(1, 0), b3, voffB); PG8_STAGE(PG8_SB(1, 1), b3 + hstep, voffB); PG8_STAGE(PG8_SA(1, 0), a3, voffA);
;             PG8_WAIT_V(8); PG8_WAIT_L(0); PG8_BAR; PG8_MMA(1, 0, At, B0); PG8_MMA(1, 1, At, B1); PG8_BAR; PG8_SCHED;
;         }
;         if (wr == 0) PG8_BAR;
	s_add_i32 s3, 0, 0x18000
	v_add_u32_e32 v74, s3, v232
	s_add_i32 s81, 0, 0x1c000
	ds_read_b128 v[58:61], v74
	ds_read_b128 v[62:65], v74 offset:1024
	ds_read_b128 v[66:69], v74 offset:2048
	ds_read_b128 v[80:83], v74 offset:3072
	v_add_u32_e32 v74, s81, v232
	ds_read_b128 v[84:87], v74
	ds_read_b128 v[88:91], v74 offset:1024
	ds_read_b128 v[92:95], v74 offset:2048
	ds_read_b128 v[152:155], v74 offset:3072
	s_add_u32 s74, s74, s12
	s_addc_u32 s75, s75, 0
	s_mov_b32 m0, s99
	v_lshl_add_u64 v[74:75], s[74:75], 0, v[202:203]
	ds_read_b128 v[164:167], v240 offset:32768
	ds_read_b128 v[168:171], v240 offset:33792
	ds_read_b128 v[172:175], v240 offset:34816
	ds_read_b128 v[176:179], v240 offset:35840
	ds_read_b128 v[180:183], v240 offset:36864
	ds_read_b128 v[184:187], v240 offset:37888
	ds_read_b128 v[188:191], v240 offset:38912
	ds_read_b128 v[208:211], v240 offset:39936
	global_load_lds_dwordx4 v[74:75], off
	v_lshl_add_u64 v[74:75], s[74:75], 0, v[200:201]
	s_mov_b32 m0, s78
	s_nop 0
	global_load_lds_dwordx4 v[74:75], off
	s_waitcnt vmcnt(8)
	s_waitcnt lgkmcnt(0)
	s_barrier
	s_waitcnt lgkmcnt(0)
	v_mfma_f32_16x16x32_bf16 v[160:163], v[58:61], v[164:167], v[160:163]
	v_mfma_f32_16x16x32_bf16 v[140:143], v[58:61], v[172:175], v[140:143]
	v_mfma_f32_16x16x32_bf16 v[124:127], v[58:61], v[180:183], v[124:127]
	v_mfma_f32_16x16x32_bf16 v[108:111], v[58:61], v[188:191], v[108:111]
	v_mfma_f32_16x16x32_bf16 v[104:107], v[66:69], v[188:191], v[104:107]
	v_mfma_f32_16x16x32_bf16 v[120:123], v[66:69], v[180:183], v[120:123]
	v_mfma_f32_16x16x32_bf16 v[136:139], v[66:69], v[172:175], v[136:139]
	v_mfma_f32_16x16x32_bf16 v[156:159], v[66:69], v[164:167], v[156:159]
	v_mfma_f32_16x16x32_bf16 v[160:163], v[62:65], v[168:171], v[160:163]
	v_mfma_f32_16x16x32_bf16 v[140:143], v[62:65], v[176:179], v[140:143]
	v_mfma_f32_16x16x32_bf16 v[124:127], v[62:65], v[184:187], v[124:127]
	v_mfma_f32_16x16x32_bf16 v[108:111], v[62:65], v[208:211], v[108:111]
	v_mfma_f32_16x16x32_bf16 v[104:107], v[80:83], v[208:211], v[104:107]
	v_mfma_f32_16x16x32_bf16 v[120:123], v[80:83], v[184:187], v[120:123]
	v_mfma_f32_16x16x32_bf16 v[136:139], v[80:83], v[176:179], v[136:139]
	v_mfma_f32_16x16x32_bf16 v[156:159], v[80:83], v[168:171], v[156:159]
	v_mfma_f32_16x16x32_bf16 v[148:151], v[84:87], v[164:167], v[148:151]
	v_mfma_f32_16x16x32_bf16 v[132:135], v[84:87], v[172:175], v[132:135]
	v_mfma_f32_16x16x32_bf16 v[116:119], v[84:87], v[180:183], v[116:119]
	v_mfma_f32_16x16x32_bf16 v[100:103], v[84:87], v[188:191], v[100:103]
	v_mfma_f32_16x16x32_bf16 v[96:99], v[92:95], v[188:191], v[96:99]
	v_mfma_f32_16x16x32_bf16 v[112:115], v[92:95], v[180:183], v[112:115]
	v_mfma_f32_16x16x32_bf16 v[128:131], v[92:95], v[172:175], v[128:131]
	v_mfma_f32_16x16x32_bf16 v[144:147], v[92:95], v[164:167], v[144:147]
	v_mfma_f32_16x16x32_bf16 v[148:151], v[88:91], v[168:171], v[148:151]
	v_mfma_f32_16x16x32_bf16 v[132:135], v[88:91], v[176:179], v[132:135]
	v_mfma_f32_16x16x32_bf16 v[116:119], v[88:91], v[184:187], v[116:119]
	v_mfma_f32_16x16x32_bf16 v[100:103], v[88:91], v[208:211], v[100:103]
	v_mfma_f32_16x16x32_bf16 v[96:99], v[152:155], v[208:211], v[96:99]
	v_mfma_f32_16x16x32_bf16 v[112:115], v[152:155], v[184:187], v[112:115]
	v_mfma_f32_16x16x32_bf16 v[128:131], v[152:155], v[176:179], v[128:131]
	v_mfma_f32_16x16x32_bf16 v[144:147], v[152:155], v[168:171], v[144:147]
	s_barrier
	s_add_i32 s3, s3, s94
	v_lshl_add_u64 v[74:75], v[212:213], 0, s[68:69]
	s_mov_b32 m0, s3
	ds_read_b128 v[164:167], v240 offset:49152
	ds_read_b128 v[168:171], v240 offset:50176
	ds_read_b128 v[172:175], v240 offset:51200
	ds_read_b128 v[176:179], v240 offset:52224
	ds_read_b128 v[180:183], v240 offset:53248
	ds_read_b128 v[184:187], v240 offset:54272
	ds_read_b128 v[188:191], v240 offset:55296
	ds_read_b128 v[208:211], v240 offset:56320
	global_load_lds_dwordx4 v[74:75], off
	v_lshl_add_u64 v[74:75], v[214:215], 0, s[68:69]
	s_add_i32 m0, s3, 0x2000
	s_add_i32 s3, s81, s94
	global_load_lds_dwordx4 v[74:75], off
	v_lshl_add_u64 v[74:75], v[216:217], 0, s[68:69]
	s_mov_b32 m0, s3
	s_nop 0
	global_load_lds_dwordx4 v[74:75], off
	v_lshl_add_u64 v[74:75], v[218:219], 0, s[68:69]
	s_add_i32 m0, s3, 0x2000
	s_nop 0
	global_load_lds_dwordx4 v[74:75], off
	v_lshl_add_u64 v[74:75], v[220:221], 0, s[68:69]
	s_mov_b32 m0, s53
	s_nop 0
	global_load_lds_dwordx4 v[74:75], off
	v_lshl_add_u64 v[74:75], v[224:225], 0, s[68:69]
	s_mov_b32 m0, s56
	s_nop 0
	global_load_lds_dwordx4 v[74:75], off
	s_waitcnt vmcnt(8)
	s_waitcnt lgkmcnt(0)
	s_barrier
	s_waitcnt lgkmcnt(0)
	v_mfma_f32_16x16x32_bf16 v[74:77], v[58:61], v[164:167], v[76:79]
	v_mfma_f32_16x16x32_bf16 v[44:47], v[58:61], v[172:175], v[44:47]
	v_mfma_f32_16x16x32_bf16 v[28:31], v[58:61], v[180:183], v[28:31]
	v_mfma_f32_16x16x32_bf16 v[12:15], v[58:61], v[188:191], v[12:15]
	v_mfma_f32_16x16x32_bf16 v[8:11], v[66:69], v[188:191], v[8:11]
	v_mfma_f32_16x16x32_bf16 v[24:27], v[66:69], v[180:183], v[24:27]
	v_mfma_f32_16x16x32_bf16 v[40:43], v[66:69], v[172:175], v[40:43]
	v_mfma_f32_16x16x32_bf16 v[70:73], v[66:69], v[164:167], v[70:73]
	v_mfma_f32_16x16x32_bf16 v[76:79], v[62:65], v[168:171], v[74:77]
	v_mfma_f32_16x16x32_bf16 v[44:47], v[62:65], v[176:179], v[44:47]
	v_mfma_f32_16x16x32_bf16 v[28:31], v[62:65], v[184:187], v[28:31]
	v_mfma_f32_16x16x32_bf16 v[12:15], v[62:65], v[208:211], v[12:15]
	v_mfma_f32_16x16x32_bf16 v[8:11], v[80:83], v[208:211], v[8:11]
	v_mfma_f32_16x16x32_bf16 v[24:27], v[80:83], v[184:187], v[24:27]
	v_mfma_f32_16x16x32_bf16 v[40:43], v[80:83], v[176:179], v[40:43]
	v_mfma_f32_16x16x32_bf16 v[72:75], v[80:83], v[168:171], v[70:73]
	v_mfma_f32_16x16x32_bf16 v[52:55], v[84:87], v[164:167], v[52:55]
	v_mfma_f32_16x16x32_bf16 v[36:39], v[84:87], v[172:175], v[36:39]
	v_mfma_f32_16x16x32_bf16 v[20:23], v[84:87], v[180:183], v[20:23]
	v_mfma_f32_16x16x32_bf16 v[4:7], v[84:87], v[188:191], v[4:7]
	v_mfma_f32_16x16x32_bf16 v[0:3], v[92:95], v[188:191], v[0:3]
	v_mfma_f32_16x16x32_bf16 v[16:19], v[92:95], v[180:183], v[16:19]
	v_mfma_f32_16x16x32_bf16 v[32:35], v[92:95], v[172:175], v[32:35]
	v_mfma_f32_16x16x32_bf16 v[48:51], v[92:95], v[164:167], v[48:51]
	v_mfma_f32_16x16x32_bf16 v[52:55], v[88:91], v[168:171], v[52:55]
	v_mfma_f32_16x16x32_bf16 v[36:39], v[88:91], v[176:179], v[36:39]
	v_mfma_f32_16x16x32_bf16 v[20:23], v[88:91], v[184:187], v[20:23]
	v_mfma_f32_16x16x32_bf16 v[4:7], v[88:91], v[208:211], v[4:7]
	v_mfma_f32_16x16x32_bf16 v[0:3], v[152:155], v[208:211], v[0:3]
	v_mfma_f32_16x16x32_bf16 v[16:19], v[152:155], v[184:187], v[16:19]
	v_mfma_f32_16x16x32_bf16 v[32:35], v[152:155], v[176:179], v[32:35]
	v_mfma_f32_16x16x32_bf16 v[48:51], v[152:155], v[168:171], v[48:51]
	s_barrier
	s_add_u32 vcc_lo, vcc_lo, 0x100
	s_addc_u32 vcc_hi, vcc_hi, 0
	s_add_u32 s61, s61, 0x100
	s_addc_u32 s67, s67, 0
	s_cmp_ge_u32 s80, s52
	s_mov_b32 s74, s80
	s_cbranch_scc0 .LBB0_567
	s_and_b64 vcc, exec, s[64:65]
	s_cbranch_vccz .LBB0_570
	s_barrier
